# on top of v32: in the 12-read intervals the lgkmcnt(8)+lgkmcnt(0) pair merged into one lgkmcnt(0) before the barrier (reads are now issued first)
# baseline (speedup 1.0000x reference)
; #define PG8_STAGE(bufoff, gbase) do { _Pragma("unroll") for (int _i = 0; _i < 2; ++_i) \
;         __builtin_amdgcn_global_load_lds((const unsigned*)((const char*)(gbase) + voff[_i]), (LAS unsigned*)(lds + (bufoff) + ldsw + _i * 8192), 16, 0, 0); } while (0)
; #define PG8_LDA(dst, b, h) do { _Pragma("unroll") for (int m = 0; m < 4; ++m) _Pragma("unroll") for (int k = 0; k < 2; ++k) dst[m][k] = *(const LAS bf16x8*)(lds + PG8_SA(b, h) + aoff + m * 2048 + k * 1024); } while (0)
; #define PG8_LDB(dst, b, h) do { _Pragma("unroll") for (int n = 0; n < 2; ++n) _Pragma("unroll") for (int k = 0; k < 2; ++k) dst[n][k] = *(const LAS bf16x8*)(lds + PG8_SB(b, h) + boff + n * 2048 + k * 1024); } while (0)
; #define PG8_MMA(ai, bj, At, Bt) do { __builtin_amdgcn_s_setprio(1); _Pragma("unroll") for (int m = 0; m < 4; ++m) _Pragma("unroll") for (int n = 0; n < 2; ++n) _Pragma("unroll") for (int k = 0; k < 2; ++k) \
;         acc[ai][bj][m][n] = __builtin_amdgcn_mfma_f32_16x16x32_bf16(Bt[n][k], At[m][k], acc[ai][bj][m][n], 0, 0, 0); __builtin_amdgcn_s_setprio(0); } while (0)
; #define PG8_WAIT_V(n) asm volatile("s_waitcnt vmcnt(" #n ")" ::: "memory")
; #define PG8_WAIT_L(n) asm volatile("s_waitcnt lgkmcnt(" #n ")" ::: "memory")
; #define PG8_BAR __builtin_amdgcn_s_barrier()
; #define PG8_SCHED __builtin_amdgcn_sched_barrier(0)
; template <class Epi>
; DI void gemm_phase(LAS unsigned char* lds, const Gemm g, const StaticOrder& S, const Epi& E) {
;     ...
;             const bool last = (t == nt - 2);
;             const char* a1 = cA + (size_t)(t + 1) * kstep;
;             const char* a2 = last ? nA : cA + (size_t)(t + 2) * kstep; const char* b2 = last ? nB : cB + (size_t)(t + 2) * kstep;
;             const char* a3 = a2 + kstep; const char* b3 = b2 + kstep;
;             PG8_LDB(B0, 0, 0); PG8_SCHED; PG8_LDA(At, 0, 0); PG8_STAGE(PG8_SA(1, 1), a1 + hstep);
;             PG8_WAIT_L(8); PG8_BAR; PG8_WAIT_L(0); PG8_MMA(0, 0, At, B0); PG8_BAR; PG8_SCHED;
;             PG8_LDB(B1, 0, 1); PG8_STAGE(PG8_SB(0, 0), b2);
;             PG8_BAR; PG8_WAIT_L(0); PG8_MMA(0, 1, At, B1); PG8_BAR;
;             PG8_LDA(At, 0, 1); PG8_STAGE(PG8_SA(0, 0), a2);
;             PG8_BAR; PG8_WAIT_L(0); PG8_MMA(1, 0, At, B0); PG8_BAR; PG8_SCHED;
;             PG8_STAGE(PG8_SB(0, 1), b2 + hstep);
;             PG8_WAIT_V(6); PG8_BAR; PG8_MMA(1, 1, At, B1); PG8_BAR;
.LBB0_37:
	ds_read_b128 v[138:141], v135
	ds_read_b128 v[142:145], v135 offset:1024
	ds_read_b128 v[146:149], v135 offset:2048
	ds_read_b128 v[150:153], v135 offset:3072
	ds_read_b128 v[186:189], v137
	ds_read_b128 v[190:193], v137 offset:1024
	ds_read_b128 v[194:197], v137 offset:2048
	ds_read_b128 v[198:201], v137 offset:3072
	ds_read_b128 v[202:205], v137 offset:4096
	ds_read_b128 v[206:209], v137 offset:5120
	ds_read_b128 v[210:213], v137 offset:6144
	ds_read_b128 v[214:217], v137 offset:7168
	s_add_u32 s20, s18, 0xfff80080
	s_addc_u32 s21, s19, -1
	s_add_i32 s39, 0, 0x10000
	s_cmp_eq_u32 s38, 28
	s_cselect_b32 s23, s4, s21
	s_cselect_b32 s22, s5, s20
	s_cselect_b32 s21, s9, s37
	s_cselect_b32 s20, s11, s33
	s_add_i32 m0, s28, 0xc000
	s_nop 0
	global_load_lds_dwordx4 v130, s[18:19]
	s_add_i32 m0, s28, 0xe000
	s_nop 0
	global_load_lds_dwordx4 v132, s[18:19]
	s_waitcnt lgkmcnt(0)
	s_setprio 1
	s_barrier
	v_mfma_f32_16x16x32_bf16 v[124:127], v[138:141], v[186:189], v[124:127]
	v_mfma_f32_16x16x32_bf16 v[120:123], v[146:149], v[186:189], v[120:123]
	v_mfma_f32_16x16x32_bf16 v[108:111], v[138:141], v[194:197], v[108:111]
	v_mfma_f32_16x16x32_bf16 v[104:107], v[146:149], v[194:197], v[104:107]
	v_mfma_f32_16x16x32_bf16 v[92:95], v[138:141], v[202:205], v[92:95]
	v_mfma_f32_16x16x32_bf16 v[88:91], v[146:149], v[202:205], v[88:91]
	v_mfma_f32_16x16x32_bf16 v[76:79], v[138:141], v[210:213], v[76:79]
	v_mfma_f32_16x16x32_bf16 v[72:75], v[146:149], v[210:213], v[72:75]
	v_mfma_f32_16x16x32_bf16 v[124:127], v[142:145], v[190:193], v[124:127]
	v_mfma_f32_16x16x32_bf16 v[120:123], v[150:153], v[190:193], v[120:123]
	v_mfma_f32_16x16x32_bf16 v[108:111], v[142:145], v[198:201], v[108:111]
	v_mfma_f32_16x16x32_bf16 v[104:107], v[150:153], v[198:201], v[104:107]
	v_mfma_f32_16x16x32_bf16 v[92:95], v[142:145], v[206:209], v[92:95]
	v_mfma_f32_16x16x32_bf16 v[88:91], v[150:153], v[206:209], v[88:91]
	v_mfma_f32_16x16x32_bf16 v[76:79], v[142:145], v[214:217], v[76:79]
	s_setprio 0
	v_mfma_f32_16x16x32_bf16 v[72:75], v[150:153], v[214:217], v[72:75]
	s_barrier
	ds_read_b128 v[226:229], v135 offset:16384
	ds_read_b128 v[230:233], v135 offset:17408
	ds_read_b128 v[234:237], v135 offset:18432
	ds_read_b128 v[238:241], v135 offset:19456
	s_add_i32 s42, 0, 0x14000
	s_add_i32 s39, s39, s27
	s_mov_b32 m0, s39
	s_nop 0
	global_load_lds_dwordx4 v158, s[20:21]
	s_add_i32 m0, s39, 0x2000
	s_nop 0
	global_load_lds_dwordx4 v128, s[20:21]
	s_waitcnt lgkmcnt(0)
	s_setprio 1
	s_barrier
	v_mfma_f32_16x16x32_bf16 v[116:119], v[226:229], v[186:189], v[116:119]
	v_mfma_f32_16x16x32_bf16 v[112:115], v[234:237], v[186:189], v[112:115]
	v_mfma_f32_16x16x32_bf16 v[100:103], v[226:229], v[194:197], v[100:103]
	v_mfma_f32_16x16x32_bf16 v[96:99], v[234:237], v[194:197], v[96:99]
	v_mfma_f32_16x16x32_bf16 v[84:87], v[226:229], v[202:205], v[84:87]
	v_mfma_f32_16x16x32_bf16 v[80:83], v[234:237], v[202:205], v[80:83]
	v_mfma_f32_16x16x32_bf16 v[68:71], v[226:229], v[210:213], v[68:71]
	v_mfma_f32_16x16x32_bf16 v[64:67], v[234:237], v[210:213], v[64:67]
	v_mfma_f32_16x16x32_bf16 v[116:119], v[230:233], v[190:193], v[116:119]
	s_mov_b32 m0, s28
	v_mfma_f32_16x16x32_bf16 v[112:115], v[238:241], v[190:193], v[112:115]
	v_mfma_f32_16x16x32_bf16 v[100:103], v[230:233], v[198:201], v[100:103]
	v_mfma_f32_16x16x32_bf16 v[96:99], v[238:241], v[198:201], v[96:99]
	v_mfma_f32_16x16x32_bf16 v[84:87], v[230:233], v[206:209], v[84:87]
	v_mfma_f32_16x16x32_bf16 v[80:83], v[238:241], v[206:209], v[80:83]
	v_mfma_f32_16x16x32_bf16 v[68:71], v[230:233], v[214:217], v[68:71]
	s_setprio 0
	v_mfma_f32_16x16x32_bf16 v[64:67], v[238:241], v[214:217], v[64:67]
	s_barrier
	ds_read_b128 v[186:189], v137 offset:16384
	ds_read_b128 v[190:193], v137 offset:17408
	ds_read_b128 v[194:197], v137 offset:18432
	ds_read_b128 v[198:201], v137 offset:19456
	ds_read_b128 v[202:205], v137 offset:20480
	ds_read_b128 v[206:209], v137 offset:21504
	ds_read_b128 v[210:213], v137 offset:22528
	ds_read_b128 v[214:217], v137 offset:23552
	global_load_lds_dwordx4 v158, s[22:23]
	s_mov_b64 s[100:101], s[22:23]
	s_mov_b32 m0, s29
	s_nop 0
	global_load_lds_dwordx4 v128, s[22:23]
	s_waitcnt lgkmcnt(0)
	s_setprio 1
	s_barrier
	v_mfma_f32_16x16x32_bf16 v[60:63], v[138:141], v[186:189], v[60:63]
	v_mfma_f32_16x16x32_bf16 v[56:59], v[146:149], v[186:189], v[56:59]
	v_mfma_f32_16x16x32_bf16 v[44:47], v[138:141], v[194:197], v[44:47]
	v_mfma_f32_16x16x32_bf16 v[40:43], v[146:149], v[194:197], v[40:43]
	v_mfma_f32_16x16x32_bf16 v[28:31], v[138:141], v[202:205], v[28:31]
	v_mfma_f32_16x16x32_bf16 v[24:27], v[146:149], v[202:205], v[24:27]
	v_mfma_f32_16x16x32_bf16 v[12:15], v[138:141], v[210:213], v[12:15]
	v_mfma_f32_16x16x32_bf16 v[8:11], v[146:149], v[210:213], v[8:11]
	v_mfma_f32_16x16x32_bf16 v[60:63], v[142:145], v[190:193], v[60:63]
	v_mfma_f32_16x16x32_bf16 v[56:59], v[150:153], v[190:193], v[56:59]
	v_mfma_f32_16x16x32_bf16 v[44:47], v[142:145], v[198:201], v[44:47]
	v_mfma_f32_16x16x32_bf16 v[40:43], v[150:153], v[198:201], v[40:43]
	v_mfma_f32_16x16x32_bf16 v[28:31], v[142:145], v[206:209], v[28:31]
	v_mfma_f32_16x16x32_bf16 v[24:27], v[150:153], v[206:209], v[24:27]
	v_mfma_f32_16x16x32_bf16 v[12:15], v[142:145], v[214:217], v[12:15]
	s_setprio 0
	v_mfma_f32_16x16x32_bf16 v[8:11], v[150:153], v[214:217], v[8:11]
	s_barrier
	s_add_u32 s40, s20, 0x80000
	s_addc_u32 s41, s21, 0
	s_add_i32 s39, s42, s27
	s_mov_b32 m0, s39
	s_nop 0
	global_load_lds_dwordx4 v158, s[40:41]
	s_add_i32 m0, s39, 0x2000
	s_nop 0
	global_load_lds_dwordx4 v128, s[40:41]
	s_waitcnt vmcnt(6)
	s_setprio 1
	s_barrier
; #define PG8_STAGE(bufoff, gbase) do { _Pragma("unroll") for (int _i = 0; _i < 2; ++_i) \
;         __builtin_amdgcn_global_load_lds((const unsigned*)((const char*)(gbase) + voff[_i]), (LAS unsigned*)(lds + (bufoff) + ldsw + _i * 8192), 16, 0, 0); } while (0)
; #define PG8_LDA(dst, b, h) do { _Pragma("unroll") for (int m = 0; m < 4; ++m) _Pragma("unroll") for (int k = 0; k < 2; ++k) dst[m][k] = *(const LAS bf16x8*)(lds + PG8_SA(b, h) + aoff + m * 2048 + k * 1024); } while (0)
; #define PG8_LDB(dst, b, h) do { _Pragma("unroll") for (int n = 0; n < 2; ++n) _Pragma("unroll") for (int k = 0; k < 2; ++k) dst[n][k] = *(const LAS bf16x8*)(lds + PG8_SB(b, h) + boff + n * 2048 + k * 1024); } while (0)
; #define PG8_MMA(ai, bj, At, Bt) do { __builtin_amdgcn_s_setprio(1); _Pragma("unroll") for (int m = 0; m < 4; ++m) _Pragma("unroll") for (int n = 0; n < 2; ++n) _Pragma("unroll") for (int k = 0; k < 2; ++k) \
;         acc[ai][bj][m][n] = __builtin_amdgcn_mfma_f32_16x16x32_bf16(Bt[n][k], At[m][k], acc[ai][bj][m][n], 0, 0, 0); __builtin_amdgcn_s_setprio(0); } while (0)
; #define PG8_WAIT_V(n) asm volatile("s_waitcnt vmcnt(" #n ")" ::: "memory")
; #define PG8_WAIT_L(n) asm volatile("s_waitcnt lgkmcnt(" #n ")" ::: "memory")
; #define PG8_BAR __builtin_amdgcn_s_barrier()
; #define PG8_SCHED __builtin_amdgcn_sched_barrier(0)
; template <class Epi>
; DI void gemm_phase(LAS unsigned char* lds, const Gemm g, const StaticOrder& S, const Epi& E) {
;     ...
;             PG8_WAIT_V(6); PG8_BAR; PG8_MMA(1, 1, At, B1); PG8_BAR;
;             PG8_LDB(B0, 1, 0); PG8_SCHED; PG8_LDA(At, 1, 0); PG8_STAGE(PG8_SA(0, 1), a2 + hstep);
;             PG8_WAIT_L(8); PG8_BAR; PG8_WAIT_L(0); PG8_MMA(0, 0, At, B0); PG8_BAR; PG8_SCHED;
;             PG8_LDB(B1, 1, 1); PG8_STAGE(PG8_SB(1, 0), b3);
;             PG8_BAR; PG8_WAIT_L(0); PG8_MMA(0, 1, At, B1); PG8_BAR;
;             PG8_LDA(At, 1, 1); PG8_STAGE(PG8_SA(1, 0), a3);
;             PG8_BAR; PG8_WAIT_L(0); PG8_MMA(1, 0, At, B0); PG8_BAR; PG8_SCHED;
	v_mfma_f32_16x16x32_bf16 v[52:55], v[226:229], v[186:189], v[52:55]
	v_mfma_f32_16x16x32_bf16 v[48:51], v[234:237], v[186:189], v[48:51]
	v_mfma_f32_16x16x32_bf16 v[36:39], v[226:229], v[194:197], v[36:39]
	v_mfma_f32_16x16x32_bf16 v[32:35], v[234:237], v[194:197], v[32:35]
	v_mfma_f32_16x16x32_bf16 v[20:23], v[226:229], v[202:205], v[20:23]
	v_mfma_f32_16x16x32_bf16 v[16:19], v[234:237], v[202:205], v[16:19]
	v_mfma_f32_16x16x32_bf16 v[4:7], v[226:229], v[210:213], v[4:7]
	v_mfma_f32_16x16x32_bf16 v[0:3], v[234:237], v[210:213], v[0:3]
	v_mfma_f32_16x16x32_bf16 v[52:55], v[230:233], v[190:193], v[52:55]
	s_add_i32 s39, 0, 0x18000
	v_mfma_f32_16x16x32_bf16 v[48:51], v[238:241], v[190:193], v[48:51]
	v_mfma_f32_16x16x32_bf16 v[36:39], v[230:233], v[198:201], v[36:39]
	v_mfma_f32_16x16x32_bf16 v[32:35], v[238:241], v[198:201], v[32:35]
	v_mfma_f32_16x16x32_bf16 v[20:23], v[230:233], v[206:209], v[20:23]
	v_mfma_f32_16x16x32_bf16 v[16:19], v[238:241], v[206:209], v[16:19]
	v_mfma_f32_16x16x32_bf16 v[4:7], v[230:233], v[214:217], v[4:7]
	s_setprio 0
	v_mfma_f32_16x16x32_bf16 v[0:3], v[238:241], v[214:217], v[0:3]
	s_barrier
	ds_read_b128 v[138:141], v135 offset:32768
	ds_read_b128 v[142:145], v135 offset:33792
	ds_read_b128 v[146:149], v135 offset:34816
	ds_read_b128 v[150:153], v135 offset:35840
	ds_read_b128 v[186:189], v137 offset:32768
	ds_read_b128 v[190:193], v137 offset:33792
	ds_read_b128 v[194:197], v137 offset:34816
	ds_read_b128 v[198:201], v137 offset:35840
	ds_read_b128 v[202:205], v137 offset:36864
	ds_read_b128 v[206:209], v137 offset:37888
	ds_read_b128 v[210:213], v137 offset:38912
	ds_read_b128 v[214:217], v137 offset:39936
	s_add_u32 s22, s22, 0x80000
	s_addc_u32 s23, s23, 0
	s_mov_b32 m0, s30
	s_nop 0
	global_load_lds_dwordx4 v158, s[22:23]
	s_mov_b32 m0, s31
	s_nop 0
	global_load_lds_dwordx4 v128, s[22:23]
	s_waitcnt lgkmcnt(0)
	s_setprio 1
	s_barrier
	v_mfma_f32_16x16x32_bf16 v[124:127], v[138:141], v[186:189], v[124:127]
	v_mfma_f32_16x16x32_bf16 v[120:123], v[146:149], v[186:189], v[120:123]
	v_mfma_f32_16x16x32_bf16 v[108:111], v[138:141], v[194:197], v[108:111]
	v_mfma_f32_16x16x32_bf16 v[104:107], v[146:149], v[194:197], v[104:107]
	v_mfma_f32_16x16x32_bf16 v[92:95], v[138:141], v[202:205], v[92:95]
	v_mfma_f32_16x16x32_bf16 v[88:91], v[146:149], v[202:205], v[88:91]
	v_mfma_f32_16x16x32_bf16 v[76:79], v[138:141], v[210:213], v[76:79]
	v_mfma_f32_16x16x32_bf16 v[72:75], v[146:149], v[210:213], v[72:75]
	v_mfma_f32_16x16x32_bf16 v[124:127], v[142:145], v[190:193], v[124:127]
	v_mfma_f32_16x16x32_bf16 v[120:123], v[150:153], v[190:193], v[120:123]
	v_mfma_f32_16x16x32_bf16 v[108:111], v[142:145], v[198:201], v[108:111]
	v_mfma_f32_16x16x32_bf16 v[104:107], v[150:153], v[198:201], v[104:107]
	v_mfma_f32_16x16x32_bf16 v[92:95], v[142:145], v[206:209], v[92:95]
	v_mfma_f32_16x16x32_bf16 v[88:91], v[150:153], v[206:209], v[88:91]
	v_mfma_f32_16x16x32_bf16 v[76:79], v[142:145], v[214:217], v[76:79]
	s_setprio 0
	v_mfma_f32_16x16x32_bf16 v[72:75], v[150:153], v[214:217], v[72:75]
	s_barrier
	ds_read_b128 v[226:229], v135 offset:49152
	ds_read_b128 v[230:233], v135 offset:50176
	ds_read_b128 v[234:237], v135 offset:51200
	ds_read_b128 v[238:241], v135 offset:52224
	s_add_i32 s22, 0, 0x1c000
	s_add_i32 s23, s39, s27
	s_add_i32 m0, s23, 0xffffff80
	s_nop 0
	global_load_lds_dwordx4 v158, s[20:21] offset:128
	s_add_i32 m0, s23, 0x1f80
	s_nop 0
	global_load_lds_dwordx4 v128, s[20:21] offset:128
	s_waitcnt lgkmcnt(0)
	s_setprio 1
	s_barrier
	v_mfma_f32_16x16x32_bf16 v[116:119], v[226:229], v[186:189], v[116:119]
	v_mfma_f32_16x16x32_bf16 v[112:115], v[234:237], v[186:189], v[112:115]
	v_mfma_f32_16x16x32_bf16 v[100:103], v[226:229], v[194:197], v[100:103]
	v_mfma_f32_16x16x32_bf16 v[96:99], v[234:237], v[194:197], v[96:99]
	v_mfma_f32_16x16x32_bf16 v[84:87], v[226:229], v[202:205], v[84:87]
	v_mfma_f32_16x16x32_bf16 v[80:83], v[234:237], v[202:205], v[80:83]
	v_mfma_f32_16x16x32_bf16 v[68:71], v[226:229], v[210:213], v[68:71]
	v_mfma_f32_16x16x32_bf16 v[64:67], v[234:237], v[210:213], v[64:67]
	v_mfma_f32_16x16x32_bf16 v[116:119], v[230:233], v[190:193], v[116:119]
	s_add_i32 m0, s34, 0xffffff80
	v_mfma_f32_16x16x32_bf16 v[112:115], v[238:241], v[190:193], v[112:115]
	v_mfma_f32_16x16x32_bf16 v[100:103], v[230:233], v[198:201], v[100:103]
	v_mfma_f32_16x16x32_bf16 v[96:99], v[238:241], v[198:201], v[96:99]
	v_mfma_f32_16x16x32_bf16 v[84:87], v[230:233], v[206:209], v[84:87]
	v_mfma_f32_16x16x32_bf16 v[80:83], v[238:241], v[206:209], v[80:83]
	v_mfma_f32_16x16x32_bf16 v[68:71], v[230:233], v[214:217], v[68:71]
	s_setprio 0
	v_mfma_f32_16x16x32_bf16 v[64:67], v[238:241], v[214:217], v[64:67]
	s_barrier
	ds_read_b128 v[186:189], v137 offset:49152
	ds_read_b128 v[190:193], v137 offset:50176
	ds_read_b128 v[194:197], v137 offset:51200
	ds_read_b128 v[198:201], v137 offset:52224
	ds_read_b128 v[202:205], v137 offset:53248
	ds_read_b128 v[206:209], v137 offset:54272
	ds_read_b128 v[210:213], v137 offset:55296
	ds_read_b128 v[214:217], v137 offset:56320
	global_load_lds_dwordx4 v158, s[100:101] offset:128
	s_add_i32 m0, s35, 0xffffff80
	s_nop 0
	global_load_lds_dwordx4 v128, s[100:101] offset:128
	s_waitcnt lgkmcnt(0)
	s_setprio 1
	s_barrier
; #define PG8_STAGE(bufoff, gbase) do { _Pragma("unroll") for (int _i = 0; _i < 2; ++_i) \
;         __builtin_amdgcn_global_load_lds((const unsigned*)((const char*)(gbase) + voff[_i]), (LAS unsigned*)(lds + (bufoff) + ldsw + _i * 8192), 16, 0, 0); } while (0)
; #define PG8_MMA(ai, bj, At, Bt) do { __builtin_amdgcn_s_setprio(1); _Pragma("unroll") for (int m = 0; m < 4; ++m) _Pragma("unroll") for (int n = 0; n < 2; ++n) _Pragma("unroll") for (int k = 0; k < 2; ++k) \
;         acc[ai][bj][m][n] = __builtin_amdgcn_mfma_f32_16x16x32_bf16(Bt[n][k], At[m][k], acc[ai][bj][m][n], 0, 0, 0); __builtin_amdgcn_s_setprio(0); } while (0)
; #define PG8_WAIT_V(n) asm volatile("s_waitcnt vmcnt(" #n ")" ::: "memory")
; #define PG8_WAIT_L(n) asm volatile("s_waitcnt lgkmcnt(" #n ")" ::: "memory")
; #define PG8_BAR __builtin_amdgcn_s_barrier()
; #define PG8_SCHED __builtin_amdgcn_sched_barrier(0)
; template <class Epi>
; DI void gemm_phase(LAS unsigned char* lds, const Gemm g, const StaticOrder& S, const Epi& E) {
;     ...
;             PG8_BAR; PG8_WAIT_L(0); PG8_MMA(1, 0, At, B0); PG8_BAR; PG8_SCHED;
;             PG8_STAGE(PG8_SB(1, 1), b3 + hstep);
;             PG8_WAIT_V(6); PG8_BAR; PG8_MMA(1, 1, At, B1); PG8_BAR;
;     DI void operator()(const f32x4 (&acc)[2][2][4][2], const Unit& u, int wr, int wc, int fr, int fq) const {
;     ...
;             for (int m = 0; m < 4; ++m) { float hv[8];
; #pragma unroll
;                 for (int n = 0; n < 2; ++n)
; #pragma unroll
;                     for (int e = 0; e < 4; ++e) { const float gt = acc[ai][0][m][n][e], up = acc[ai][1][m][n][e];
;                         hv[n * 4 + e] = gt * __builtin_amdgcn_rcpf(1.f + __builtin_amdgcn_exp2f(-1.4426950408889634f * gt)) * up; }
;                 *(u32x4*)(H + (size_t)(row0 + ai * HALF + m * 16) * DFF + col0) = (u32x4){pk(hv[0], hv[1]), pk(hv[2], hv[3]), pk(hv[4], hv[5]), pk(hv[6], hv[7])}; }
	v_mfma_f32_16x16x32_bf16 v[60:63], v[138:141], v[186:189], v[60:63]
	v_mfma_f32_16x16x32_bf16 v[56:59], v[146:149], v[186:189], v[56:59]
	v_mfma_f32_16x16x32_bf16 v[44:47], v[138:141], v[194:197], v[44:47]
	v_mfma_f32_16x16x32_bf16 v[40:43], v[146:149], v[194:197], v[40:43]
	v_mfma_f32_16x16x32_bf16 v[28:31], v[138:141], v[202:205], v[28:31]
	v_mfma_f32_16x16x32_bf16 v[24:27], v[146:149], v[202:205], v[24:27]
	v_mfma_f32_16x16x32_bf16 v[12:15], v[138:141], v[210:213], v[12:15]
	v_mfma_f32_16x16x32_bf16 v[8:11], v[146:149], v[210:213], v[8:11]
	v_mfma_f32_16x16x32_bf16 v[60:63], v[142:145], v[190:193], v[60:63]
	v_mfma_f32_16x16x32_bf16 v[56:59], v[150:153], v[190:193], v[56:59]
	v_mfma_f32_16x16x32_bf16 v[44:47], v[142:145], v[198:201], v[44:47]
	v_mfma_f32_16x16x32_bf16 v[40:43], v[150:153], v[198:201], v[40:43]
	v_mfma_f32_16x16x32_bf16 v[28:31], v[142:145], v[206:209], v[28:31]
	v_mfma_f32_16x16x32_bf16 v[24:27], v[150:153], v[206:209], v[24:27]
	v_mfma_f32_16x16x32_bf16 v[12:15], v[142:145], v[214:217], v[12:15]
	s_setprio 0
	v_mfma_f32_16x16x32_bf16 v[8:11], v[150:153], v[214:217], v[8:11]
	s_barrier
	s_add_u32 s20, s20, 0x80080
	s_addc_u32 s21, s21, 0
	s_add_i32 s22, s22, s27
	s_mov_b32 m0, s22
	s_nop 0
	global_load_lds_dwordx4 v158, s[20:21]
	s_add_i32 m0, s22, 0x2000
	s_nop 0
	global_load_lds_dwordx4 v128, s[20:21]
	s_waitcnt vmcnt(6)
	s_setprio 1
	s_barrier
	v_mfma_f32_16x16x32_bf16 v[52:55], v[226:229], v[186:189], v[52:55]
	v_mfma_f32_16x16x32_bf16 v[48:51], v[234:237], v[186:189], v[48:51]
	v_mfma_f32_16x16x32_bf16 v[36:39], v[226:229], v[194:197], v[36:39]
	v_mfma_f32_16x16x32_bf16 v[32:35], v[234:237], v[194:197], v[32:35]
	v_mfma_f32_16x16x32_bf16 v[20:23], v[226:229], v[202:205], v[20:23]
	v_mfma_f32_16x16x32_bf16 v[16:19], v[234:237], v[202:205], v[16:19]
	v_mfma_f32_16x16x32_bf16 v[4:7], v[226:229], v[210:213], v[4:7]
	v_mfma_f32_16x16x32_bf16 v[0:3], v[234:237], v[210:213], v[0:3]
	v_mfma_f32_16x16x32_bf16 v[52:55], v[230:233], v[190:193], v[52:55]
	s_add_i32 s38, s38, 2
	v_mfma_f32_16x16x32_bf16 v[48:51], v[238:241], v[190:193], v[48:51]
	s_add_u32 s18, s18, 0x100
	v_mfma_f32_16x16x32_bf16 v[36:39], v[230:233], v[198:201], v[36:39]
	s_addc_u32 s19, s19, 0
	v_mfma_f32_16x16x32_bf16 v[32:35], v[238:241], v[198:201], v[32:35]
	s_add_u32 s33, s33, 0x100
	v_mfma_f32_16x16x32_bf16 v[20:23], v[230:233], v[206:209], v[20:23]
	s_addc_u32 s37, s37, 0
	v_mfma_f32_16x16x32_bf16 v[16:19], v[238:241], v[206:209], v[16:19]
	s_cmp_gt_u32 s38, 29
	v_mfma_f32_16x16x32_bf16 v[4:7], v[230:233], v[214:217], v[4:7]
	s_setprio 0
	v_mfma_f32_16x16x32_bf16 v[0:3], v[238:241], v[214:217], v[0:3]
	s_barrier
	s_cbranch_scc0 .LBB0_37
	v_mul_f32_e32 v139, 0xbfb8aa3b, v124
	v_exp_f32_e32 v139, v139
	v_lshl_or_b32 v140, s2, 7, v136
	v_lshl_add_u32 v138, s3, 8, v134
	v_ashrrev_i32_e32 v141, 31, v140
	v_add_f32_e32 v139, 1.0, v139
	v_rcp_f32_e32 v142, v139
	v_mul_f32_e32 v139, 0xbfb8aa3b, v125
	v_exp_f32_e32 v139, v139
	s_movk_i32 s4, 0x2c00
	s_and_b64 vcc, exec, s[6:7]
	s_mov_b64 s[20:21], s[16:17]
	v_add_f32_e32 v139, 1.0, v139
	v_rcp_f32_e32 v143, v139
	v_mul_f32_e32 v139, 0xbfb8aa3b, v126
	v_exp_f32_e32 v139, v139
	s_mov_b64 s[18:19], s[14:15]
	v_pk_mul_f32 v[124:125], v[124:125], v[142:143]
	v_add_f32_e32 v139, 1.0, v139
	v_rcp_f32_e32 v144, v139
	v_mul_f32_e32 v139, 0xbfb8aa3b, v127
	v_exp_f32_e32 v139, v139
	v_pk_mul_f32 v[116:117], v[124:125], v[116:117]
	v_add_f32_e32 v139, 1.0, v139
	v_rcp_f32_e32 v145, v139
	v_mul_f32_e32 v139, 0xbfb8aa3b, v120
	v_exp_f32_e32 v139, v139
	v_cvt_pk_bf16_f32 v116, v116, v117
	v_pk_mul_f32 v[124:125], v[126:127], v[144:145]
	v_add_f32_e32 v139, 1.0, v139
	v_rcp_f32_e32 v146, v139
	v_mul_f32_e32 v139, 0xbfb8aa3b, v121
	v_exp_f32_e32 v139, v139
	v_pk_mul_f32 v[118:119], v[124:125], v[118:119]
	v_add_f32_e32 v139, 1.0, v139
	v_rcp_f32_e32 v147, v139
	v_mul_f32_e32 v139, 0xbfb8aa3b, v122
	v_exp_f32_e32 v139, v139
	v_cvt_pk_bf16_f32 v117, v118, v119
	v_pk_mul_f32 v[118:119], v[120:121], v[146:147]
	v_add_f32_e32 v139, 1.0, v139
	v_rcp_f32_e32 v148, v139
	v_mul_f32_e32 v139, 0xbfb8aa3b, v123
	v_exp_f32_e32 v139, v139
	v_pk_mul_f32 v[112:113], v[118:119], v[112:113]
	v_add_f32_e32 v139, 1.0, v139
	v_rcp_f32_e32 v149, v139
	v_cvt_pk_bf16_f32 v118, v112, v113
	v_pk_mul_f32 v[112:113], v[122:123], v[148:149]
	s_nop 0
	v_pk_mul_f32 v[112:113], v[112:113], v[114:115]
	v_lshlrev_b64 v[114:115], 1, v[140:141]
	v_cvt_pk_bf16_f32 v119, v112, v113
	v_mov_b64_e32 v[112:113], s[54:55]
	v_mad_i64_i32 v[120:121], s[2:3], v138, s4, v[112:113]
	v_lshl_add_u64 v[120:121], v[120:121], 0, v[114:115]
	global_store_dwordx4 v[120:121], v[116:119], off
	v_mul_f32_e32 v120, 0xbfb8aa3b, v104
	v_mul_f32_e32 v121, 0xbfb8aa3b, v105
	v_mul_f32_e32 v116, 0xbfb8aa3b, v108
	v_mul_f32_e32 v117, 0xbfb8aa3b, v109
	v_exp_f32_e32 v116, v116
	v_exp_f32_e32 v117, v117
	v_mul_f32_e32 v118, 0xbfb8aa3b, v110
	v_mul_f32_e32 v119, 0xbfb8aa3b, v111
	v_exp_f32_e32 v118, v118
	v_exp_f32_e32 v119, v119
	v_exp_f32_e32 v120, v120
	v_exp_f32_e32 v121, v121
	v_add_f32_e32 v116, 1.0, v116
	v_add_f32_e32 v117, 1.0, v117
	v_mul_f32_e32 v122, 0xbfb8aa3b, v106
	v_mul_f32_e32 v123, 0xbfb8aa3b, v107
	v_rcp_f32_e32 v116, v116
	v_rcp_f32_e32 v117, v117
	v_add_f32_e32 v118, 1.0, v118
	v_add_f32_e32 v119, 1.0, v119
	v_exp_f32_e32 v122, v122
	v_exp_f32_e32 v123, v123
	v_rcp_f32_e32 v118, v118
	v_rcp_f32_e32 v119, v119
	v_add_f32_e32 v120, 1.0, v120
	v_add_f32_e32 v121, 1.0, v121
	v_rcp_f32_e32 v120, v120
	v_rcp_f32_e32 v121, v121
	v_add_f32_e32 v122, 1.0, v122
	v_add_f32_e32 v123, 1.0, v123
	v_pk_mul_f32 v[108:109], v[108:109], v[116:117]
	v_rcp_f32_e32 v122, v122
;     DI void operator()(const f32x4 (&acc)[2][2][4][2], const Unit& u, int wr, int wc, int fr, int fq) const {
;     ...
;             for (int m = 0; m < 4; ++m) { float hv[8];
; #pragma unroll
;                 for (int n = 0; n < 2; ++n)
; #pragma unroll
;                     for (int e = 0; e < 4; ++e) { const float gt = acc[ai][0][m][n][e], up = acc[ai][1][m][n][e];
;                         hv[n * 4 + e] = gt * __builtin_amdgcn_rcpf(1.f + __builtin_amdgcn_exp2f(-1.4426950408889634f * gt)) * up; }
;                 *(u32x4*)(H + (size_t)(row0 + ai * HALF + m * 16) * DFF + col0) = (u32x4){pk(hv[0], hv[1]), pk(hv[2], hv[3]), pk(hv[4], hv[5]), pk(hv[6], hv[7])}; }
	v_rcp_f32_e32 v123, v123
	v_pk_mul_f32 v[100:101], v[108:109], v[100:101]
	v_pk_mul_f32 v[108:109], v[110:111], v[118:119]
	v_cvt_pk_bf16_f32 v100, v100, v101
	v_pk_mul_f32 v[102:103], v[108:109], v[102:103]
	s_nop 0
	v_cvt_pk_bf16_f32 v101, v102, v103
	v_pk_mul_f32 v[102:103], v[104:105], v[120:121]
	s_nop 0
	v_pk_mul_f32 v[96:97], v[102:103], v[96:97]
	s_nop 0
	v_cvt_pk_bf16_f32 v102, v96, v97
	v_pk_mul_f32 v[96:97], v[106:107], v[122:123]
	s_nop 0
	v_pk_mul_f32 v[96:97], v[96:97], v[98:99]
	v_mul_f32_e32 v98, 0xbfb8aa3b, v94
	v_cvt_pk_bf16_f32 v103, v96, v97
	v_or_b32_e32 v96, 16, v138
	v_mad_i64_i32 v[96:97], s[2:3], v96, s4, v[112:113]
	v_lshl_add_u64 v[96:97], v[96:97], 0, v[114:115]
	global_store_dwordx4 v[96:97], v[100:103], off
	v_mul_f32_e32 v96, 0xbfb8aa3b, v92
	v_mul_f32_e32 v97, 0xbfb8aa3b, v93
	v_exp_f32_e32 v96, v96
	v_exp_f32_e32 v97, v97
	v_mul_f32_e32 v99, 0xbfb8aa3b, v95
	v_exp_f32_e32 v98, v98
	v_exp_f32_e32 v99, v99
	v_mul_f32_e32 v100, 0xbfb8aa3b, v88
	v_mul_f32_e32 v101, 0xbfb8aa3b, v89
	v_exp_f32_e32 v100, v100
	v_exp_f32_e32 v101, v101
	v_add_f32_e32 v96, 1.0, v96
	v_add_f32_e32 v97, 1.0, v97
	v_mul_f32_e32 v102, 0xbfb8aa3b, v90
	v_mul_f32_e32 v103, 0xbfb8aa3b, v91
	v_rcp_f32_e32 v96, v96
	v_rcp_f32_e32 v97, v97
	v_add_f32_e32 v98, 1.0, v98
	v_add_f32_e32 v99, 1.0, v99
	v_exp_f32_e32 v102, v102
	v_exp_f32_e32 v103, v103
	v_rcp_f32_e32 v98, v98
	v_rcp_f32_e32 v99, v99
	v_add_f32_e32 v100, 1.0, v100
	v_add_f32_e32 v101, 1.0, v101
	v_rcp_f32_e32 v100, v100
	v_rcp_f32_e32 v101, v101
	v_add_f32_e32 v102, 1.0, v102
	v_add_f32_e32 v103, 1.0, v103
	v_pk_mul_f32 v[92:93], v[92:93], v[96:97]
	v_rcp_f32_e32 v102, v102
	v_rcp_f32_e32 v103, v103
	v_pk_mul_f32 v[84:85], v[92:93], v[84:85]
	v_pk_mul_f32 v[92:93], v[94:95], v[98:99]
	v_cvt_pk_bf16_f32 v84, v84, v85
	v_pk_mul_f32 v[86:87], v[92:93], v[86:87]
	s_nop 0
	v_cvt_pk_bf16_f32 v85, v86, v87
	v_pk_mul_f32 v[86:87], v[88:89], v[100:101]
	s_nop 0
	v_pk_mul_f32 v[80:81], v[86:87], v[80:81]
	s_nop 0
	v_cvt_pk_bf16_f32 v86, v80, v81
	v_pk_mul_f32 v[80:81], v[90:91], v[102:103]
	s_nop 0
	v_pk_mul_f32 v[80:81], v[80:81], v[82:83]
	v_mul_f32_e32 v82, 0xbfb8aa3b, v78
	v_cvt_pk_bf16_f32 v87, v80, v81
	v_or_b32_e32 v80, 32, v138
	v_mad_i64_i32 v[80:81], s[2:3], v80, s4, v[112:113]
	v_lshl_add_u64 v[80:81], v[80:81], 0, v[114:115]
	global_store_dwordx4 v[80:81], v[84:87], off
	v_mul_f32_e32 v80, 0xbfb8aa3b, v76
	v_mul_f32_e32 v81, 0xbfb8aa3b, v77
	v_exp_f32_e32 v80, v80
	v_exp_f32_e32 v81, v81
	v_mul_f32_e32 v83, 0xbfb8aa3b, v79
	v_exp_f32_e32 v82, v82
	v_exp_f32_e32 v83, v83
	v_mul_f32_e32 v84, 0xbfb8aa3b, v72
	v_mul_f32_e32 v85, 0xbfb8aa3b, v73
	v_exp_f32_e32 v84, v84
	v_exp_f32_e32 v85, v85
	v_add_f32_e32 v80, 1.0, v80
	v_add_f32_e32 v81, 1.0, v81
	v_mul_f32_e32 v86, 0xbfb8aa3b, v74
	v_mul_f32_e32 v87, 0xbfb8aa3b, v75
	v_rcp_f32_e32 v80, v80
	v_rcp_f32_e32 v81, v81
	v_add_f32_e32 v82, 1.0, v82
	v_add_f32_e32 v83, 1.0, v83
	v_exp_f32_e32 v86, v86
	v_exp_f32_e32 v87, v87
	v_rcp_f32_e32 v82, v82
	v_rcp_f32_e32 v83, v83
	v_add_f32_e32 v84, 1.0, v84
	v_add_f32_e32 v85, 1.0, v85
	v_rcp_f32_e32 v84, v84
	v_rcp_f32_e32 v85, v85
	v_add_f32_e32 v86, 1.0, v86
	v_add_f32_e32 v87, 1.0, v87
	v_pk_mul_f32 v[76:77], v[76:77], v[80:81]
	v_rcp_f32_e32 v86, v86
	v_rcp_f32_e32 v87, v87
	v_pk_mul_f32 v[68:69], v[76:77], v[68:69]
	v_pk_mul_f32 v[76:77], v[78:79], v[82:83]
	v_cvt_pk_bf16_f32 v68, v68, v69
	v_pk_mul_f32 v[70:71], v[76:77], v[70:71]
	s_nop 0
	v_cvt_pk_bf16_f32 v69, v70, v71
	v_pk_mul_f32 v[70:71], v[72:73], v[84:85]
	v_add_u32_e32 v72, 0x80, v138
	v_pk_mul_f32 v[64:65], v[70:71], v[64:65]
	s_nop 0
	v_cvt_pk_bf16_f32 v70, v64, v65
	v_pk_mul_f32 v[64:65], v[74:75], v[86:87]
	s_nop 0
	v_pk_mul_f32 v[64:65], v[64:65], v[66:67]
	v_mul_f32_e32 v66, 0xbfb8aa3b, v62
	v_cvt_pk_bf16_f32 v71, v64, v65
	v_or_b32_e32 v64, 48, v138
	v_mad_i64_i32 v[64:65], s[2:3], v64, s4, v[112:113]
	v_lshl_add_u64 v[64:65], v[64:65], 0, v[114:115]
	global_store_dwordx4 v[64:65], v[68:71], off
	v_mul_f32_e32 v64, 0xbfb8aa3b, v60
	v_mul_f32_e32 v65, 0xbfb8aa3b, v61
	v_exp_f32_e32 v64, v64
	v_exp_f32_e32 v65, v65
	v_mul_f32_e32 v67, 0xbfb8aa3b, v63
	v_exp_f32_e32 v66, v66
	v_exp_f32_e32 v67, v67
	v_mul_f32_e32 v68, 0xbfb8aa3b, v56
	v_mul_f32_e32 v69, 0xbfb8aa3b, v57
	v_exp_f32_e32 v68, v68
	v_exp_f32_e32 v69, v69
	v_add_f32_e32 v64, 1.0, v64
	v_add_f32_e32 v65, 1.0, v65
	v_mul_f32_e32 v70, 0xbfb8aa3b, v58
	v_mul_f32_e32 v71, 0xbfb8aa3b, v59
	v_rcp_f32_e32 v64, v64
	v_rcp_f32_e32 v65, v65
	v_add_f32_e32 v66, 1.0, v66
	v_add_f32_e32 v67, 1.0, v67
	v_exp_f32_e32 v70, v70
	v_exp_f32_e32 v71, v71
	v_rcp_f32_e32 v66, v66
	v_rcp_f32_e32 v67, v67
	v_add_f32_e32 v68, 1.0, v68
	v_add_f32_e32 v69, 1.0, v69
	v_rcp_f32_e32 v68, v68
	v_rcp_f32_e32 v69, v69
	v_add_f32_e32 v70, 1.0, v70
	v_add_f32_e32 v71, 1.0, v71
	v_pk_mul_f32 v[60:61], v[60:61], v[64:65]
	v_rcp_f32_e32 v70, v70
	v_rcp_f32_e32 v71, v71
	v_pk_mul_f32 v[52:53], v[60:61], v[52:53]
	v_pk_mul_f32 v[60:61], v[62:63], v[66:67]
	v_cvt_pk_bf16_f32 v52, v52, v53
	v_pk_mul_f32 v[54:55], v[60:61], v[54:55]
	s_nop 0
	v_cvt_pk_bf16_f32 v53, v54, v55
	v_pk_mul_f32 v[54:55], v[56:57], v[68:69]
	s_nop 0
	v_pk_mul_f32 v[48:49], v[54:55], v[48:49]
; #define PG8_WAIT_V(n) asm volatile("s_waitcnt vmcnt(" #n ")" ::: "memory")
; #define PG8_BAR __builtin_amdgcn_s_barrier()
; template <class Epi>
; DI void gemm_phase(LAS unsigned char* lds, const Gemm g, const StaticOrder& S, const Epi& E) {
;     ...
;         E(acc, cur, wr, wc, fr, fq);
;         if (!has_next) break;
; #pragma unroll
;         for (int a = 0; a < 2; ++a)
; #pragma unroll
;             for (int b = 0; b < 2; ++b)
; #pragma unroll
;                 for (int m = 0; m < 4; ++m)
; #pragma unroll
;                     for (int n = 0; n < 2; ++n) acc[a][b][m][n] = (f32x4){0.f, 0.f, 0.f, 0.f};
;         cur = nxt; cA = nA; cB = nB; ++ui;
;     }
;     PG8_WAIT_V(0);
;     if (wr == 0) PG8_BAR;
;     DI void operator()(const f32x4 (&acc)[2][2][4][2], const Unit& u, int wr, int wc, int fr, int fq) const {
;     ...
;             for (int m = 0; m < 4; ++m) { float hv[8];
; #pragma unroll
;                 for (int n = 0; n < 2; ++n)
; #pragma unroll
;                     for (int e = 0; e < 4; ++e) { const float gt = acc[ai][0][m][n][e], up = acc[ai][1][m][n][e];
;                         hv[n * 4 + e] = gt * __builtin_amdgcn_rcpf(1.f + __builtin_amdgcn_exp2f(-1.4426950408889634f * gt)) * up; }
;                 *(u32x4*)(H + (size_t)(row0 + ai * HALF + m * 16) * DFF + col0) = (u32x4){pk(hv[0], hv[1]), pk(hv[2], hv[3]), pk(hv[4], hv[5]), pk(hv[6], hv[7])}; }
	s_nop 0
	v_cvt_pk_bf16_f32 v54, v48, v49
	v_pk_mul_f32 v[48:49], v[58:59], v[70:71]
	s_nop 0
	v_pk_mul_f32 v[48:49], v[48:49], v[50:51]
	v_mul_f32_e32 v50, 0xbfb8aa3b, v46
	v_cvt_pk_bf16_f32 v55, v48, v49
	v_mad_i64_i32 v[48:49], s[2:3], v72, s4, v[112:113]
	v_lshl_add_u64 v[48:49], v[48:49], 0, v[114:115]
	global_store_dwordx4 v[48:49], v[52:55], off
	v_mul_f32_e32 v48, 0xbfb8aa3b, v44
	v_mul_f32_e32 v49, 0xbfb8aa3b, v45
	v_exp_f32_e32 v48, v48
	v_exp_f32_e32 v49, v49
	v_mul_f32_e32 v51, 0xbfb8aa3b, v47
	v_exp_f32_e32 v50, v50
	v_exp_f32_e32 v51, v51
	v_mul_f32_e32 v52, 0xbfb8aa3b, v40
	v_mul_f32_e32 v53, 0xbfb8aa3b, v41
	v_exp_f32_e32 v52, v52
	v_exp_f32_e32 v53, v53
	v_add_f32_e32 v48, 1.0, v48
	v_add_f32_e32 v49, 1.0, v49
	v_mul_f32_e32 v54, 0xbfb8aa3b, v42
	v_mul_f32_e32 v55, 0xbfb8aa3b, v43
	v_rcp_f32_e32 v48, v48
	v_rcp_f32_e32 v49, v49
	v_add_f32_e32 v50, 1.0, v50
	v_add_f32_e32 v51, 1.0, v51
	v_exp_f32_e32 v54, v54
	v_exp_f32_e32 v55, v55
	v_rcp_f32_e32 v50, v50
	v_rcp_f32_e32 v51, v51
	v_add_f32_e32 v52, 1.0, v52
	v_add_f32_e32 v53, 1.0, v53
	v_rcp_f32_e32 v52, v52
	v_rcp_f32_e32 v53, v53
	v_add_f32_e32 v54, 1.0, v54
	v_add_f32_e32 v55, 1.0, v55
	v_pk_mul_f32 v[44:45], v[44:45], v[48:49]
	v_rcp_f32_e32 v54, v54
	v_rcp_f32_e32 v55, v55
	v_pk_mul_f32 v[36:37], v[44:45], v[36:37]
	v_pk_mul_f32 v[44:45], v[46:47], v[50:51]
	v_cvt_pk_bf16_f32 v36, v36, v37
	v_pk_mul_f32 v[38:39], v[44:45], v[38:39]
	s_nop 0
	v_cvt_pk_bf16_f32 v37, v38, v39
	v_pk_mul_f32 v[38:39], v[40:41], v[52:53]
	s_nop 0
	v_pk_mul_f32 v[32:33], v[38:39], v[32:33]
	s_nop 0
	v_cvt_pk_bf16_f32 v38, v32, v33
	v_pk_mul_f32 v[32:33], v[42:43], v[54:55]
	s_nop 0
	v_pk_mul_f32 v[32:33], v[32:33], v[34:35]
	v_mul_f32_e32 v34, 0xbfb8aa3b, v30
	v_cvt_pk_bf16_f32 v39, v32, v33
	v_add_u32_e32 v32, 0x90, v138
	v_mad_i64_i32 v[32:33], s[2:3], v32, s4, v[112:113]
	v_lshl_add_u64 v[32:33], v[32:33], 0, v[114:115]
	global_store_dwordx4 v[32:33], v[36:39], off
	v_mul_f32_e32 v32, 0xbfb8aa3b, v28
	v_mul_f32_e32 v33, 0xbfb8aa3b, v29
	v_exp_f32_e32 v32, v32
	v_exp_f32_e32 v33, v33
	v_mul_f32_e32 v35, 0xbfb8aa3b, v31
	v_exp_f32_e32 v34, v34
	v_exp_f32_e32 v35, v35
	v_mul_f32_e32 v36, 0xbfb8aa3b, v24
	v_mul_f32_e32 v37, 0xbfb8aa3b, v25
	v_exp_f32_e32 v36, v36
	v_exp_f32_e32 v37, v37
	v_add_f32_e32 v32, 1.0, v32
	v_add_f32_e32 v33, 1.0, v33
	v_mul_f32_e32 v38, 0xbfb8aa3b, v26
	v_mul_f32_e32 v39, 0xbfb8aa3b, v27
	v_rcp_f32_e32 v32, v32
	v_rcp_f32_e32 v33, v33
	v_add_f32_e32 v34, 1.0, v34
	v_add_f32_e32 v35, 1.0, v35
	v_exp_f32_e32 v38, v38
	v_exp_f32_e32 v39, v39
	v_rcp_f32_e32 v34, v34
	v_rcp_f32_e32 v35, v35
	v_add_f32_e32 v36, 1.0, v36
	v_add_f32_e32 v37, 1.0, v37
	v_rcp_f32_e32 v36, v36
	v_rcp_f32_e32 v37, v37
	v_add_f32_e32 v38, 1.0, v38
	v_add_f32_e32 v39, 1.0, v39
	v_pk_mul_f32 v[28:29], v[28:29], v[32:33]
	v_rcp_f32_e32 v38, v38
	v_rcp_f32_e32 v39, v39
	v_pk_mul_f32 v[20:21], v[28:29], v[20:21]
	v_pk_mul_f32 v[28:29], v[30:31], v[34:35]
	v_cvt_pk_bf16_f32 v20, v20, v21
	v_pk_mul_f32 v[22:23], v[28:29], v[22:23]
	s_nop 0
	v_cvt_pk_bf16_f32 v21, v22, v23
	v_pk_mul_f32 v[22:23], v[24:25], v[36:37]
	s_nop 0
	v_pk_mul_f32 v[16:17], v[22:23], v[16:17]
	s_nop 0
	v_cvt_pk_bf16_f32 v22, v16, v17
	v_pk_mul_f32 v[16:17], v[26:27], v[38:39]
	s_nop 0
	v_pk_mul_f32 v[16:17], v[16:17], v[18:19]
	v_mul_f32_e32 v18, 0xbfb8aa3b, v14
	v_cvt_pk_bf16_f32 v23, v16, v17
	v_add_u32_e32 v16, 0xa0, v138
	v_mad_i64_i32 v[16:17], s[2:3], v16, s4, v[112:113]
	v_lshl_add_u64 v[16:17], v[16:17], 0, v[114:115]
	global_store_dwordx4 v[16:17], v[20:23], off
	v_mul_f32_e32 v16, 0xbfb8aa3b, v12
	v_mul_f32_e32 v17, 0xbfb8aa3b, v13
	v_exp_f32_e32 v16, v16
	v_exp_f32_e32 v17, v17
	v_mul_f32_e32 v19, 0xbfb8aa3b, v15
	v_exp_f32_e32 v18, v18
	v_exp_f32_e32 v19, v19
	v_mul_f32_e32 v20, 0xbfb8aa3b, v8
	v_mul_f32_e32 v21, 0xbfb8aa3b, v9
	v_exp_f32_e32 v20, v20
	v_exp_f32_e32 v21, v21
	v_add_f32_e32 v16, 1.0, v16
	v_add_f32_e32 v17, 1.0, v17
	v_mul_f32_e32 v22, 0xbfb8aa3b, v10
	v_mul_f32_e32 v23, 0xbfb8aa3b, v11
	v_rcp_f32_e32 v16, v16
	v_rcp_f32_e32 v17, v17
	v_add_f32_e32 v18, 1.0, v18
	v_add_f32_e32 v19, 1.0, v19
	v_exp_f32_e32 v22, v22
	v_exp_f32_e32 v23, v23
	v_rcp_f32_e32 v18, v18
	v_rcp_f32_e32 v19, v19
	v_add_f32_e32 v20, 1.0, v20
	v_add_f32_e32 v21, 1.0, v21
	v_rcp_f32_e32 v20, v20
	v_rcp_f32_e32 v21, v21
	v_add_f32_e32 v22, 1.0, v22
	v_add_f32_e32 v23, 1.0, v23
	v_pk_mul_f32 v[12:13], v[12:13], v[16:17]
	v_rcp_f32_e32 v22, v22
	v_rcp_f32_e32 v23, v23
	v_pk_mul_f32 v[4:5], v[12:13], v[4:5]
	v_pk_mul_f32 v[12:13], v[14:15], v[18:19]
	v_cvt_pk_bf16_f32 v4, v4, v5
	v_pk_mul_f32 v[6:7], v[12:13], v[6:7]
	s_nop 0
	v_cvt_pk_bf16_f32 v5, v6, v7
	v_pk_mul_f32 v[6:7], v[8:9], v[20:21]
	s_nop 0
	v_pk_mul_f32 v[0:1], v[6:7], v[0:1]
	s_nop 0
	v_cvt_pk_bf16_f32 v6, v0, v1
	v_pk_mul_f32 v[0:1], v[10:11], v[22:23]
	s_nop 0
	v_pk_mul_f32 v[0:1], v[0:1], v[2:3]
	s_nop 0
	v_cvt_pk_bf16_f32 v7, v0, v1
	v_add_u32_e32 v0, 0xb0, v138
	v_mad_i64_i32 v[0:1], s[2:3], v0, s4, v[112:113]
	v_lshl_add_u64 v[0:1], v[0:1], 0, v[114:115]
	s_mov_b32 s2, s8
	s_mov_b32 s3, s10
	global_store_dwordx4 v[0:1], v[4:7], off
	s_cbranch_vccz .LBB0_34
	s_waitcnt vmcnt(0)
	s_cmpk_gt_u32 s24, 0xff
	s_cbranch_scc1 .LBB0_41
	s_barrier

; #define PG8_STAGE(bufoff, gbase) do { _Pragma("unroll") for (int _i = 0; _i < 2; ++_i) \
;         __builtin_amdgcn_global_load_lds((const unsigned*)((const char*)(gbase) + voff[_i]), (LAS unsigned*)(lds + (bufoff) + ldsw + _i * 8192), 16, 0, 0); } while (0)
; #define PG8_LDA(dst, b, h) do { _Pragma("unroll") for (int m = 0; m < 4; ++m) _Pragma("unroll") for (int k = 0; k < 2; ++k) dst[m][k] = *(const LAS bf16x8*)(lds + PG8_SA(b, h) + aoff + m * 2048 + k * 1024); } while (0)
; #define PG8_LDB(dst, b, h) do { _Pragma("unroll") for (int n = 0; n < 2; ++n) _Pragma("unroll") for (int k = 0; k < 2; ++k) dst[n][k] = *(const LAS bf16x8*)(lds + PG8_SB(b, h) + boff + n * 2048 + k * 1024); } while (0)
; #define PG8_MMA(ai, bj, At, Bt) do { __builtin_amdgcn_s_setprio(1); _Pragma("unroll") for (int m = 0; m < 4; ++m) _Pragma("unroll") for (int n = 0; n < 2; ++n) _Pragma("unroll") for (int k = 0; k < 2; ++k) \
;         acc[ai][bj][m][n] = __builtin_amdgcn_mfma_f32_16x16x32_bf16(Bt[n][k], At[m][k], acc[ai][bj][m][n], 0, 0, 0); __builtin_amdgcn_s_setprio(0); } while (0)
; #define PG8_WAIT_V(n) asm volatile("s_waitcnt vmcnt(" #n ")" ::: "memory")
; #define PG8_WAIT_L(n) asm volatile("s_waitcnt lgkmcnt(" #n ")" ::: "memory")
; #define PG8_BAR __builtin_amdgcn_s_barrier()
; #define PG8_SCHED __builtin_amdgcn_sched_barrier(0)
; template <class Epi>
; DI void gemm_phase(LAS unsigned char* lds, const Gemm g, const StaticOrder& S, const Epi& E) {
;     ...
;             const bool last = (t == nt - 2);
;             const char* a1 = cA + (size_t)(t + 1) * kstep;
;             const char* a2 = last ? nA : cA + (size_t)(t + 2) * kstep; const char* b2 = last ? nB : cB + (size_t)(t + 2) * kstep;
;             const char* a3 = a2 + kstep; const char* b3 = b2 + kstep;
;             PG8_LDB(B0, 0, 0); PG8_SCHED; PG8_LDA(At, 0, 0); PG8_STAGE(PG8_SA(1, 1), a1 + hstep);
;             PG8_WAIT_L(8); PG8_BAR; PG8_WAIT_L(0); PG8_MMA(0, 0, At, B0); PG8_BAR; PG8_SCHED;
;             PG8_LDB(B1, 0, 1); PG8_STAGE(PG8_SB(0, 0), b2);
;             PG8_BAR; PG8_WAIT_L(0); PG8_MMA(0, 1, At, B1); PG8_BAR;
;             PG8_LDA(At, 0, 1); PG8_STAGE(PG8_SA(0, 0), a2);
;             PG8_BAR; PG8_WAIT_L(0); PG8_MMA(1, 0, At, B0); PG8_BAR; PG8_SCHED;
;             PG8_STAGE(PG8_SB(0, 1), b2 + hstep);
;             PG8_WAIT_V(6); PG8_BAR; PG8_MMA(1, 1, At, B1); PG8_BAR;
.LBB0_77:
	ds_read_b128 v[128:131], v226
	ds_read_b128 v[132:135], v226 offset:1024
	ds_read_b128 v[136:139], v226 offset:2048
	ds_read_b128 v[140:143], v226 offset:3072
	ds_read_b128 v[144:147], v228
	ds_read_b128 v[148:151], v228 offset:1024
	ds_read_b128 v[152:155], v228 offset:2048
	ds_read_b128 v[194:197], v228 offset:3072
	ds_read_b128 v[198:201], v228 offset:4096
	ds_read_b128 v[202:205], v228 offset:5120
	ds_read_b128 v[206:209], v228 offset:6144
	ds_read_b128 v[210:213], v228 offset:7168
	s_add_u32 s22, s20, 0x100
	s_addc_u32 s23, s21, 0
	s_add_i32 s43, 0, 0x10000
	s_cmp_eq_u32 s33, 32
	s_cselect_b32 s27, s9, s23
	s_cselect_b32 s26, s8, s22
	s_cselect_b32 s25, s11, s5
	s_cselect_b32 s24, s10, s4
	s_add_i32 m0, s34, 0xc000
	s_nop 0
	global_load_lds_dwordx4 v190, s[20:21]
	s_add_i32 m0, s34, 0xe000
	s_nop 0
	global_load_lds_dwordx4 v192, s[20:21]
	s_waitcnt lgkmcnt(0)
	s_setprio 1
	s_barrier
	v_mfma_f32_16x16x32_bf16 v[124:127], v[128:131], v[144:147], v[124:127]
	v_mfma_f32_16x16x32_bf16 v[120:123], v[136:139], v[144:147], v[120:123]
	v_mfma_f32_16x16x32_bf16 v[116:119], v[128:131], v[152:155], v[116:119]
	v_mfma_f32_16x16x32_bf16 v[112:115], v[136:139], v[152:155], v[112:115]
	v_mfma_f32_16x16x32_bf16 v[108:111], v[128:131], v[198:201], v[108:111]
	v_mfma_f32_16x16x32_bf16 v[104:107], v[136:139], v[198:201], v[104:107]
	v_mfma_f32_16x16x32_bf16 v[100:103], v[128:131], v[206:209], v[100:103]
	v_mfma_f32_16x16x32_bf16 v[96:99], v[136:139], v[206:209], v[96:99]
	v_mfma_f32_16x16x32_bf16 v[124:127], v[132:135], v[148:151], v[124:127]
	v_mfma_f32_16x16x32_bf16 v[120:123], v[140:143], v[148:151], v[120:123]
	v_mfma_f32_16x16x32_bf16 v[116:119], v[132:135], v[194:197], v[116:119]
	v_mfma_f32_16x16x32_bf16 v[112:115], v[140:143], v[194:197], v[112:115]
	v_mfma_f32_16x16x32_bf16 v[108:111], v[132:135], v[202:205], v[108:111]
	v_mfma_f32_16x16x32_bf16 v[104:107], v[140:143], v[202:205], v[104:107]
	v_mfma_f32_16x16x32_bf16 v[100:103], v[132:135], v[210:213], v[100:103]
	s_setprio 0
	v_mfma_f32_16x16x32_bf16 v[96:99], v[140:143], v[210:213], v[96:99]
	s_barrier
	ds_read_b128 v[214:217], v226 offset:16384
	ds_read_b128 v[230:233], v226 offset:17408
	ds_read_b128 v[234:237], v226 offset:18432
	ds_read_b128 v[238:241], v226 offset:19456
	s_add_i32 s44, 0, 0x14000
	s_add_i32 s20, s43, s31
	s_mov_b32 m0, s20
	s_nop 0
	global_load_lds_dwordx4 v188, s[24:25]
	s_add_i32 m0, s20, 0x2000
	s_nop 0
	global_load_lds_dwordx4 v186, s[24:25]
	s_waitcnt lgkmcnt(0)
	s_setprio 1
	s_barrier
	v_mfma_f32_16x16x32_bf16 v[60:63], v[214:217], v[144:147], v[60:63]
	v_mfma_f32_16x16x32_bf16 v[56:59], v[234:237], v[144:147], v[56:59]
	v_mfma_f32_16x16x32_bf16 v[52:55], v[214:217], v[152:155], v[52:55]
	v_mfma_f32_16x16x32_bf16 v[48:51], v[234:237], v[152:155], v[48:51]
	v_mfma_f32_16x16x32_bf16 v[44:47], v[214:217], v[198:201], v[44:47]
	v_mfma_f32_16x16x32_bf16 v[40:43], v[234:237], v[198:201], v[40:43]
	v_mfma_f32_16x16x32_bf16 v[36:39], v[214:217], v[206:209], v[36:39]
	v_mfma_f32_16x16x32_bf16 v[32:35], v[234:237], v[206:209], v[32:35]
	v_mfma_f32_16x16x32_bf16 v[60:63], v[230:233], v[148:151], v[60:63]
	s_mov_b32 m0, s34
	v_mfma_f32_16x16x32_bf16 v[56:59], v[238:241], v[148:151], v[56:59]
	v_mfma_f32_16x16x32_bf16 v[52:55], v[230:233], v[194:197], v[52:55]
	v_mfma_f32_16x16x32_bf16 v[48:51], v[238:241], v[194:197], v[48:51]
	v_mfma_f32_16x16x32_bf16 v[44:47], v[230:233], v[202:205], v[44:47]
	v_mfma_f32_16x16x32_bf16 v[40:43], v[238:241], v[202:205], v[40:43]
	v_mfma_f32_16x16x32_bf16 v[36:39], v[230:233], v[210:213], v[36:39]
	s_setprio 0
	v_mfma_f32_16x16x32_bf16 v[32:35], v[238:241], v[210:213], v[32:35]
	s_barrier
	ds_read_b128 v[144:147], v228 offset:16384
	ds_read_b128 v[148:151], v228 offset:17408
	ds_read_b128 v[152:155], v228 offset:18432
	ds_read_b128 v[194:197], v228 offset:19456
	ds_read_b128 v[198:201], v228 offset:20480
	ds_read_b128 v[202:205], v228 offset:21504
	ds_read_b128 v[206:209], v228 offset:22528
	ds_read_b128 v[210:213], v228 offset:23552
	global_load_lds_dwordx4 v188, s[26:27]
	s_mov_b64 s[100:101], s[26:27]
	s_mov_b32 m0, s35
	s_nop 0
	global_load_lds_dwordx4 v186, s[26:27]
	s_waitcnt lgkmcnt(0)
	s_setprio 1
	s_barrier
	v_mfma_f32_16x16x32_bf16 v[92:95], v[128:131], v[144:147], v[92:95]
	v_mfma_f32_16x16x32_bf16 v[88:91], v[136:139], v[144:147], v[88:91]
	v_mfma_f32_16x16x32_bf16 v[84:87], v[128:131], v[152:155], v[84:87]
	v_mfma_f32_16x16x32_bf16 v[80:83], v[136:139], v[152:155], v[80:83]
	v_mfma_f32_16x16x32_bf16 v[76:79], v[128:131], v[198:201], v[76:79]
	v_mfma_f32_16x16x32_bf16 v[72:75], v[136:139], v[198:201], v[72:75]
	v_mfma_f32_16x16x32_bf16 v[68:71], v[128:131], v[206:209], v[68:71]
	v_mfma_f32_16x16x32_bf16 v[64:67], v[136:139], v[206:209], v[64:67]
	v_mfma_f32_16x16x32_bf16 v[92:95], v[132:135], v[148:151], v[92:95]
	v_mfma_f32_16x16x32_bf16 v[88:91], v[140:143], v[148:151], v[88:91]
	v_mfma_f32_16x16x32_bf16 v[84:87], v[132:135], v[194:197], v[84:87]
	v_mfma_f32_16x16x32_bf16 v[80:83], v[140:143], v[194:197], v[80:83]
	v_mfma_f32_16x16x32_bf16 v[76:79], v[132:135], v[202:205], v[76:79]
	v_mfma_f32_16x16x32_bf16 v[72:75], v[140:143], v[202:205], v[72:75]
	v_mfma_f32_16x16x32_bf16 v[68:71], v[132:135], v[210:213], v[68:71]
	s_setprio 0
	v_mfma_f32_16x16x32_bf16 v[64:67], v[140:143], v[210:213], v[64:67]
	s_barrier
	s_add_u32 s20, s24, 0x90000
	s_addc_u32 s21, s25, 0
	s_add_i32 s43, s44, s31
	s_mov_b32 m0, s43
	s_nop 0
	global_load_lds_dwordx4 v188, s[20:21]
	s_add_i32 m0, s43, 0x2000
	s_nop 0
	global_load_lds_dwordx4 v186, s[20:21]
	s_waitcnt vmcnt(6)
	s_setprio 1
	s_barrier
; #define PG8_STAGE(bufoff, gbase) do { _Pragma("unroll") for (int _i = 0; _i < 2; ++_i) \
;         __builtin_amdgcn_global_load_lds((const unsigned*)((const char*)(gbase) + voff[_i]), (LAS unsigned*)(lds + (bufoff) + ldsw + _i * 8192), 16, 0, 0); } while (0)
; #define PG8_LDA(dst, b, h) do { _Pragma("unroll") for (int m = 0; m < 4; ++m) _Pragma("unroll") for (int k = 0; k < 2; ++k) dst[m][k] = *(const LAS bf16x8*)(lds + PG8_SA(b, h) + aoff + m * 2048 + k * 1024); } while (0)
; #define PG8_LDB(dst, b, h) do { _Pragma("unroll") for (int n = 0; n < 2; ++n) _Pragma("unroll") for (int k = 0; k < 2; ++k) dst[n][k] = *(const LAS bf16x8*)(lds + PG8_SB(b, h) + boff + n * 2048 + k * 1024); } while (0)
; #define PG8_MMA(ai, bj, At, Bt) do { __builtin_amdgcn_s_setprio(1); _Pragma("unroll") for (int m = 0; m < 4; ++m) _Pragma("unroll") for (int n = 0; n < 2; ++n) _Pragma("unroll") for (int k = 0; k < 2; ++k) \
;         acc[ai][bj][m][n] = __builtin_amdgcn_mfma_f32_16x16x32_bf16(Bt[n][k], At[m][k], acc[ai][bj][m][n], 0, 0, 0); __builtin_amdgcn_s_setprio(0); } while (0)
; #define PG8_WAIT_V(n) asm volatile("s_waitcnt vmcnt(" #n ")" ::: "memory")
; #define PG8_WAIT_L(n) asm volatile("s_waitcnt lgkmcnt(" #n ")" ::: "memory")
; #define PG8_BAR __builtin_amdgcn_s_barrier()
; #define PG8_SCHED __builtin_amdgcn_sched_barrier(0)
; template <class Epi>
; DI void gemm_phase(LAS unsigned char* lds, const Gemm g, const StaticOrder& S, const Epi& E) {
;     ...
;             PG8_WAIT_V(6); PG8_BAR; PG8_MMA(1, 1, At, B1); PG8_BAR;
;             PG8_LDB(B0, 1, 0); PG8_SCHED; PG8_LDA(At, 1, 0); PG8_STAGE(PG8_SA(0, 1), a2 + hstep);
;             PG8_WAIT_L(8); PG8_BAR; PG8_WAIT_L(0); PG8_MMA(0, 0, At, B0); PG8_BAR; PG8_SCHED;
;             PG8_LDB(B1, 1, 1); PG8_STAGE(PG8_SB(1, 0), b3);
;             PG8_BAR; PG8_WAIT_L(0); PG8_MMA(0, 1, At, B1); PG8_BAR;
;             PG8_LDA(At, 1, 1); PG8_STAGE(PG8_SA(1, 0), a3);
;             PG8_BAR; PG8_WAIT_L(0); PG8_MMA(1, 0, At, B0); PG8_BAR; PG8_SCHED;
	v_mfma_f32_16x16x32_bf16 v[28:31], v[214:217], v[144:147], v[28:31]
	v_mfma_f32_16x16x32_bf16 v[24:27], v[234:237], v[144:147], v[24:27]
	v_mfma_f32_16x16x32_bf16 v[20:23], v[214:217], v[152:155], v[20:23]
	v_mfma_f32_16x16x32_bf16 v[16:19], v[234:237], v[152:155], v[16:19]
	v_mfma_f32_16x16x32_bf16 v[12:15], v[214:217], v[198:201], v[12:15]
	v_mfma_f32_16x16x32_bf16 v[8:11], v[234:237], v[198:201], v[8:11]
	v_mfma_f32_16x16x32_bf16 v[4:7], v[214:217], v[206:209], v[4:7]
	v_mfma_f32_16x16x32_bf16 v[0:3], v[234:237], v[206:209], v[0:3]
	v_mfma_f32_16x16x32_bf16 v[28:31], v[230:233], v[148:151], v[28:31]
	s_add_i32 s43, 0, 0x18000
	v_mfma_f32_16x16x32_bf16 v[24:27], v[238:241], v[148:151], v[24:27]
	v_mfma_f32_16x16x32_bf16 v[20:23], v[230:233], v[194:197], v[20:23]
	v_mfma_f32_16x16x32_bf16 v[16:19], v[238:241], v[194:197], v[16:19]
	v_mfma_f32_16x16x32_bf16 v[12:15], v[230:233], v[202:205], v[12:15]
	v_mfma_f32_16x16x32_bf16 v[8:11], v[238:241], v[202:205], v[8:11]
	v_mfma_f32_16x16x32_bf16 v[4:7], v[230:233], v[210:213], v[4:7]
	s_setprio 0
	v_mfma_f32_16x16x32_bf16 v[0:3], v[238:241], v[210:213], v[0:3]
	s_barrier
	ds_read_b128 v[128:131], v226 offset:32768
	ds_read_b128 v[132:135], v226 offset:33792
	ds_read_b128 v[136:139], v226 offset:34816
	ds_read_b128 v[140:143], v226 offset:35840
	ds_read_b128 v[144:147], v228 offset:32768
	ds_read_b128 v[148:151], v228 offset:33792
	ds_read_b128 v[152:155], v228 offset:34816
	ds_read_b128 v[194:197], v228 offset:35840
	ds_read_b128 v[198:201], v228 offset:36864
	ds_read_b128 v[202:205], v228 offset:37888
	ds_read_b128 v[206:209], v228 offset:38912
	ds_read_b128 v[210:213], v228 offset:39936
	s_add_u32 s20, s26, 0x90000
	s_addc_u32 s21, s27, 0
	s_mov_b32 m0, s36
	s_nop 0
	global_load_lds_dwordx4 v188, s[20:21]
	s_mov_b32 m0, s37
	s_nop 0
	global_load_lds_dwordx4 v186, s[20:21]
	s_waitcnt lgkmcnt(0)
	s_setprio 1
	s_barrier
	v_mfma_f32_16x16x32_bf16 v[124:127], v[128:131], v[144:147], v[124:127]
	v_mfma_f32_16x16x32_bf16 v[120:123], v[136:139], v[144:147], v[120:123]
	v_mfma_f32_16x16x32_bf16 v[116:119], v[128:131], v[152:155], v[116:119]
	v_mfma_f32_16x16x32_bf16 v[112:115], v[136:139], v[152:155], v[112:115]
	v_mfma_f32_16x16x32_bf16 v[108:111], v[128:131], v[198:201], v[108:111]
	v_mfma_f32_16x16x32_bf16 v[104:107], v[136:139], v[198:201], v[104:107]
	v_mfma_f32_16x16x32_bf16 v[100:103], v[128:131], v[206:209], v[100:103]
	v_mfma_f32_16x16x32_bf16 v[96:99], v[136:139], v[206:209], v[96:99]
	v_mfma_f32_16x16x32_bf16 v[124:127], v[132:135], v[148:151], v[124:127]
	v_mfma_f32_16x16x32_bf16 v[120:123], v[140:143], v[148:151], v[120:123]
	v_mfma_f32_16x16x32_bf16 v[116:119], v[132:135], v[194:197], v[116:119]
	v_mfma_f32_16x16x32_bf16 v[112:115], v[140:143], v[194:197], v[112:115]
	v_mfma_f32_16x16x32_bf16 v[108:111], v[132:135], v[202:205], v[108:111]
	v_mfma_f32_16x16x32_bf16 v[104:107], v[140:143], v[202:205], v[104:107]
	v_mfma_f32_16x16x32_bf16 v[100:103], v[132:135], v[210:213], v[100:103]
	s_setprio 0
	v_mfma_f32_16x16x32_bf16 v[96:99], v[140:143], v[210:213], v[96:99]
	s_barrier
	ds_read_b128 v[214:217], v226 offset:49152
	ds_read_b128 v[230:233], v226 offset:50176
	ds_read_b128 v[234:237], v226 offset:51200
	ds_read_b128 v[238:241], v226 offset:52224
	s_add_i32 s26, 0, 0x1c000
	s_add_i32 s20, s43, s31
	s_add_i32 m0, s20, 0xffffff80
	s_nop 0
	global_load_lds_dwordx4 v188, s[24:25] offset:128
	s_add_i32 m0, s20, 0x1f80
	s_nop 0
	global_load_lds_dwordx4 v186, s[24:25] offset:128
	s_waitcnt lgkmcnt(0)
	s_setprio 1
	s_barrier
	v_mfma_f32_16x16x32_bf16 v[60:63], v[214:217], v[144:147], v[60:63]
	v_mfma_f32_16x16x32_bf16 v[56:59], v[234:237], v[144:147], v[56:59]
	v_mfma_f32_16x16x32_bf16 v[52:55], v[214:217], v[152:155], v[52:55]
	v_mfma_f32_16x16x32_bf16 v[48:51], v[234:237], v[152:155], v[48:51]
	v_mfma_f32_16x16x32_bf16 v[44:47], v[214:217], v[198:201], v[44:47]
	v_mfma_f32_16x16x32_bf16 v[40:43], v[234:237], v[198:201], v[40:43]
	v_mfma_f32_16x16x32_bf16 v[36:39], v[214:217], v[206:209], v[36:39]
	v_mfma_f32_16x16x32_bf16 v[32:35], v[234:237], v[206:209], v[32:35]
	v_mfma_f32_16x16x32_bf16 v[60:63], v[230:233], v[148:151], v[60:63]
	s_add_i32 m0, s38, 0xffffff80
	v_mfma_f32_16x16x32_bf16 v[56:59], v[238:241], v[148:151], v[56:59]
	v_mfma_f32_16x16x32_bf16 v[52:55], v[230:233], v[194:197], v[52:55]
	v_mfma_f32_16x16x32_bf16 v[48:51], v[238:241], v[194:197], v[48:51]
	v_mfma_f32_16x16x32_bf16 v[44:47], v[230:233], v[202:205], v[44:47]
	v_mfma_f32_16x16x32_bf16 v[40:43], v[238:241], v[202:205], v[40:43]
	v_mfma_f32_16x16x32_bf16 v[36:39], v[230:233], v[210:213], v[36:39]
	s_setprio 0
	v_mfma_f32_16x16x32_bf16 v[32:35], v[238:241], v[210:213], v[32:35]
	s_barrier
	ds_read_b128 v[144:147], v228 offset:49152
	ds_read_b128 v[148:151], v228 offset:50176
	ds_read_b128 v[152:155], v228 offset:51200
	ds_read_b128 v[194:197], v228 offset:52224
	ds_read_b128 v[198:201], v228 offset:53248
	ds_read_b128 v[202:205], v228 offset:54272
	ds_read_b128 v[206:209], v228 offset:55296
	ds_read_b128 v[210:213], v228 offset:56320
	global_load_lds_dwordx4 v188, s[100:101] offset:128
	s_add_i32 m0, s39, 0xffffff80
	s_nop 0
	global_load_lds_dwordx4 v186, s[100:101] offset:128
	s_waitcnt lgkmcnt(0)
	s_setprio 1
	s_barrier
; #define PG8_WAIT_V(n) asm volatile("s_waitcnt vmcnt(" #n ")" ::: "memory")
; #define PG8_WAIT_L(n) asm volatile("s_waitcnt lgkmcnt(" #n ")" ::: "memory")
; #define PG8_BAR __builtin_amdgcn_s_barrier()
; template <class Epi>
; DI void gemm_phase(LAS unsigned char* lds, const Gemm g, const StaticOrder& S, const Epi& E) {
;     ...
;             PG8_BAR; PG8_WAIT_L(0); PG8_MMA(1, 0, At, B0); PG8_BAR; PG8_SCHED;
;             PG8_STAGE(PG8_SB(1, 1), b3 + hstep);
;             PG8_WAIT_V(6); PG8_BAR; PG8_MMA(1, 1, At, B1); PG8_BAR;
;     template <bool LN, int BJ, int LO, int HI> DI void batch(const f32x4 (&acc)[2][2][4][2], unsigned row0, unsigned col0, const f32x4 (&gv)[2], const f32x4 (&bv)[2]) const {
;         f32x4 r[HI - LO]; float mean[(HI - LO) / 2], rstd[(HI - LO) / 2];
; #pragma unroll
;         for (int i = LO; i < HI; ++i) { const int ai = i >> 3, m = (i >> 1) & 3, n = i & 1; const unsigned row = row0 + ai * HALF + m * 16;
;             if (n == 0) { mean[(i - LO) >> 1] = 0.f; rstd[(i - LO) >> 1] = 1.f;
;                 if (LN) { const float2 st = *(const float2*)(stats + row * 2u); mean[(i - LO) >> 1] = st.x; rstd[(i - LO) >> 1] = st.y; } }
;             r[i - LO] = *(const f32x4*)(src + (row * (unsigned)DM + col0 + BJ * HALF + n * 16)); }
; #pragma unroll
;         for (int i = LO; i < HI; ++i) { const int ai = i >> 3, m = (i >> 1) & 3, n = i & 1; const unsigned row = row0 + ai * HALF + m * 16;
;             *(f32x4*)(Y + (row * (unsigned)DM + col0 + BJ * HALF + n * 16)) = acc[ai][BJ][m][n] + ((r[i - LO] - mean[(i - LO) >> 1]) * rstd[(i - LO) >> 1]) * gv[n] + bv[n]; }
;         __builtin_amdgcn_sched_barrier(0);
;     }
;     template <bool LN, int BJ> DI void load_gb(unsigned col0, f32x4 (&gv)[2], f32x4 (&bv)[2]) const {
; #pragma unroll
;         for (int n = 0; n < 2; ++n) {
;             if (LN) { gv[n] = *(const f32x4*)(gam + col0 + BJ * HALF + n * 16) * ALPHA; bv[n] = *(const f32x4*)(bet + col0 + BJ * HALF + n * 16) * ALPHA; }
;             else { gv[n] = (f32x4){ALPHA, ALPHA, ALPHA, ALPHA}; bv[n] = (f32x4){0.f, 0.f, 0.f, 0.f}; }
;         }
;     }
;     template <bool LN> DI void run(const f32x4 (&acc)[2][2][4][2], const Unit& u, int wr, int wc, int fr, int fq) const {
;         const unsigned row0 = u.pm * BM + wr * 64 + fr, col0 = u.pn * BM + wc * 32 + 4 * fq;
;         f32x4 gv[2], bv[2];
;         load_gb<LN, 0>(col0, gv, bv);
	v_mfma_f32_16x16x32_bf16 v[92:95], v[128:131], v[144:147], v[92:95]
	v_mfma_f32_16x16x32_bf16 v[88:91], v[136:139], v[144:147], v[88:91]
	v_mfma_f32_16x16x32_bf16 v[84:87], v[128:131], v[152:155], v[84:87]
	v_mfma_f32_16x16x32_bf16 v[80:83], v[136:139], v[152:155], v[80:83]
	v_mfma_f32_16x16x32_bf16 v[76:79], v[128:131], v[198:201], v[76:79]
	v_mfma_f32_16x16x32_bf16 v[72:75], v[136:139], v[198:201], v[72:75]
	v_mfma_f32_16x16x32_bf16 v[68:71], v[128:131], v[206:209], v[68:71]
	v_mfma_f32_16x16x32_bf16 v[64:67], v[136:139], v[206:209], v[64:67]
	v_mfma_f32_16x16x32_bf16 v[92:95], v[132:135], v[148:151], v[92:95]
	v_mfma_f32_16x16x32_bf16 v[88:91], v[140:143], v[148:151], v[88:91]
	v_mfma_f32_16x16x32_bf16 v[84:87], v[132:135], v[194:197], v[84:87]
	v_mfma_f32_16x16x32_bf16 v[80:83], v[140:143], v[194:197], v[80:83]
	v_mfma_f32_16x16x32_bf16 v[76:79], v[132:135], v[202:205], v[76:79]
	v_mfma_f32_16x16x32_bf16 v[72:75], v[140:143], v[202:205], v[72:75]
	v_mfma_f32_16x16x32_bf16 v[68:71], v[132:135], v[210:213], v[68:71]
	s_setprio 0
	v_mfma_f32_16x16x32_bf16 v[64:67], v[140:143], v[210:213], v[64:67]
	s_barrier
	s_add_u32 s20, s24, 0x90080
	s_addc_u32 s21, s25, 0
	s_add_i32 s24, s26, s31
	s_mov_b32 m0, s24
	s_nop 0
	global_load_lds_dwordx4 v188, s[20:21]
	s_add_i32 m0, s24, 0x2000
	s_nop 0
	global_load_lds_dwordx4 v186, s[20:21]
	s_waitcnt vmcnt(6)
	s_setprio 1
	s_barrier
	v_mfma_f32_16x16x32_bf16 v[28:31], v[214:217], v[144:147], v[28:31]
	v_mfma_f32_16x16x32_bf16 v[24:27], v[234:237], v[144:147], v[24:27]
	v_mfma_f32_16x16x32_bf16 v[20:23], v[214:217], v[152:155], v[20:23]
	v_mfma_f32_16x16x32_bf16 v[16:19], v[234:237], v[152:155], v[16:19]
	v_mfma_f32_16x16x32_bf16 v[12:15], v[214:217], v[198:201], v[12:15]
	v_mfma_f32_16x16x32_bf16 v[8:11], v[234:237], v[198:201], v[8:11]
	v_mfma_f32_16x16x32_bf16 v[4:7], v[214:217], v[206:209], v[4:7]
	v_mfma_f32_16x16x32_bf16 v[0:3], v[234:237], v[206:209], v[0:3]
	v_mfma_f32_16x16x32_bf16 v[28:31], v[230:233], v[148:151], v[28:31]
	s_add_i32 s33, s33, 2
	v_mfma_f32_16x16x32_bf16 v[24:27], v[238:241], v[148:151], v[24:27]
	s_add_u32 s4, s4, 0x100
	v_mfma_f32_16x16x32_bf16 v[20:23], v[230:233], v[194:197], v[20:23]
	s_addc_u32 s5, s5, 0
	v_mfma_f32_16x16x32_bf16 v[16:19], v[238:241], v[194:197], v[16:19]
	s_cmp_gt_u32 s33, 33
	v_mfma_f32_16x16x32_bf16 v[12:15], v[230:233], v[202:205], v[12:15]
	s_mov_b64 s[20:21], s[22:23]
	v_mfma_f32_16x16x32_bf16 v[8:11], v[238:241], v[202:205], v[8:11]
	v_mfma_f32_16x16x32_bf16 v[4:7], v[230:233], v[210:213], v[4:7]
	s_setprio 0
	v_mfma_f32_16x16x32_bf16 v[0:3], v[238:241], v[210:213], v[0:3]
	s_barrier
	s_cbranch_scc0 .LBB0_77
	v_lshl_add_u32 v206, s3, 8, v225
	v_lshl_or_b32 v158, s2, 8, v227
	v_lshlrev_b32_e32 v232, 11, v206
	s_andn2_b64 vcc, exec, s[14:15]
	v_or_b32_e32 v231, 16, v158
	v_add_u32_e32 v194, v232, v158
	v_or_b32_e32 v230, 0x80, v158
	v_or_b32_e32 v229, 0x90, v158
	s_cbranch_vccnz .LBB0_80
	v_lshlrev_b64 v[132:133], 2, v[158:159]
	v_lshl_add_u64 v[140:141], s[16:17], 0, v[132:133]
	global_load_dwordx4 v[128:131], v[140:141], off
	v_lshl_add_u64 v[142:143], s[18:19], 0, v[132:133]
	v_readlane_b32 s2, v253, 8
	v_mov_b32_e32 v195, v159
	v_lshlrev_b32_e32 v136, 1, v206
	v_mov_b32_e32 v137, v159
	v_readlane_b32 s3, v253, 9
	v_lshlrev_b64 v[212:213], 2, v[194:195]
	v_add_u32_e32 v146, v232, v231
	v_lshl_add_u64 v[144:145], v[136:137], 2, s[2:3]
	v_lshl_add_u64 v[136:137], s[88:89], 0, v[212:213]
	v_mov_b32_e32 v147, v159
	v_lshl_add_u64 v[146:147], v[146:147], 2, s[88:89]
	v_or_b32_e32 v195, 16, v206
	v_mov_b32_e32 v201, v159
	v_mov_b32_e32 v209, v159
	v_lshl_add_u64 v[212:213], s[90:91], 0, v[212:213]
	s_waitcnt vmcnt(0)
	v_pk_mul_f32 v[152:153], v[130:131], s[78:79] op_sel_hi:[1,0]
	v_pk_mul_f32 v[154:155], v[128:129], s[78:79] op_sel_hi:[1,0]
	global_load_dwordx4 v[132:135], v[142:143], off
	global_load_dwordx4 v[128:131], v[140:141], off offset:64
	global_load_dwordx2 v[204:205], v[144:145], off
	global_load_dwordx4 v[196:199], v[146:147], off
	v_lshlrev_b32_e32 v146, 1, v195
	global_load_dwordx4 v[136:139], v[136:137], off
	v_lshlrev_b32_e32 v195, 11, v195
	v_mov_b32_e32 v147, v159
	v_add_u32_e32 v200, v195, v158
	v_lshl_add_u64 v[146:147], v[146:147], 2, s[2:3]
	v_lshl_add_u64 v[200:201], v[200:201], 2, s[88:89]
	global_load_dwordx2 v[214:215], v[146:147], off
	v_add_u32_e32 v208, v195, v231
	global_load_dwordx4 v[200:203], v[200:201], off
	v_lshl_add_u64 v[208:209], v[208:209], 2, s[88:89]
	global_load_dwordx4 v[208:211], v[208:209], off
	s_waitcnt vmcnt(0)
	v_pk_mul_f32 v[148:149], v[130:131], s[78:79] op_sel_hi:[1,0]
	v_pk_mul_f32 v[150:151], v[128:129], s[78:79] op_sel_hi:[1,0]
	global_load_dwordx4 v[128:131], v[142:143], off offset:64
	v_sub_f32_e32 v137, v137, v204
	v_sub_f32_e32 v136, v136, v204
	v_sub_f32_e32 v139, v139, v204
	v_sub_f32_e32 v138, v138, v204
	v_pk_mul_f32 v[138:139], v[204:205], v[138:139] op_sel:[1,0]
	v_pk_mul_f32 v[136:137], v[204:205], v[136:137] op_sel:[1,0]
	v_pk_fma_f32 v[138:139], v[152:153], v[138:139], v[126:127]
	v_pk_fma_f32 v[136:137], v[154:155], v[136:137], v[124:125]
	v_pk_fma_f32 v[138:139], v[134:135], s[78:79], v[138:139] op_sel_hi:[1,0,1]
	v_pk_fma_f32 v[136:137], v[132:133], s[78:79], v[136:137] op_sel_hi:[1,0,1]
	global_store_dwordx4 v[212:213], v[136:139], off
	s_nop 1
	v_sub_f32_e32 v137, v197, v204
	v_sub_f32_e32 v136, v196, v204
	v_sub_f32_e32 v139, v199, v204
	v_sub_f32_e32 v138, v198, v204
	v_pk_mul_f32 v[138:139], v[204:205], v[138:139] op_sel:[1,0]
	v_pk_mul_f32 v[136:137], v[204:205], v[136:137] op_sel:[1,0]
	v_pk_fma_f32 v[138:139], v[148:149], v[138:139], v[122:123]
	v_pk_fma_f32 v[136:137], v[150:151], v[136:137], v[120:121]
	v_or_b32_e32 v196, 16, v194
	v_mov_b32_e32 v197, v159
	v_lshl_add_u64 v[196:197], v[196:197], 2, s[90:91]
	s_waitcnt vmcnt(0)
;     template <bool LN, int BJ, int LO, int HI> DI void batch(const f32x4 (&acc)[2][2][4][2], unsigned row0, unsigned col0, const f32x4 (&gv)[2], const f32x4 (&bv)[2]) const {
;         f32x4 r[HI - LO]; float mean[(HI - LO) / 2], rstd[(HI - LO) / 2];
; #pragma unroll
;         for (int i = LO; i < HI; ++i) { const int ai = i >> 3, m = (i >> 1) & 3, n = i & 1; const unsigned row = row0 + ai * HALF + m * 16;
;             if (n == 0) { mean[(i - LO) >> 1] = 0.f; rstd[(i - LO) >> 1] = 1.f;
;                 if (LN) { const float2 st = *(const float2*)(stats + row * 2u); mean[(i - LO) >> 1] = st.x; rstd[(i - LO) >> 1] = st.y; } }
;             r[i - LO] = *(const f32x4*)(src + (row * (unsigned)DM + col0 + BJ * HALF + n * 16)); }
; #pragma unroll
;         for (int i = LO; i < HI; ++i) { const int ai = i >> 3, m = (i >> 1) & 3, n = i & 1; const unsigned row = row0 + ai * HALF + m * 16;
;             *(f32x4*)(Y + (row * (unsigned)DM + col0 + BJ * HALF + n * 16)) = acc[ai][BJ][m][n] + ((r[i - LO] - mean[(i - LO) >> 1]) * rstd[(i - LO) >> 1]) * gv[n] + bv[n]; }
;         __builtin_amdgcn_sched_barrier(0);
;     }
	v_pk_fma_f32 v[138:139], v[130:131], s[78:79], v[138:139] op_sel_hi:[1,0,1]
	v_pk_fma_f32 v[136:137], v[128:129], s[78:79], v[136:137] op_sel_hi:[1,0,1]
	global_store_dwordx4 v[196:197], v[136:139], off
	v_add_u32_e32 v196, 0x8000, v194
	v_mov_b32_e32 v197, v159
	v_sub_f32_e32 v137, v201, v214
	v_sub_f32_e32 v136, v200, v214
	v_sub_f32_e32 v139, v203, v214
	v_sub_f32_e32 v138, v202, v214
	v_pk_mul_f32 v[138:139], v[214:215], v[138:139] op_sel:[1,0]
	v_pk_mul_f32 v[136:137], v[214:215], v[136:137] op_sel:[1,0]
	v_pk_fma_f32 v[138:139], v[152:153], v[138:139], v[118:119]
	v_pk_fma_f32 v[136:137], v[154:155], v[136:137], v[116:117]
	v_pk_fma_f32 v[138:139], v[134:135], s[78:79], v[138:139] op_sel_hi:[1,0,1]
	v_pk_fma_f32 v[136:137], v[132:133], s[78:79], v[136:137] op_sel_hi:[1,0,1]
	v_lshl_add_u64 v[196:197], v[196:197], 2, s[90:91]
	global_store_dwordx4 v[196:197], v[136:139], off
	v_add_u32_e32 v196, 0x8010, v194
	v_mov_b32_e32 v197, v159
	v_sub_f32_e32 v137, v209, v214
	v_sub_f32_e32 v136, v208, v214
	v_sub_f32_e32 v139, v211, v214
	v_sub_f32_e32 v138, v210, v214
	v_pk_mul_f32 v[138:139], v[214:215], v[138:139] op_sel:[1,0]
	v_pk_mul_f32 v[136:137], v[214:215], v[136:137] op_sel:[1,0]
	v_pk_fma_f32 v[138:139], v[148:149], v[138:139], v[114:115]
	v_pk_fma_f32 v[136:137], v[150:151], v[136:137], v[112:113]
	v_pk_fma_f32 v[138:139], v[130:131], s[78:79], v[138:139] op_sel_hi:[1,0,1]
	v_pk_fma_f32 v[136:137], v[128:129], s[78:79], v[136:137] op_sel_hi:[1,0,1]
	v_lshl_add_u64 v[196:197], v[196:197], 2, s[90:91]
	global_store_dwordx4 v[196:197], v[136:139], off
	s_nop 1
	v_or_b32_e32 v138, 32, v206
	v_lshlrev_b32_e32 v136, 1, v138
	v_mov_b32_e32 v137, v159
	v_lshlrev_b32_e32 v236, 11, v138
	v_lshl_add_u64 v[200:201], v[136:137], 2, s[2:3]
	v_add_u32_e32 v136, v236, v158
	v_lshl_add_u64 v[136:137], v[136:137], 2, s[88:89]
	global_load_dwordx2 v[204:205], v[200:201], off
	v_add_u32_e32 v196, v236, v231
	global_load_dwordx4 v[136:139], v[136:137], off
	v_mov_b32_e32 v197, v159
	v_lshl_add_u64 v[196:197], v[196:197], 2, s[88:89]
	global_load_dwordx4 v[196:199], v[196:197], off
	v_or_b32_e32 v207, 48, v206
	v_lshlrev_b32_e32 v235, 11, v207
	v_lshlrev_b32_e32 v202, 1, v207
	v_mov_b32_e32 v203, v159
	v_add_u32_e32 v208, v235, v158
	v_mov_b32_e32 v209, v159
	v_lshl_add_u64 v[202:203], v[202:203], 2, s[2:3]
	v_lshl_add_u64 v[208:209], v[208:209], 2, s[88:89]
	global_load_dwordx2 v[216:217], v[202:203], off
	v_add_u32_e32 v212, v235, v231
	global_load_dwordx4 v[208:211], v[208:209], off
	v_mov_b32_e32 v213, v159
	v_lshl_add_u64 v[212:213], v[212:213], 2, s[88:89]
	global_load_dwordx4 v[212:215], v[212:213], off
	v_add_u32_e32 v218, 0x10000, v194
	v_mov_b32_e32 v219, v159
	v_lshl_add_u64 v[218:219], v[218:219], 2, s[90:91]
	s_waitcnt vmcnt(0)
	v_sub_f32_e32 v137, v137, v204
	v_sub_f32_e32 v136, v136, v204
	v_sub_f32_e32 v139, v139, v204
	v_sub_f32_e32 v138, v138, v204
	v_pk_mul_f32 v[138:139], v[204:205], v[138:139] op_sel:[1,0]
	v_pk_mul_f32 v[136:137], v[204:205], v[136:137] op_sel:[1,0]
	v_pk_fma_f32 v[138:139], v[152:153], v[138:139], v[110:111]
	v_pk_fma_f32 v[136:137], v[154:155], v[136:137], v[108:109]
	v_pk_fma_f32 v[138:139], v[134:135], s[78:79], v[138:139] op_sel_hi:[1,0,1]
	v_pk_fma_f32 v[136:137], v[132:133], s[78:79], v[136:137] op_sel_hi:[1,0,1]
	global_store_dwordx4 v[218:219], v[136:139], off
	s_nop 1
	v_sub_f32_e32 v137, v197, v204
	v_sub_f32_e32 v136, v196, v204
	v_sub_f32_e32 v139, v199, v204
	v_sub_f32_e32 v138, v198, v204
	v_pk_mul_f32 v[138:139], v[204:205], v[138:139] op_sel:[1,0]
	v_pk_mul_f32 v[136:137], v[204:205], v[136:137] op_sel:[1,0]
	v_pk_fma_f32 v[138:139], v[148:149], v[138:139], v[106:107]
	v_pk_fma_f32 v[136:137], v[150:151], v[136:137], v[104:105]
	v_add_u32_e32 v196, 0x10010, v194
	v_mov_b32_e32 v197, v159
	v_pk_fma_f32 v[138:139], v[130:131], s[78:79], v[138:139] op_sel_hi:[1,0,1]
	v_pk_fma_f32 v[136:137], v[128:129], s[78:79], v[136:137] op_sel_hi:[1,0,1]
	v_lshl_add_u64 v[196:197], v[196:197], 2, s[90:91]
	global_store_dwordx4 v[196:197], v[136:139], off
	v_add_u32_e32 v196, 0x18000, v194
	v_mov_b32_e32 v197, v159
	v_sub_f32_e32 v137, v209, v216
	v_sub_f32_e32 v136, v208, v216
	v_sub_f32_e32 v139, v211, v216
	v_sub_f32_e32 v138, v210, v216
	v_pk_mul_f32 v[138:139], v[216:217], v[138:139] op_sel:[1,0]
	v_pk_mul_f32 v[136:137], v[216:217], v[136:137] op_sel:[1,0]
	v_pk_fma_f32 v[138:139], v[152:153], v[138:139], v[102:103]
	v_pk_fma_f32 v[136:137], v[154:155], v[136:137], v[100:101]
	v_pk_fma_f32 v[138:139], v[134:135], s[78:79], v[138:139] op_sel_hi:[1,0,1]
	v_pk_fma_f32 v[136:137], v[132:133], s[78:79], v[136:137] op_sel_hi:[1,0,1]
	v_lshl_add_u64 v[196:197], v[196:197], 2, s[90:91]
	global_store_dwordx4 v[196:197], v[136:139], off
	v_add_u32_e32 v196, 0x18010, v194
	v_mov_b32_e32 v197, v159
	v_sub_f32_e32 v137, v213, v216
	v_sub_f32_e32 v136, v212, v216
	v_sub_f32_e32 v139, v215, v216
	v_sub_f32_e32 v138, v214, v216
	v_pk_mul_f32 v[138:139], v[216:217], v[138:139] op_sel:[1,0]
	v_pk_mul_f32 v[136:137], v[216:217], v[136:137] op_sel:[1,0]
	v_pk_fma_f32 v[138:139], v[148:149], v[138:139], v[98:99]
	v_pk_fma_f32 v[136:137], v[150:151], v[136:137], v[96:97]
	v_pk_fma_f32 v[138:139], v[130:131], s[78:79], v[138:139] op_sel_hi:[1,0,1]
	v_pk_fma_f32 v[136:137], v[128:129], s[78:79], v[136:137] op_sel_hi:[1,0,1]
	v_lshl_add_u64 v[196:197], v[196:197], 2, s[90:91]
	global_store_dwordx4 v[196:197], v[136:139], off
	s_nop 1
	v_add_u32_e32 v138, 0x80, v206
	v_lshlrev_b32_e32 v136, 1, v138
	v_mov_b32_e32 v137, v159
	v_lshlrev_b32_e32 v233, 11, v138
	v_lshl_add_u64 v[196:197], v[136:137], 2, s[2:3]
	v_add_u32_e32 v136, v233, v158
	v_lshl_add_u64 v[136:137], v[136:137], 2, s[88:89]
	global_load_dwordx2 v[204:205], v[196:197], off
	v_add_u32_e32 v198, v233, v231
	global_load_dwordx4 v[136:139], v[136:137], off
	v_mov_b32_e32 v199, v159
	v_add_u32_e32 v207, 0x90, v206
	v_lshl_add_u64 v[198:199], v[198:199], 2, s[88:89]
	v_lshlrev_b32_e32 v234, 11, v207
	global_load_dwordx4 v[208:211], v[198:199], off
	v_add_u32_e32 v212, v234, v158
	v_mov_b32_e32 v213, v159
	v_lshl_add_u64 v[212:213], v[212:213], 2, s[88:89]
	global_load_dwordx4 v[212:215], v[212:213], off
	v_lshlrev_b32_e32 v198, 1, v207
	v_mov_b32_e32 v199, v159
	v_lshl_add_u64 v[198:199], v[198:199], 2, s[2:3]
	global_load_dwordx2 v[220:221], v[198:199], off
	v_add_u32_e32 v216, v234, v231
	v_mov_b32_e32 v217, v159
	v_lshl_add_u64 v[216:217], v[216:217], 2, s[88:89]
	global_load_dwordx4 v[216:219], v[216:217], off
	v_add_u32_e32 v238, 0x40000, v194
	v_mov_b32_e32 v239, v159
	v_lshl_add_u64 v[238:239], v[238:239], 2, s[90:91]
	s_waitcnt vmcnt(0)
;     template <bool LN, int BJ, int LO, int HI> DI void batch(const f32x4 (&acc)[2][2][4][2], unsigned row0, unsigned col0, const f32x4 (&gv)[2], const f32x4 (&bv)[2]) const {
;         f32x4 r[HI - LO]; float mean[(HI - LO) / 2], rstd[(HI - LO) / 2];
; #pragma unroll
;         for (int i = LO; i < HI; ++i) { const int ai = i >> 3, m = (i >> 1) & 3, n = i & 1; const unsigned row = row0 + ai * HALF + m * 16;
;             if (n == 0) { mean[(i - LO) >> 1] = 0.f; rstd[(i - LO) >> 1] = 1.f;
;                 if (LN) { const float2 st = *(const float2*)(stats + row * 2u); mean[(i - LO) >> 1] = st.x; rstd[(i - LO) >> 1] = st.y; } }
;             r[i - LO] = *(const f32x4*)(src + (row * (unsigned)DM + col0 + BJ * HALF + n * 16)); }
; #pragma unroll
;         for (int i = LO; i < HI; ++i) { const int ai = i >> 3, m = (i >> 1) & 3, n = i & 1; const unsigned row = row0 + ai * HALF + m * 16;
;             *(f32x4*)(Y + (row * (unsigned)DM + col0 + BJ * HALF + n * 16)) = acc[ai][BJ][m][n] + ((r[i - LO] - mean[(i - LO) >> 1]) * rstd[(i - LO) >> 1]) * gv[n] + bv[n]; }
;         __builtin_amdgcn_sched_barrier(0);
;     }
;     template <bool LN, int BJ> DI void load_gb(unsigned col0, f32x4 (&gv)[2], f32x4 (&bv)[2]) const {
; #pragma unroll
;         for (int n = 0; n < 2; ++n) {
;             if (LN) { gv[n] = *(const f32x4*)(gam + col0 + BJ * HALF + n * 16) * ALPHA; bv[n] = *(const f32x4*)(bet + col0 + BJ * HALF + n * 16) * ALPHA; }
;             else { gv[n] = (f32x4){ALPHA, ALPHA, ALPHA, ALPHA}; bv[n] = (f32x4){0.f, 0.f, 0.f, 0.f}; }
;         }
;     }
;     template <bool LN> DI void run(const f32x4 (&acc)[2][2][4][2], const Unit& u, int wr, int wc, int fr, int fq) const {
;         const unsigned row0 = u.pm * BM + wr * 64 + fr, col0 = u.pn * BM + wc * 32 + 4 * fq;
;         f32x4 gv[2], bv[2];
;         load_gb<LN, 0>(col0, gv, bv);
;         batch<LN, 0, 0, 4>(acc, row0, col0, gv, bv);
;         batch<LN, 0, 4, 8>(acc, row0, col0, gv, bv);
;         batch<LN, 0, 8, 12>(acc, row0, col0, gv, bv);
;         batch<LN, 0, 12, 16>(acc, row0, col0, gv, bv);
;         load_gb<LN, 1>(col0, gv, bv);
	v_sub_f32_e32 v137, v137, v204
	v_sub_f32_e32 v136, v136, v204
	v_sub_f32_e32 v139, v139, v204
	v_sub_f32_e32 v138, v138, v204
	v_pk_mul_f32 v[138:139], v[204:205], v[138:139] op_sel:[1,0]
	v_pk_mul_f32 v[136:137], v[204:205], v[136:137] op_sel:[1,0]
	v_pk_fma_f32 v[138:139], v[152:153], v[138:139], v[94:95]
	v_pk_fma_f32 v[136:137], v[154:155], v[136:137], v[92:93]
	v_pk_fma_f32 v[138:139], v[134:135], s[78:79], v[138:139] op_sel_hi:[1,0,1]
	v_pk_fma_f32 v[136:137], v[132:133], s[78:79], v[136:137] op_sel_hi:[1,0,1]
	global_store_dwordx4 v[238:239], v[136:139], off
	s_nop 1
	v_sub_f32_e32 v137, v209, v204
	v_sub_f32_e32 v136, v208, v204
	v_sub_f32_e32 v139, v211, v204
	v_sub_f32_e32 v138, v210, v204
	v_pk_mul_f32 v[138:139], v[204:205], v[138:139] op_sel:[1,0]
	v_pk_mul_f32 v[136:137], v[204:205], v[136:137] op_sel:[1,0]
	v_pk_fma_f32 v[138:139], v[148:149], v[138:139], v[90:91]
	v_pk_fma_f32 v[136:137], v[150:151], v[136:137], v[88:89]
	v_add_u32_e32 v204, 0x40010, v194
	v_mov_b32_e32 v205, v159
	v_pk_fma_f32 v[138:139], v[130:131], s[78:79], v[138:139] op_sel_hi:[1,0,1]
	v_pk_fma_f32 v[136:137], v[128:129], s[78:79], v[136:137] op_sel_hi:[1,0,1]
	v_lshl_add_u64 v[204:205], v[204:205], 2, s[90:91]
	global_store_dwordx4 v[204:205], v[136:139], off
	v_add_u32_e32 v204, 0x48000, v194
	v_mov_b32_e32 v205, v159
	v_sub_f32_e32 v137, v213, v220
	v_sub_f32_e32 v136, v212, v220
	v_sub_f32_e32 v139, v215, v220
	v_sub_f32_e32 v138, v214, v220
	v_pk_mul_f32 v[138:139], v[220:221], v[138:139] op_sel:[1,0]
	v_pk_mul_f32 v[136:137], v[220:221], v[136:137] op_sel:[1,0]
	v_pk_fma_f32 v[138:139], v[152:153], v[138:139], v[86:87]
	v_pk_fma_f32 v[136:137], v[154:155], v[136:137], v[84:85]
	v_pk_fma_f32 v[138:139], v[134:135], s[78:79], v[138:139] op_sel_hi:[1,0,1]
	v_pk_fma_f32 v[136:137], v[132:133], s[78:79], v[136:137] op_sel_hi:[1,0,1]
	v_lshl_add_u64 v[204:205], v[204:205], 2, s[90:91]
	global_store_dwordx4 v[204:205], v[136:139], off
	v_add_u32_e32 v204, 0x48010, v194
	v_mov_b32_e32 v205, v159
	v_sub_f32_e32 v137, v217, v220
	v_sub_f32_e32 v136, v216, v220
	v_sub_f32_e32 v139, v219, v220
	v_sub_f32_e32 v138, v218, v220
	v_pk_mul_f32 v[138:139], v[220:221], v[138:139] op_sel:[1,0]
	v_pk_mul_f32 v[136:137], v[220:221], v[136:137] op_sel:[1,0]
	v_pk_fma_f32 v[138:139], v[148:149], v[138:139], v[82:83]
	v_pk_fma_f32 v[136:137], v[150:151], v[136:137], v[80:81]
	v_pk_fma_f32 v[138:139], v[130:131], s[78:79], v[138:139] op_sel_hi:[1,0,1]
	v_pk_fma_f32 v[136:137], v[128:129], s[78:79], v[136:137] op_sel_hi:[1,0,1]
	v_lshl_add_u64 v[204:205], v[204:205], 2, s[90:91]
	global_store_dwordx4 v[204:205], v[136:139], off
	s_nop 1
	v_add_u32_e32 v138, 0xa0, v206
	v_lshlrev_b32_e32 v136, 1, v138
	v_mov_b32_e32 v137, v159
	v_lshlrev_b32_e32 v237, 11, v138
	v_lshl_add_u64 v[204:205], v[136:137], 2, s[2:3]
	v_add_u32_e32 v136, v237, v158
	v_lshl_add_u64 v[136:137], v[136:137], 2, s[88:89]
	global_load_dwordx2 v[220:221], v[204:205], off
	v_add_u32_e32 v208, v237, v231
	global_load_dwordx4 v[136:139], v[136:137], off
	v_mov_b32_e32 v209, v159
	v_lshl_add_u64 v[208:209], v[208:209], 2, s[88:89]
	global_load_dwordx4 v[212:215], v[208:209], off
	v_add_u32_e32 v208, 0xb0, v206
	v_lshlrev_b32_e32 v206, 1, v208
	v_mov_b32_e32 v207, v159
	v_lshlrev_b32_e32 v238, 11, v208
	v_lshl_add_u64 v[210:211], v[206:207], 2, s[2:3]
	v_add_u32_e32 v206, v238, v158
	v_lshl_add_u64 v[206:207], v[206:207], 2, s[88:89]
	global_load_dwordx2 v[240:241], v[210:211], off
	v_add_u32_e32 v216, v238, v231
	global_load_dwordx4 v[206:209], v[206:207], off
	v_mov_b32_e32 v217, v159
	v_lshl_add_u64 v[216:217], v[216:217], 2, s[88:89]
	global_load_dwordx4 v[216:219], v[216:217], off
	v_add_u32_e32 v242, 0x50000, v194
	v_mov_b32_e32 v243, v159
	v_lshl_add_u64 v[242:243], v[242:243], 2, s[90:91]
	s_waitcnt vmcnt(0)
	v_sub_f32_e32 v137, v137, v220
	v_sub_f32_e32 v136, v136, v220
	v_sub_f32_e32 v139, v139, v220
	v_sub_f32_e32 v138, v138, v220
	v_pk_mul_f32 v[138:139], v[220:221], v[138:139] op_sel:[1,0]
	v_pk_mul_f32 v[136:137], v[220:221], v[136:137] op_sel:[1,0]
	v_pk_fma_f32 v[138:139], v[152:153], v[138:139], v[78:79]
	v_pk_fma_f32 v[136:137], v[154:155], v[136:137], v[76:77]
	v_pk_fma_f32 v[138:139], v[134:135], s[78:79], v[138:139] op_sel_hi:[1,0,1]
	v_pk_fma_f32 v[136:137], v[132:133], s[78:79], v[136:137] op_sel_hi:[1,0,1]
	global_store_dwordx4 v[242:243], v[136:139], off
	s_nop 1
	v_sub_f32_e32 v137, v213, v220
	v_sub_f32_e32 v136, v212, v220
	v_sub_f32_e32 v139, v215, v220
	v_sub_f32_e32 v138, v214, v220
	v_pk_mul_f32 v[138:139], v[220:221], v[138:139] op_sel:[1,0]
	v_pk_mul_f32 v[136:137], v[220:221], v[136:137] op_sel:[1,0]
	v_pk_fma_f32 v[138:139], v[148:149], v[138:139], v[74:75]
	v_pk_fma_f32 v[136:137], v[150:151], v[136:137], v[72:73]
	v_add_u32_e32 v212, 0x50010, v194
	v_mov_b32_e32 v213, v159
	v_pk_fma_f32 v[138:139], v[130:131], s[78:79], v[138:139] op_sel_hi:[1,0,1]
	v_pk_fma_f32 v[136:137], v[128:129], s[78:79], v[136:137] op_sel_hi:[1,0,1]
	v_lshl_add_u64 v[212:213], v[212:213], 2, s[90:91]
	global_store_dwordx4 v[212:213], v[136:139], off
	s_nop 1
	v_sub_f32_e32 v137, v207, v240
	v_sub_f32_e32 v136, v206, v240
	v_sub_f32_e32 v139, v209, v240
	v_sub_f32_e32 v138, v208, v240
	v_pk_mul_f32 v[136:137], v[240:241], v[136:137] op_sel:[1,0]
	v_pk_mul_f32 v[138:139], v[240:241], v[138:139] op_sel:[1,0]
	v_pk_fma_f32 v[136:137], v[154:155], v[136:137], v[68:69]
	v_pk_fma_f32 v[138:139], v[152:153], v[138:139], v[70:71]
	v_pk_fma_f32 v[132:133], v[132:133], s[78:79], v[136:137] op_sel_hi:[1,0,1]
	v_add_u32_e32 v136, 0x58000, v194
	v_mov_b32_e32 v137, v159
	v_pk_fma_f32 v[134:135], v[134:135], s[78:79], v[138:139] op_sel_hi:[1,0,1]
	v_lshl_add_u64 v[136:137], v[136:137], 2, s[90:91]
	global_store_dwordx4 v[136:137], v[132:135], off
	s_nop 1
	v_sub_f32_e32 v133, v217, v240
	v_sub_f32_e32 v132, v216, v240
	v_sub_f32_e32 v135, v219, v240
	v_sub_f32_e32 v134, v218, v240
	v_pk_mul_f32 v[132:133], v[240:241], v[132:133] op_sel:[1,0]
	v_pk_mul_f32 v[134:135], v[240:241], v[134:135] op_sel:[1,0]
	v_pk_fma_f32 v[132:133], v[150:151], v[132:133], v[64:65]
	v_pk_fma_f32 v[134:135], v[148:149], v[134:135], v[66:67]
	v_pk_fma_f32 v[128:129], v[128:129], s[78:79], v[132:133] op_sel_hi:[1,0,1]
	v_add_u32_e32 v132, 0x58010, v194
	v_mov_b32_e32 v133, v159
	v_pk_fma_f32 v[130:131], v[130:131], s[78:79], v[134:135] op_sel_hi:[1,0,1]
	v_lshl_add_u64 v[132:133], v[132:133], 2, s[90:91]
	global_store_dwordx4 v[132:133], v[128:131], off
	global_load_dwordx4 v[128:131], v[140:141], off offset:512
	v_add_u32_e32 v136, v232, v230
	v_mov_b32_e32 v137, v159
	v_lshl_add_u64 v[136:137], v[136:137], 2, s[88:89]
	s_waitcnt vmcnt(0)
;     template <bool LN, int BJ, int LO, int HI> DI void batch(const f32x4 (&acc)[2][2][4][2], unsigned row0, unsigned col0, const f32x4 (&gv)[2], const f32x4 (&bv)[2]) const {
;         f32x4 r[HI - LO]; float mean[(HI - LO) / 2], rstd[(HI - LO) / 2];
; #pragma unroll
;         for (int i = LO; i < HI; ++i) { const int ai = i >> 3, m = (i >> 1) & 3, n = i & 1; const unsigned row = row0 + ai * HALF + m * 16;
;             if (n == 0) { mean[(i - LO) >> 1] = 0.f; rstd[(i - LO) >> 1] = 1.f;
;                 if (LN) { const float2 st = *(const float2*)(stats + row * 2u); mean[(i - LO) >> 1] = st.x; rstd[(i - LO) >> 1] = st.y; } }
;             r[i - LO] = *(const f32x4*)(src + (row * (unsigned)DM + col0 + BJ * HALF + n * 16)); }
; #pragma unroll
;         for (int i = LO; i < HI; ++i) { const int ai = i >> 3, m = (i >> 1) & 3, n = i & 1; const unsigned row = row0 + ai * HALF + m * 16;
;             *(f32x4*)(Y + (row * (unsigned)DM + col0 + BJ * HALF + n * 16)) = acc[ai][BJ][m][n] + ((r[i - LO] - mean[(i - LO) >> 1]) * rstd[(i - LO) >> 1]) * gv[n] + bv[n]; }
;         __builtin_amdgcn_sched_barrier(0);
;     }
;     template <bool LN> DI void run(const f32x4 (&acc)[2][2][4][2], const Unit& u, int wr, int wc, int fr, int fq) const {
;     ...
;         load_gb<LN, 1>(col0, gv, bv);
;         batch<LN, 1, 0, 8>(acc, row0, col0, gv, bv);
	v_pk_mul_f32 v[212:213], v[130:131], s[78:79] op_sel_hi:[1,0]
	v_pk_mul_f32 v[214:215], v[128:129], s[78:79] op_sel_hi:[1,0]
	global_load_dwordx4 v[132:135], v[142:143], off offset:512
	global_load_dwordx4 v[128:131], v[140:141], off offset:576
	s_waitcnt vmcnt(0)
	v_pk_mul_f32 v[206:207], v[130:131], s[78:79] op_sel_hi:[1,0]
	v_pk_mul_f32 v[208:209], v[128:129], s[78:79] op_sel_hi:[1,0]
	global_load_dwordx4 v[128:131], v[142:143], off offset:576
	global_load_dwordx2 v[220:221], v[144:145], off
	global_load_dwordx4 v[240:243], v[136:137], off
	v_add_u32_e32 v136, v232, v229
	v_mov_b32_e32 v137, v159
	v_lshl_add_u64 v[136:137], v[136:137], 2, s[88:89]
	global_load_dwordx4 v[244:247], v[136:137], off
	global_load_dwordx2 v[218:219], v[146:147], off
	v_add_u32_e32 v136, v195, v230
	v_mov_b32_e32 v137, v159
	v_lshl_add_u64 v[136:137], v[136:137], 2, s[88:89]
	global_load_dwordx4 v[248:251], v[136:137], off
	v_add_u32_e32 v136, v195, v229
	v_mov_b32_e32 v137, v159
	v_lshl_add_u64 v[136:137], v[136:137], 2, s[88:89]
	global_load_dwordx4 v[152:155], v[136:137], off
	global_load_dwordx2 v[216:217], v[200:201], off
	v_add_u32_e32 v136, v236, v230
	v_mov_b32_e32 v137, v159
	v_lshl_add_u64 v[136:137], v[136:137], 2, s[88:89]
	global_load_dwordx4 v[148:151], v[136:137], off
	v_add_u32_e32 v136, v236, v229
	v_mov_b32_e32 v137, v159
	v_lshl_add_u64 v[136:137], v[136:137], 2, s[88:89]
	global_load_dwordx4 v[144:147], v[136:137], off
	global_load_dwordx2 v[200:201], v[202:203], off
	v_add_u32_e32 v136, v235, v230
	v_mov_b32_e32 v137, v159
	v_lshl_add_u64 v[136:137], v[136:137], 2, s[88:89]
	global_load_dwordx4 v[140:143], v[136:137], off
	v_add_u32_e32 v136, v235, v229
	v_mov_b32_e32 v137, v159
	v_lshl_add_u64 v[136:137], v[136:137], 2, s[88:89]
	global_load_dwordx4 v[136:139], v[136:137], off
	v_add_u32_e32 v202, 0x80, v194
	v_mov_b32_e32 v203, v159
	v_lshl_add_u64 v[202:203], v[202:203], 2, s[90:91]
	s_waitcnt vmcnt(0)
	v_sub_f32_e32 v241, v241, v220
	v_sub_f32_e32 v240, v240, v220
	v_sub_f32_e32 v243, v243, v220
	v_sub_f32_e32 v242, v242, v220
	v_pk_mul_f32 v[242:243], v[220:221], v[242:243] op_sel:[1,0]
	v_pk_mul_f32 v[240:241], v[220:221], v[240:241] op_sel:[1,0]
	v_pk_fma_f32 v[242:243], v[212:213], v[242:243], v[62:63]
	v_pk_fma_f32 v[240:241], v[214:215], v[240:241], v[60:61]
	v_pk_fma_f32 v[242:243], v[134:135], s[78:79], v[242:243] op_sel_hi:[1,0,1]
	v_pk_fma_f32 v[240:241], v[132:133], s[78:79], v[240:241] op_sel_hi:[1,0,1]
	global_store_dwordx4 v[202:203], v[240:243], off
	v_sub_f32_e32 v203, v245, v220
	v_sub_f32_e32 v202, v244, v220
	v_sub_f32_e32 v241, v247, v220
	v_sub_f32_e32 v240, v246, v220
	v_pk_mul_f32 v[202:203], v[220:221], v[202:203] op_sel:[1,0]
	v_pk_mul_f32 v[240:241], v[220:221], v[240:241] op_sel:[1,0]
	v_pk_fma_f32 v[202:203], v[208:209], v[202:203], v[56:57]
	v_pk_fma_f32 v[220:221], v[206:207], v[240:241], v[58:59]
	v_pk_fma_f32 v[240:241], v[128:129], s[78:79], v[202:203] op_sel_hi:[1,0,1]
	v_add_u32_e32 v202, 0x90, v194
	v_mov_b32_e32 v203, v159
	v_pk_fma_f32 v[242:243], v[130:131], s[78:79], v[220:221] op_sel_hi:[1,0,1]
	v_lshl_add_u64 v[202:203], v[202:203], 2, s[90:91]
	global_store_dwordx4 v[202:203], v[240:243], off
	v_sub_f32_e32 v203, v249, v218
	v_sub_f32_e32 v202, v248, v218
	v_sub_f32_e32 v221, v251, v218
	v_sub_f32_e32 v220, v250, v218
	v_pk_mul_f32 v[202:203], v[218:219], v[202:203] op_sel:[1,0]
	v_pk_mul_f32 v[220:221], v[218:219], v[220:221] op_sel:[1,0]
	v_pk_fma_f32 v[202:203], v[214:215], v[202:203], v[52:53]
	v_pk_fma_f32 v[220:221], v[212:213], v[220:221], v[54:55]
	v_pk_fma_f32 v[240:241], v[132:133], s[78:79], v[202:203] op_sel_hi:[1,0,1]
	v_add_u32_e32 v202, 0x8080, v194
	v_mov_b32_e32 v203, v159
	v_sub_f32_e32 v153, v153, v218
	v_sub_f32_e32 v152, v152, v218
	v_sub_f32_e32 v155, v155, v218
	v_sub_f32_e32 v154, v154, v218
	v_pk_fma_f32 v[242:243], v[134:135], s[78:79], v[220:221] op_sel_hi:[1,0,1]
	v_lshl_add_u64 v[202:203], v[202:203], 2, s[90:91]
	v_pk_mul_f32 v[154:155], v[218:219], v[154:155] op_sel:[1,0]
	v_pk_mul_f32 v[152:153], v[218:219], v[152:153] op_sel:[1,0]
	global_store_dwordx4 v[202:203], v[240:243], off
	v_pk_fma_f32 v[152:153], v[208:209], v[152:153], v[48:49]
	v_pk_fma_f32 v[154:155], v[206:207], v[154:155], v[50:51]
	v_add_u32_e32 v202, 0x8090, v194
	v_mov_b32_e32 v203, v159
	v_sub_f32_e32 v149, v149, v216
	v_sub_f32_e32 v148, v148, v216
	v_sub_f32_e32 v151, v151, v216
	v_sub_f32_e32 v150, v150, v216
	v_pk_fma_f32 v[154:155], v[130:131], s[78:79], v[154:155] op_sel_hi:[1,0,1]
	v_pk_fma_f32 v[152:153], v[128:129], s[78:79], v[152:153] op_sel_hi:[1,0,1]
	v_lshl_add_u64 v[202:203], v[202:203], 2, s[90:91]
	v_pk_mul_f32 v[150:151], v[216:217], v[150:151] op_sel:[1,0]
	v_pk_mul_f32 v[148:149], v[216:217], v[148:149] op_sel:[1,0]
	global_store_dwordx4 v[202:203], v[152:155], off
	v_pk_fma_f32 v[148:149], v[214:215], v[148:149], v[44:45]
	v_pk_fma_f32 v[150:151], v[212:213], v[150:151], v[46:47]
	v_add_u32_e32 v152, 0x10080, v194
	v_mov_b32_e32 v153, v159
	v_sub_f32_e32 v145, v145, v216
	v_sub_f32_e32 v144, v144, v216
	v_sub_f32_e32 v147, v147, v216
	v_sub_f32_e32 v146, v146, v216
	v_pk_fma_f32 v[150:151], v[134:135], s[78:79], v[150:151] op_sel_hi:[1,0,1]
	v_pk_fma_f32 v[148:149], v[132:133], s[78:79], v[148:149] op_sel_hi:[1,0,1]
	v_lshl_add_u64 v[152:153], v[152:153], 2, s[90:91]
	v_pk_mul_f32 v[146:147], v[216:217], v[146:147] op_sel:[1,0]
	v_pk_mul_f32 v[144:145], v[216:217], v[144:145] op_sel:[1,0]
	global_store_dwordx4 v[152:153], v[148:151], off
	v_pk_fma_f32 v[144:145], v[208:209], v[144:145], v[40:41]
	v_pk_fma_f32 v[146:147], v[206:207], v[146:147], v[42:43]
;     template <bool LN, int BJ, int LO, int HI> DI void batch(const f32x4 (&acc)[2][2][4][2], unsigned row0, unsigned col0, const f32x4 (&gv)[2], const f32x4 (&bv)[2]) const {
;         f32x4 r[HI - LO]; float mean[(HI - LO) / 2], rstd[(HI - LO) / 2];
; #pragma unroll
;         for (int i = LO; i < HI; ++i) { const int ai = i >> 3, m = (i >> 1) & 3, n = i & 1; const unsigned row = row0 + ai * HALF + m * 16;
;             if (n == 0) { mean[(i - LO) >> 1] = 0.f; rstd[(i - LO) >> 1] = 1.f;
;                 if (LN) { const float2 st = *(const float2*)(stats + row * 2u); mean[(i - LO) >> 1] = st.x; rstd[(i - LO) >> 1] = st.y; } }
;             r[i - LO] = *(const f32x4*)(src + (row * (unsigned)DM + col0 + BJ * HALF + n * 16)); }
; #pragma unroll
;         for (int i = LO; i < HI; ++i) { const int ai = i >> 3, m = (i >> 1) & 3, n = i & 1; const unsigned row = row0 + ai * HALF + m * 16;
;             *(f32x4*)(Y + (row * (unsigned)DM + col0 + BJ * HALF + n * 16)) = acc[ai][BJ][m][n] + ((r[i - LO] - mean[(i - LO) >> 1]) * rstd[(i - LO) >> 1]) * gv[n] + bv[n]; }
;         __builtin_amdgcn_sched_barrier(0);
;     }
	v_add_u32_e32 v148, 0x10090, v194
	v_mov_b32_e32 v149, v159
	v_sub_f32_e32 v141, v141, v200
	v_sub_f32_e32 v140, v140, v200
	v_sub_f32_e32 v143, v143, v200
	v_sub_f32_e32 v142, v142, v200
	v_pk_fma_f32 v[146:147], v[130:131], s[78:79], v[146:147] op_sel_hi:[1,0,1]
	v_pk_fma_f32 v[144:145], v[128:129], s[78:79], v[144:145] op_sel_hi:[1,0,1]
	v_lshl_add_u64 v[148:149], v[148:149], 2, s[90:91]
	v_pk_mul_f32 v[142:143], v[200:201], v[142:143] op_sel:[1,0]
	v_pk_mul_f32 v[140:141], v[200:201], v[140:141] op_sel:[1,0]
	global_store_dwordx4 v[148:149], v[144:147], off
	v_pk_fma_f32 v[140:141], v[214:215], v[140:141], v[36:37]
	v_pk_fma_f32 v[142:143], v[212:213], v[142:143], v[38:39]
	v_add_u32_e32 v144, 0x18080, v194
	v_mov_b32_e32 v145, v159
	v_sub_f32_e32 v137, v137, v200
	v_sub_f32_e32 v136, v136, v200
	v_sub_f32_e32 v139, v139, v200
	v_sub_f32_e32 v138, v138, v200
	v_pk_fma_f32 v[142:143], v[134:135], s[78:79], v[142:143] op_sel_hi:[1,0,1]
	v_pk_fma_f32 v[140:141], v[132:133], s[78:79], v[140:141] op_sel_hi:[1,0,1]
	v_lshl_add_u64 v[144:145], v[144:145], 2, s[90:91]
	v_pk_mul_f32 v[138:139], v[200:201], v[138:139] op_sel:[1,0]
	v_pk_mul_f32 v[136:137], v[200:201], v[136:137] op_sel:[1,0]
	global_store_dwordx4 v[144:145], v[140:143], off
	v_pk_fma_f32 v[136:137], v[208:209], v[136:137], v[32:33]
	v_pk_fma_f32 v[138:139], v[206:207], v[138:139], v[34:35]
	v_add_u32_e32 v140, 0x18090, v194
	v_mov_b32_e32 v141, v159
	v_pk_fma_f32 v[138:139], v[130:131], s[78:79], v[138:139] op_sel_hi:[1,0,1]
	v_pk_fma_f32 v[136:137], v[128:129], s[78:79], v[136:137] op_sel_hi:[1,0,1]
	v_lshl_add_u64 v[140:141], v[140:141], 2, s[90:91]
	global_store_dwordx4 v[140:141], v[136:139], off
	s_nop 1
	v_add_u32_e32 v136, v233, v230
	v_mov_b32_e32 v137, v159
	v_lshl_add_u64 v[136:137], v[136:137], 2, s[88:89]
	global_load_dwordx2 v[220:221], v[196:197], off
	global_load_dwordx4 v[216:219], v[136:137], off
	v_add_u32_e32 v136, v233, v229
	v_mov_b32_e32 v137, v159
	v_lshl_add_u64 v[136:137], v[136:137], 2, s[88:89]
	global_load_dwordx4 v[240:243], v[136:137], off
	global_load_dwordx2 v[200:201], v[198:199], off
	v_add_u32_e32 v136, v234, v230
	v_mov_b32_e32 v137, v159
	v_lshl_add_u64 v[136:137], v[136:137], 2, s[88:89]
	global_load_dwordx4 v[244:247], v[136:137], off
	v_add_u32_e32 v136, v234, v229
	v_mov_b32_e32 v137, v159
	v_lshl_add_u64 v[136:137], v[136:137], 2, s[88:89]
	global_load_dwordx4 v[152:155], v[136:137], off
	global_load_dwordx2 v[198:199], v[204:205], off
	v_add_u32_e32 v136, v237, v230
	v_mov_b32_e32 v137, v159
	v_lshl_add_u64 v[136:137], v[136:137], 2, s[88:89]
	global_load_dwordx4 v[148:151], v[136:137], off
	v_add_u32_e32 v136, v237, v229
	v_mov_b32_e32 v137, v159
	v_lshl_add_u64 v[136:137], v[136:137], 2, s[88:89]
	global_load_dwordx4 v[144:147], v[136:137], off
	global_load_dwordx2 v[196:197], v[210:211], off
	v_add_u32_e32 v136, v238, v230
	v_mov_b32_e32 v137, v159
	v_lshl_add_u64 v[136:137], v[136:137], 2, s[88:89]
	global_load_dwordx4 v[140:143], v[136:137], off
	v_add_u32_e32 v136, v238, v229
	v_mov_b32_e32 v137, v159
	v_lshl_add_u64 v[136:137], v[136:137], 2, s[88:89]
	global_load_dwordx4 v[136:139], v[136:137], off
	v_add_u32_e32 v210, 0x40080, v194
	v_mov_b32_e32 v211, v159
	v_lshl_add_u64 v[210:211], v[210:211], 2, s[90:91]
	s_waitcnt vmcnt(0)
;     template <bool LN, int BJ, int LO, int HI> DI void batch(const f32x4 (&acc)[2][2][4][2], unsigned row0, unsigned col0, const f32x4 (&gv)[2], const f32x4 (&bv)[2]) const {
;         f32x4 r[HI - LO]; float mean[(HI - LO) / 2], rstd[(HI - LO) / 2];
; #pragma unroll
;         for (int i = LO; i < HI; ++i) { const int ai = i >> 3, m = (i >> 1) & 3, n = i & 1; const unsigned row = row0 + ai * HALF + m * 16;
;             if (n == 0) { mean[(i - LO) >> 1] = 0.f; rstd[(i - LO) >> 1] = 1.f;
;                 if (LN) { const float2 st = *(const float2*)(stats + row * 2u); mean[(i - LO) >> 1] = st.x; rstd[(i - LO) >> 1] = st.y; } }
;             r[i - LO] = *(const f32x4*)(src + (row * (unsigned)DM + col0 + BJ * HALF + n * 16)); }
; #pragma unroll
;         for (int i = LO; i < HI; ++i) { const int ai = i >> 3, m = (i >> 1) & 3, n = i & 1; const unsigned row = row0 + ai * HALF + m * 16;
;             *(f32x4*)(Y + (row * (unsigned)DM + col0 + BJ * HALF + n * 16)) = acc[ai][BJ][m][n] + ((r[i - LO] - mean[(i - LO) >> 1]) * rstd[(i - LO) >> 1]) * gv[n] + bv[n]; }
;         __builtin_amdgcn_sched_barrier(0);
;     }
	v_sub_f32_e32 v203, v217, v220
	v_sub_f32_e32 v202, v216, v220
	v_sub_f32_e32 v205, v219, v220
	v_sub_f32_e32 v204, v218, v220
	v_pk_mul_f32 v[204:205], v[220:221], v[204:205] op_sel:[1,0]
	v_pk_mul_f32 v[202:203], v[220:221], v[202:203] op_sel:[1,0]
	v_pk_fma_f32 v[204:205], v[212:213], v[204:205], v[30:31]
	v_pk_fma_f32 v[202:203], v[214:215], v[202:203], v[28:29]
	v_pk_fma_f32 v[204:205], v[134:135], s[78:79], v[204:205] op_sel_hi:[1,0,1]
	v_pk_fma_f32 v[202:203], v[132:133], s[78:79], v[202:203] op_sel_hi:[1,0,1]
	global_store_dwordx4 v[210:211], v[202:205], off
	v_add_u32_e32 v210, 0x40090, v194
	v_mov_b32_e32 v211, v159
	v_sub_f32_e32 v203, v241, v220
	v_sub_f32_e32 v202, v240, v220
	v_sub_f32_e32 v205, v243, v220
	v_sub_f32_e32 v204, v242, v220
	v_pk_mul_f32 v[204:205], v[220:221], v[204:205] op_sel:[1,0]
	v_pk_mul_f32 v[202:203], v[220:221], v[202:203] op_sel:[1,0]
	v_pk_fma_f32 v[204:205], v[206:207], v[204:205], v[26:27]
	v_pk_fma_f32 v[202:203], v[208:209], v[202:203], v[24:25]
	v_pk_fma_f32 v[204:205], v[130:131], s[78:79], v[204:205] op_sel_hi:[1,0,1]
	v_pk_fma_f32 v[202:203], v[128:129], s[78:79], v[202:203] op_sel_hi:[1,0,1]
	v_lshl_add_u64 v[210:211], v[210:211], 2, s[90:91]
	global_store_dwordx4 v[210:211], v[202:205], off
	v_sub_f32_e32 v149, v149, v198
	v_sub_f32_e32 v148, v148, v198
	v_sub_f32_e32 v203, v245, v200
	v_sub_f32_e32 v202, v244, v200
	v_sub_f32_e32 v141, v141, v196
	v_sub_f32_e32 v140, v140, v196
	v_sub_f32_e32 v205, v247, v200
	v_sub_f32_e32 v204, v246, v200
	v_pk_mul_f32 v[202:203], v[200:201], v[202:203] op_sel:[1,0]
	v_sub_f32_e32 v151, v151, v198
	v_sub_f32_e32 v150, v150, v198
	v_pk_mul_f32 v[148:149], v[198:199], v[148:149] op_sel:[1,0]
	v_sub_f32_e32 v143, v143, v196
	v_sub_f32_e32 v142, v142, v196
	v_pk_mul_f32 v[140:141], v[196:197], v[140:141] op_sel:[1,0]
	v_pk_mul_f32 v[204:205], v[200:201], v[204:205] op_sel:[1,0]
	v_pk_fma_f32 v[202:203], v[214:215], v[202:203], v[20:21]
	v_sub_f32_e32 v153, v153, v200
	v_sub_f32_e32 v152, v152, v200
	v_sub_f32_e32 v155, v155, v200
	v_sub_f32_e32 v154, v154, v200
	v_pk_mul_f32 v[150:151], v[198:199], v[150:151] op_sel:[1,0]
	v_pk_fma_f32 v[148:149], v[214:215], v[148:149], v[12:13]
	v_pk_mul_f32 v[142:143], v[196:197], v[142:143] op_sel:[1,0]
	v_pk_fma_f32 v[140:141], v[214:215], v[140:141], v[4:5]
	v_pk_fma_f32 v[204:205], v[212:213], v[204:205], v[22:23]
	v_pk_fma_f32 v[202:203], v[132:133], s[78:79], v[202:203] op_sel_hi:[1,0,1]
	v_pk_mul_f32 v[154:155], v[200:201], v[154:155] op_sel:[1,0]
	v_pk_mul_f32 v[152:153], v[200:201], v[152:153] op_sel:[1,0]
	v_pk_fma_f32 v[150:151], v[212:213], v[150:151], v[14:15]
	v_pk_fma_f32 v[148:149], v[132:133], s[78:79], v[148:149] op_sel_hi:[1,0,1]
	v_pk_fma_f32 v[142:143], v[212:213], v[142:143], v[6:7]
	v_pk_fma_f32 v[132:133], v[132:133], s[78:79], v[140:141] op_sel_hi:[1,0,1]
	v_add_u32_e32 v140, 0x58080, v194
	v_mov_b32_e32 v141, v159
	v_pk_fma_f32 v[204:205], v[134:135], s[78:79], v[204:205] op_sel_hi:[1,0,1]
	v_pk_fma_f32 v[152:153], v[208:209], v[152:153], v[16:17]
	v_pk_fma_f32 v[154:155], v[206:207], v[154:155], v[18:19]
	v_add_u32_e32 v200, 0x48090, v194
	v_mov_b32_e32 v201, v159
	v_pk_fma_f32 v[150:151], v[134:135], s[78:79], v[150:151] op_sel_hi:[1,0,1]
	v_pk_fma_f32 v[134:135], v[134:135], s[78:79], v[142:143] op_sel_hi:[1,0,1]
	v_lshl_add_u64 v[140:141], v[140:141], 2, s[90:91]
	v_pk_fma_f32 v[154:155], v[130:131], s[78:79], v[154:155] op_sel_hi:[1,0,1]
	v_pk_fma_f32 v[152:153], v[128:129], s[78:79], v[152:153] op_sel_hi:[1,0,1]
	v_lshl_add_u64 v[200:201], v[200:201], 2, s[90:91]
	v_sub_f32_e32 v145, v145, v198
	v_sub_f32_e32 v144, v144, v198
	global_store_dwordx4 v[140:141], v[132:135], off
	global_store_dwordx4 v[200:201], v[152:155], off
	v_sub_f32_e32 v147, v147, v198
	v_sub_f32_e32 v133, v137, v196
	v_sub_f32_e32 v132, v136, v196
	v_add_u32_e32 v152, 0x50080, v194
	v_mov_b32_e32 v153, v159
	v_sub_f32_e32 v146, v146, v198
	v_pk_mul_f32 v[144:145], v[198:199], v[144:145] op_sel:[1,0]
	v_sub_f32_e32 v135, v139, v196
	v_sub_f32_e32 v134, v138, v196
	v_pk_mul_f32 v[132:133], v[196:197], v[132:133] op_sel:[1,0]
	v_lshl_add_u64 v[152:153], v[152:153], 2, s[90:91]
	v_pk_mul_f32 v[146:147], v[198:199], v[146:147] op_sel:[1,0]
	v_pk_fma_f32 v[144:145], v[208:209], v[144:145], v[8:9]
	v_pk_mul_f32 v[134:135], v[196:197], v[134:135] op_sel:[1,0]
	v_pk_fma_f32 v[132:133], v[208:209], v[132:133], v[0:1]
	v_add_u32_e32 v210, 0x48080, v194
	v_mov_b32_e32 v211, v159
	global_store_dwordx4 v[152:153], v[148:151], off
	v_pk_fma_f32 v[146:147], v[206:207], v[146:147], v[10:11]
	v_pk_fma_f32 v[144:145], v[128:129], s[78:79], v[144:145] op_sel_hi:[1,0,1]
	v_add_u32_e32 v148, 0x50090, v194
	v_mov_b32_e32 v149, v159
	v_pk_fma_f32 v[134:135], v[206:207], v[134:135], v[2:3]
	v_pk_fma_f32 v[128:129], v[128:129], s[78:79], v[132:133] op_sel_hi:[1,0,1]
	v_add_u32_e32 v132, 0x58090, v194
	v_mov_b32_e32 v133, v159
	v_lshl_add_u64 v[210:211], v[210:211], 2, s[90:91]
	v_pk_fma_f32 v[146:147], v[130:131], s[78:79], v[146:147] op_sel_hi:[1,0,1]
	v_lshl_add_u64 v[148:149], v[148:149], 2, s[90:91]
	v_pk_fma_f32 v[130:131], v[130:131], s[78:79], v[134:135] op_sel_hi:[1,0,1]
	v_lshl_add_u64 v[132:133], v[132:133], 2, s[90:91]
	global_store_dwordx4 v[210:211], v[202:205], off
	global_store_dwordx4 v[148:149], v[144:147], off
	global_store_dwordx4 v[132:133], v[128:131], off
	s_mov_b64 s[20:21], 0
	s_branch .LBB0_81

; #define PG8_STAGE(bufoff, gbase) do { _Pragma("unroll") for (int _i = 0; _i < 2; ++_i) \
;         __builtin_amdgcn_global_load_lds((const unsigned*)((const char*)(gbase) + voff[_i]), (LAS unsigned*)(lds + (bufoff) + ldsw + _i * 8192), 16, 0, 0); } while (0)
; #define PG8_LDA(dst, b, h) do { _Pragma("unroll") for (int m = 0; m < 4; ++m) _Pragma("unroll") for (int k = 0; k < 2; ++k) dst[m][k] = *(const LAS bf16x8*)(lds + PG8_SA(b, h) + aoff + m * 2048 + k * 1024); } while (0)
; #define PG8_LDB(dst, b, h) do { _Pragma("unroll") for (int n = 0; n < 2; ++n) _Pragma("unroll") for (int k = 0; k < 2; ++k) dst[n][k] = *(const LAS bf16x8*)(lds + PG8_SB(b, h) + boff + n * 2048 + k * 1024); } while (0)
; #define PG8_MMA(ai, bj, At, Bt) do { __builtin_amdgcn_s_setprio(1); _Pragma("unroll") for (int m = 0; m < 4; ++m) _Pragma("unroll") for (int n = 0; n < 2; ++n) _Pragma("unroll") for (int k = 0; k < 2; ++k) \
;         acc[ai][bj][m][n] = __builtin_amdgcn_mfma_f32_16x16x32_bf16(Bt[n][k], At[m][k], acc[ai][bj][m][n], 0, 0, 0); __builtin_amdgcn_s_setprio(0); } while (0)
; #define PG8_WAIT_V(n) asm volatile("s_waitcnt vmcnt(" #n ")" ::: "memory")
; #define PG8_WAIT_L(n) asm volatile("s_waitcnt lgkmcnt(" #n ")" ::: "memory")
; #define PG8_BAR __builtin_amdgcn_s_barrier()
; #define PG8_SCHED __builtin_amdgcn_sched_barrier(0)
; template <class Epi>
; DI void gemm_phase(LAS unsigned char* lds, const Gemm g, const StaticOrder& S, const Epi& E) {
;     ...
;             const bool last = (t == nt - 2);
;             const char* a1 = cA + (size_t)(t + 1) * kstep;
;             const char* a2 = last ? nA : cA + (size_t)(t + 2) * kstep; const char* b2 = last ? nB : cB + (size_t)(t + 2) * kstep;
;             const char* a3 = a2 + kstep; const char* b3 = b2 + kstep;
;             PG8_LDB(B0, 0, 0); PG8_SCHED; PG8_LDA(At, 0, 0); PG8_STAGE(PG8_SA(1, 1), a1 + hstep);
;             PG8_WAIT_L(8); PG8_BAR; PG8_WAIT_L(0); PG8_MMA(0, 0, At, B0); PG8_BAR; PG8_SCHED;
;             PG8_LDB(B1, 0, 1); PG8_STAGE(PG8_SB(0, 0), b2);
;             PG8_BAR; PG8_WAIT_L(0); PG8_MMA(0, 1, At, B1); PG8_BAR;
;             PG8_LDA(At, 0, 1); PG8_STAGE(PG8_SA(0, 0), a2);
;             PG8_BAR; PG8_WAIT_L(0); PG8_MMA(1, 0, At, B0); PG8_BAR; PG8_SCHED;
;             PG8_STAGE(PG8_SB(0, 1), b2 + hstep);
;             PG8_WAIT_V(6); PG8_BAR; PG8_MMA(1, 1, At, B1); PG8_BAR;
.LBB0_134:
	ds_read_b128 v[96:99], v199
	ds_read_b128 v[100:103], v199 offset:1024
	ds_read_b128 v[136:139], v199 offset:2048
	ds_read_b128 v[148:151], v199 offset:3072
	ds_read_b128 v[152:155], v201
	ds_read_b128 v[186:189], v201 offset:1024
	ds_read_b128 v[190:193], v201 offset:2048
	ds_read_b128 v[194:197], v201 offset:3072
	ds_read_b128 v[202:205], v201 offset:4096
	ds_read_b128 v[206:209], v201 offset:5120
	ds_read_b128 v[210:213], v201 offset:6144
	ds_read_b128 v[214:217], v201 offset:7168
	s_add_u32 s18, s16, 0x100
	s_addc_u32 s19, s17, 0
	s_add_i32 s39, 0, 0x10000
	s_cmpk_eq_i32 s33, 0x54
	s_cselect_b32 s23, s9, s19
	s_cselect_b32 s22, s8, s18
	s_cselect_b32 s21, s11, s5
	s_cselect_b32 s20, s10, s4
	s_add_i32 m0, s28, 0xc000
	s_nop 0
	global_load_lds_dwordx4 v144, s[16:17]
	s_add_i32 m0, s28, 0xe000
	s_nop 0
	global_load_lds_dwordx4 v146, s[16:17]
	s_waitcnt lgkmcnt(0)
	s_setprio 1
	s_barrier
	v_mfma_f32_16x16x32_bf16 v[132:135], v[96:99], v[152:155], v[132:135]
	v_mfma_f32_16x16x32_bf16 v[128:131], v[136:139], v[152:155], v[128:131]
	v_mfma_f32_16x16x32_bf16 v[124:127], v[96:99], v[190:193], v[124:127]
	v_mfma_f32_16x16x32_bf16 v[120:123], v[136:139], v[190:193], v[120:123]
	v_mfma_f32_16x16x32_bf16 v[116:119], v[96:99], v[202:205], v[116:119]
	v_mfma_f32_16x16x32_bf16 v[112:115], v[136:139], v[202:205], v[112:115]
	v_mfma_f32_16x16x32_bf16 v[108:111], v[96:99], v[210:213], v[108:111]
	v_mfma_f32_16x16x32_bf16 v[104:107], v[136:139], v[210:213], v[104:107]
	v_mfma_f32_16x16x32_bf16 v[132:135], v[100:103], v[186:189], v[132:135]
	v_mfma_f32_16x16x32_bf16 v[128:131], v[148:151], v[186:189], v[128:131]
	v_mfma_f32_16x16x32_bf16 v[124:127], v[100:103], v[194:197], v[124:127]
	v_mfma_f32_16x16x32_bf16 v[120:123], v[148:151], v[194:197], v[120:123]
	v_mfma_f32_16x16x32_bf16 v[116:119], v[100:103], v[206:209], v[116:119]
	v_mfma_f32_16x16x32_bf16 v[112:115], v[148:151], v[206:209], v[112:115]
	v_mfma_f32_16x16x32_bf16 v[108:111], v[100:103], v[214:217], v[108:111]
	s_setprio 0
	v_mfma_f32_16x16x32_bf16 v[104:107], v[148:151], v[214:217], v[104:107]
	s_barrier
	ds_read_b128 v[226:229], v199 offset:16384
	ds_read_b128 v[230:233], v199 offset:17408
	ds_read_b128 v[234:237], v199 offset:18432
	ds_read_b128 v[238:241], v199 offset:19456
	s_add_i32 s40, 0, 0x14000
	s_add_i32 s16, s39, s27
	s_mov_b32 m0, s16
	s_nop 0
	global_load_lds_dwordx4 v142, s[20:21]
	s_add_i32 m0, s16, 0x2000
	s_nop 0
	global_load_lds_dwordx4 v140, s[20:21]
	s_waitcnt lgkmcnt(0)
	s_setprio 1
	s_barrier
	v_mfma_f32_16x16x32_bf16 v[60:63], v[226:229], v[152:155], v[60:63]
	v_mfma_f32_16x16x32_bf16 v[56:59], v[234:237], v[152:155], v[56:59]
	v_mfma_f32_16x16x32_bf16 v[52:55], v[226:229], v[190:193], v[52:55]
	v_mfma_f32_16x16x32_bf16 v[48:51], v[234:237], v[190:193], v[48:51]
	v_mfma_f32_16x16x32_bf16 v[44:47], v[226:229], v[202:205], v[44:47]
	v_mfma_f32_16x16x32_bf16 v[40:43], v[234:237], v[202:205], v[40:43]
	v_mfma_f32_16x16x32_bf16 v[36:39], v[226:229], v[210:213], v[36:39]
	v_mfma_f32_16x16x32_bf16 v[32:35], v[234:237], v[210:213], v[32:35]
	v_mfma_f32_16x16x32_bf16 v[60:63], v[230:233], v[186:189], v[60:63]
	s_mov_b32 m0, s28
	v_mfma_f32_16x16x32_bf16 v[56:59], v[238:241], v[186:189], v[56:59]
	v_mfma_f32_16x16x32_bf16 v[52:55], v[230:233], v[194:197], v[52:55]
	v_mfma_f32_16x16x32_bf16 v[48:51], v[238:241], v[194:197], v[48:51]
	v_mfma_f32_16x16x32_bf16 v[44:47], v[230:233], v[206:209], v[44:47]
	v_mfma_f32_16x16x32_bf16 v[40:43], v[238:241], v[206:209], v[40:43]
	v_mfma_f32_16x16x32_bf16 v[36:39], v[230:233], v[214:217], v[36:39]
	s_setprio 0
	v_mfma_f32_16x16x32_bf16 v[32:35], v[238:241], v[214:217], v[32:35]
	s_barrier
	ds_read_b128 v[152:155], v201 offset:16384
	ds_read_b128 v[186:189], v201 offset:17408
	ds_read_b128 v[190:193], v201 offset:18432
	ds_read_b128 v[194:197], v201 offset:19456
	ds_read_b128 v[202:205], v201 offset:20480
	ds_read_b128 v[206:209], v201 offset:21504
	ds_read_b128 v[210:213], v201 offset:22528
	ds_read_b128 v[214:217], v201 offset:23552
	global_load_lds_dwordx4 v142, s[22:23]
	s_mov_b64 s[100:101], s[22:23]
	s_mov_b32 m0, s29
	s_nop 0
	global_load_lds_dwordx4 v140, s[22:23]
	s_waitcnt lgkmcnt(0)
	s_setprio 1
	s_barrier
	v_mfma_f32_16x16x32_bf16 v[92:95], v[96:99], v[152:155], v[92:95]
	v_mfma_f32_16x16x32_bf16 v[88:91], v[136:139], v[152:155], v[88:91]
	v_mfma_f32_16x16x32_bf16 v[84:87], v[96:99], v[190:193], v[84:87]
	v_mfma_f32_16x16x32_bf16 v[80:83], v[136:139], v[190:193], v[80:83]
	v_mfma_f32_16x16x32_bf16 v[76:79], v[96:99], v[202:205], v[76:79]
	v_mfma_f32_16x16x32_bf16 v[72:75], v[136:139], v[202:205], v[72:75]
	v_mfma_f32_16x16x32_bf16 v[68:71], v[96:99], v[210:213], v[68:71]
	v_mfma_f32_16x16x32_bf16 v[64:67], v[136:139], v[210:213], v[64:67]
	v_mfma_f32_16x16x32_bf16 v[92:95], v[100:103], v[186:189], v[92:95]
	v_mfma_f32_16x16x32_bf16 v[88:91], v[148:151], v[186:189], v[88:91]
	v_mfma_f32_16x16x32_bf16 v[84:87], v[100:103], v[194:197], v[84:87]
	v_mfma_f32_16x16x32_bf16 v[80:83], v[148:151], v[194:197], v[80:83]
	v_mfma_f32_16x16x32_bf16 v[76:79], v[100:103], v[206:209], v[76:79]
	v_mfma_f32_16x16x32_bf16 v[72:75], v[148:151], v[206:209], v[72:75]
	v_mfma_f32_16x16x32_bf16 v[68:71], v[100:103], v[214:217], v[68:71]
	s_setprio 0
	v_mfma_f32_16x16x32_bf16 v[64:67], v[148:151], v[214:217], v[64:67]
	s_barrier
	s_add_u32 s16, s20, 0x160000
	s_addc_u32 s17, s21, 0
	s_add_i32 s39, s40, s27
	s_mov_b32 m0, s39
	s_nop 0
	global_load_lds_dwordx4 v142, s[16:17]
	s_add_i32 m0, s39, 0x2000
	s_nop 0
	global_load_lds_dwordx4 v140, s[16:17]
	s_waitcnt vmcnt(6)
	s_setprio 1
	s_barrier
; #define PG8_STAGE(bufoff, gbase) do { _Pragma("unroll") for (int _i = 0; _i < 2; ++_i) \
;         __builtin_amdgcn_global_load_lds((const unsigned*)((const char*)(gbase) + voff[_i]), (LAS unsigned*)(lds + (bufoff) + ldsw + _i * 8192), 16, 0, 0); } while (0)
; #define PG8_LDA(dst, b, h) do { _Pragma("unroll") for (int m = 0; m < 4; ++m) _Pragma("unroll") for (int k = 0; k < 2; ++k) dst[m][k] = *(const LAS bf16x8*)(lds + PG8_SA(b, h) + aoff + m * 2048 + k * 1024); } while (0)
; #define PG8_LDB(dst, b, h) do { _Pragma("unroll") for (int n = 0; n < 2; ++n) _Pragma("unroll") for (int k = 0; k < 2; ++k) dst[n][k] = *(const LAS bf16x8*)(lds + PG8_SB(b, h) + boff + n * 2048 + k * 1024); } while (0)
; #define PG8_MMA(ai, bj, At, Bt) do { __builtin_amdgcn_s_setprio(1); _Pragma("unroll") for (int m = 0; m < 4; ++m) _Pragma("unroll") for (int n = 0; n < 2; ++n) _Pragma("unroll") for (int k = 0; k < 2; ++k) \
;         acc[ai][bj][m][n] = __builtin_amdgcn_mfma_f32_16x16x32_bf16(Bt[n][k], At[m][k], acc[ai][bj][m][n], 0, 0, 0); __builtin_amdgcn_s_setprio(0); } while (0)
; #define PG8_WAIT_V(n) asm volatile("s_waitcnt vmcnt(" #n ")" ::: "memory")
; #define PG8_WAIT_L(n) asm volatile("s_waitcnt lgkmcnt(" #n ")" ::: "memory")
; #define PG8_BAR __builtin_amdgcn_s_barrier()
; #define PG8_SCHED __builtin_amdgcn_sched_barrier(0)
; template <class Epi>
; DI void gemm_phase(LAS unsigned char* lds, const Gemm g, const StaticOrder& S, const Epi& E) {
;     ...
;             PG8_WAIT_V(6); PG8_BAR; PG8_MMA(1, 1, At, B1); PG8_BAR;
;             PG8_LDB(B0, 1, 0); PG8_SCHED; PG8_LDA(At, 1, 0); PG8_STAGE(PG8_SA(0, 1), a2 + hstep);
;             PG8_WAIT_L(8); PG8_BAR; PG8_WAIT_L(0); PG8_MMA(0, 0, At, B0); PG8_BAR; PG8_SCHED;
;             PG8_LDB(B1, 1, 1); PG8_STAGE(PG8_SB(1, 0), b3);
;             PG8_BAR; PG8_WAIT_L(0); PG8_MMA(0, 1, At, B1); PG8_BAR;
;             PG8_LDA(At, 1, 1); PG8_STAGE(PG8_SA(1, 0), a3);
;             PG8_BAR; PG8_WAIT_L(0); PG8_MMA(1, 0, At, B0); PG8_BAR; PG8_SCHED;
	v_mfma_f32_16x16x32_bf16 v[28:31], v[226:229], v[152:155], v[28:31]
	v_mfma_f32_16x16x32_bf16 v[24:27], v[234:237], v[152:155], v[24:27]
	v_mfma_f32_16x16x32_bf16 v[20:23], v[226:229], v[190:193], v[20:23]
	v_mfma_f32_16x16x32_bf16 v[16:19], v[234:237], v[190:193], v[16:19]
	v_mfma_f32_16x16x32_bf16 v[12:15], v[226:229], v[202:205], v[12:15]
	v_mfma_f32_16x16x32_bf16 v[8:11], v[234:237], v[202:205], v[8:11]
	v_mfma_f32_16x16x32_bf16 v[4:7], v[226:229], v[210:213], v[4:7]
	v_mfma_f32_16x16x32_bf16 v[0:3], v[234:237], v[210:213], v[0:3]
	v_mfma_f32_16x16x32_bf16 v[28:31], v[230:233], v[186:189], v[28:31]
	s_add_i32 s39, 0, 0x18000
	v_mfma_f32_16x16x32_bf16 v[24:27], v[238:241], v[186:189], v[24:27]
	v_mfma_f32_16x16x32_bf16 v[20:23], v[230:233], v[194:197], v[20:23]
	v_mfma_f32_16x16x32_bf16 v[16:19], v[238:241], v[194:197], v[16:19]
	v_mfma_f32_16x16x32_bf16 v[12:15], v[230:233], v[206:209], v[12:15]
	v_mfma_f32_16x16x32_bf16 v[8:11], v[238:241], v[206:209], v[8:11]
	v_mfma_f32_16x16x32_bf16 v[4:7], v[230:233], v[214:217], v[4:7]
	s_setprio 0
	v_mfma_f32_16x16x32_bf16 v[0:3], v[238:241], v[214:217], v[0:3]
	s_barrier
	ds_read_b128 v[96:99], v199 offset:32768
	ds_read_b128 v[100:103], v199 offset:33792
	ds_read_b128 v[136:139], v199 offset:34816
	ds_read_b128 v[148:151], v199 offset:35840
	ds_read_b128 v[152:155], v201 offset:32768
	ds_read_b128 v[186:189], v201 offset:33792
	ds_read_b128 v[190:193], v201 offset:34816
	ds_read_b128 v[194:197], v201 offset:35840
	ds_read_b128 v[202:205], v201 offset:36864
	ds_read_b128 v[206:209], v201 offset:37888
	ds_read_b128 v[210:213], v201 offset:38912
	ds_read_b128 v[214:217], v201 offset:39936
	s_add_u32 s16, s22, 0x160000
	s_addc_u32 s17, s23, 0
	s_mov_b32 m0, s30
	s_nop 0
	global_load_lds_dwordx4 v142, s[16:17]
	s_mov_b32 m0, s31
	s_nop 0
	global_load_lds_dwordx4 v140, s[16:17]
	s_waitcnt lgkmcnt(0)
	s_setprio 1
	s_barrier
	v_mfma_f32_16x16x32_bf16 v[132:135], v[96:99], v[152:155], v[132:135]
	v_mfma_f32_16x16x32_bf16 v[128:131], v[136:139], v[152:155], v[128:131]
	v_mfma_f32_16x16x32_bf16 v[124:127], v[96:99], v[190:193], v[124:127]
	v_mfma_f32_16x16x32_bf16 v[120:123], v[136:139], v[190:193], v[120:123]
	v_mfma_f32_16x16x32_bf16 v[116:119], v[96:99], v[202:205], v[116:119]
	v_mfma_f32_16x16x32_bf16 v[112:115], v[136:139], v[202:205], v[112:115]
	v_mfma_f32_16x16x32_bf16 v[108:111], v[96:99], v[210:213], v[108:111]
	v_mfma_f32_16x16x32_bf16 v[104:107], v[136:139], v[210:213], v[104:107]
	v_mfma_f32_16x16x32_bf16 v[132:135], v[100:103], v[186:189], v[132:135]
	v_mfma_f32_16x16x32_bf16 v[128:131], v[148:151], v[186:189], v[128:131]
	v_mfma_f32_16x16x32_bf16 v[124:127], v[100:103], v[194:197], v[124:127]
	v_mfma_f32_16x16x32_bf16 v[120:123], v[148:151], v[194:197], v[120:123]
	v_mfma_f32_16x16x32_bf16 v[116:119], v[100:103], v[206:209], v[116:119]
	v_mfma_f32_16x16x32_bf16 v[112:115], v[148:151], v[206:209], v[112:115]
	v_mfma_f32_16x16x32_bf16 v[108:111], v[100:103], v[214:217], v[108:111]
	s_setprio 0
	v_mfma_f32_16x16x32_bf16 v[104:107], v[148:151], v[214:217], v[104:107]
	s_barrier
	ds_read_b128 v[226:229], v199 offset:49152
	ds_read_b128 v[230:233], v199 offset:50176
	ds_read_b128 v[234:237], v199 offset:51200
	ds_read_b128 v[238:241], v199 offset:52224
	s_add_i32 s22, 0, 0x1c000
	s_add_i32 s16, s39, s27
	s_add_i32 m0, s16, 0xffffff80
	s_nop 0
	global_load_lds_dwordx4 v142, s[20:21] offset:128
	s_add_i32 m0, s16, 0x1f80
	s_nop 0
	global_load_lds_dwordx4 v140, s[20:21] offset:128
	s_waitcnt lgkmcnt(0)
	s_setprio 1
	s_barrier
	v_mfma_f32_16x16x32_bf16 v[60:63], v[226:229], v[152:155], v[60:63]
	v_mfma_f32_16x16x32_bf16 v[56:59], v[234:237], v[152:155], v[56:59]
	v_mfma_f32_16x16x32_bf16 v[52:55], v[226:229], v[190:193], v[52:55]
	v_mfma_f32_16x16x32_bf16 v[48:51], v[234:237], v[190:193], v[48:51]
	v_mfma_f32_16x16x32_bf16 v[44:47], v[226:229], v[202:205], v[44:47]
	v_mfma_f32_16x16x32_bf16 v[40:43], v[234:237], v[202:205], v[40:43]
	v_mfma_f32_16x16x32_bf16 v[36:39], v[226:229], v[210:213], v[36:39]
	v_mfma_f32_16x16x32_bf16 v[32:35], v[234:237], v[210:213], v[32:35]
	v_mfma_f32_16x16x32_bf16 v[60:63], v[230:233], v[186:189], v[60:63]
	s_add_i32 m0, s34, 0xffffff80
	v_mfma_f32_16x16x32_bf16 v[56:59], v[238:241], v[186:189], v[56:59]
	v_mfma_f32_16x16x32_bf16 v[52:55], v[230:233], v[194:197], v[52:55]
	v_mfma_f32_16x16x32_bf16 v[48:51], v[238:241], v[194:197], v[48:51]
	v_mfma_f32_16x16x32_bf16 v[44:47], v[230:233], v[206:209], v[44:47]
	v_mfma_f32_16x16x32_bf16 v[40:43], v[238:241], v[206:209], v[40:43]
	v_mfma_f32_16x16x32_bf16 v[36:39], v[230:233], v[214:217], v[36:39]
	s_setprio 0
	v_mfma_f32_16x16x32_bf16 v[32:35], v[238:241], v[214:217], v[32:35]
	s_barrier
	ds_read_b128 v[152:155], v201 offset:49152
	ds_read_b128 v[186:189], v201 offset:50176
	ds_read_b128 v[190:193], v201 offset:51200
	ds_read_b128 v[194:197], v201 offset:52224
	ds_read_b128 v[202:205], v201 offset:53248
	ds_read_b128 v[206:209], v201 offset:54272
	ds_read_b128 v[210:213], v201 offset:55296
	ds_read_b128 v[214:217], v201 offset:56320
	global_load_lds_dwordx4 v142, s[100:101] offset:128
	s_add_i32 m0, s35, 0xffffff80
	s_nop 0
	global_load_lds_dwordx4 v140, s[100:101] offset:128
	s_waitcnt lgkmcnt(0)
	s_setprio 1
	s_barrier
; #define PG8_WAIT_V(n) asm volatile("s_waitcnt vmcnt(" #n ")" ::: "memory")
; #define PG8_WAIT_L(n) asm volatile("s_waitcnt lgkmcnt(" #n ")" ::: "memory")
; #define PG8_BAR __builtin_amdgcn_s_barrier()
; template <class Epi>
; DI void gemm_phase(LAS unsigned char* lds, const Gemm g, const StaticOrder& S, const Epi& E) {
;     ...
;             PG8_BAR; PG8_WAIT_L(0); PG8_MMA(1, 0, At, B0); PG8_BAR; PG8_SCHED;
;             PG8_STAGE(PG8_SB(1, 1), b3 + hstep);
;             PG8_WAIT_V(6); PG8_BAR; PG8_MMA(1, 1, At, B1); PG8_BAR;
;     template <bool LN, int BJ, int LO, int HI> DI void batch(const f32x4 (&acc)[2][2][4][2], unsigned row0, unsigned col0, const f32x4 (&gv)[2], const f32x4 (&bv)[2]) const {
;         f32x4 r[HI - LO]; float mean[(HI - LO) / 2], rstd[(HI - LO) / 2];
; #pragma unroll
;         for (int i = LO; i < HI; ++i) { const int ai = i >> 3, m = (i >> 1) & 3, n = i & 1; const unsigned row = row0 + ai * HALF + m * 16;
;             if (n == 0) { mean[(i - LO) >> 1] = 0.f; rstd[(i - LO) >> 1] = 1.f;
;                 if (LN) { const float2 st = *(const float2*)(stats + row * 2u); mean[(i - LO) >> 1] = st.x; rstd[(i - LO) >> 1] = st.y; } }
;             r[i - LO] = *(const f32x4*)(src + (row * (unsigned)DM + col0 + BJ * HALF + n * 16)); }
; #pragma unroll
;         for (int i = LO; i < HI; ++i) { const int ai = i >> 3, m = (i >> 1) & 3, n = i & 1; const unsigned row = row0 + ai * HALF + m * 16;
;             *(f32x4*)(Y + (row * (unsigned)DM + col0 + BJ * HALF + n * 16)) = acc[ai][BJ][m][n] + ((r[i - LO] - mean[(i - LO) >> 1]) * rstd[(i - LO) >> 1]) * gv[n] + bv[n]; }
;         __builtin_amdgcn_sched_barrier(0);
;     }
;     template <bool LN, int BJ> DI void load_gb(unsigned col0, f32x4 (&gv)[2], f32x4 (&bv)[2]) const {
; #pragma unroll
;         for (int n = 0; n < 2; ++n) {
;             if (LN) { gv[n] = *(const f32x4*)(gam + col0 + BJ * HALF + n * 16) * ALPHA; bv[n] = *(const f32x4*)(bet + col0 + BJ * HALF + n * 16) * ALPHA; }
;             else { gv[n] = (f32x4){ALPHA, ALPHA, ALPHA, ALPHA}; bv[n] = (f32x4){0.f, 0.f, 0.f, 0.f}; }
;         }
;     }
;     template <bool LN> DI void run(const f32x4 (&acc)[2][2][4][2], const Unit& u, int wr, int wc, int fr, int fq) const {
;         const unsigned row0 = u.pm * BM + wr * 64 + fr, col0 = u.pn * BM + wc * 32 + 4 * fq;
;         f32x4 gv[2], bv[2];
;         load_gb<LN, 0>(col0, gv, bv);
	v_mfma_f32_16x16x32_bf16 v[92:95], v[96:99], v[152:155], v[92:95]
	v_mfma_f32_16x16x32_bf16 v[88:91], v[136:139], v[152:155], v[88:91]
	v_mfma_f32_16x16x32_bf16 v[84:87], v[96:99], v[190:193], v[84:87]
	v_mfma_f32_16x16x32_bf16 v[80:83], v[136:139], v[190:193], v[80:83]
	v_mfma_f32_16x16x32_bf16 v[76:79], v[96:99], v[202:205], v[76:79]
	v_mfma_f32_16x16x32_bf16 v[72:75], v[136:139], v[202:205], v[72:75]
	v_mfma_f32_16x16x32_bf16 v[68:71], v[96:99], v[210:213], v[68:71]
	v_mfma_f32_16x16x32_bf16 v[64:67], v[136:139], v[210:213], v[64:67]
	v_mfma_f32_16x16x32_bf16 v[92:95], v[100:103], v[186:189], v[92:95]
	v_mfma_f32_16x16x32_bf16 v[88:91], v[148:151], v[186:189], v[88:91]
	v_mfma_f32_16x16x32_bf16 v[84:87], v[100:103], v[194:197], v[84:87]
	v_mfma_f32_16x16x32_bf16 v[80:83], v[148:151], v[194:197], v[80:83]
	v_mfma_f32_16x16x32_bf16 v[76:79], v[100:103], v[206:209], v[76:79]
	v_mfma_f32_16x16x32_bf16 v[72:75], v[148:151], v[206:209], v[72:75]
	v_mfma_f32_16x16x32_bf16 v[68:71], v[100:103], v[214:217], v[68:71]
	s_setprio 0
	v_mfma_f32_16x16x32_bf16 v[64:67], v[148:151], v[214:217], v[64:67]
	s_barrier
	s_add_u32 s16, s20, 0x160080
	s_addc_u32 s17, s21, 0
	s_add_i32 s20, s22, s27
	s_mov_b32 m0, s20
	s_nop 0
	global_load_lds_dwordx4 v142, s[16:17]
	s_add_i32 m0, s20, 0x2000
	s_nop 0
	global_load_lds_dwordx4 v140, s[16:17]
	s_waitcnt vmcnt(6)
	s_setprio 1
	s_barrier
	v_mfma_f32_16x16x32_bf16 v[28:31], v[226:229], v[152:155], v[28:31]
	v_mfma_f32_16x16x32_bf16 v[24:27], v[234:237], v[152:155], v[24:27]
	v_mfma_f32_16x16x32_bf16 v[20:23], v[226:229], v[190:193], v[20:23]
	v_mfma_f32_16x16x32_bf16 v[16:19], v[234:237], v[190:193], v[16:19]
	v_mfma_f32_16x16x32_bf16 v[12:15], v[226:229], v[202:205], v[12:15]
	v_mfma_f32_16x16x32_bf16 v[8:11], v[234:237], v[202:205], v[8:11]
	v_mfma_f32_16x16x32_bf16 v[4:7], v[226:229], v[210:213], v[4:7]
	v_mfma_f32_16x16x32_bf16 v[0:3], v[234:237], v[210:213], v[0:3]
	v_mfma_f32_16x16x32_bf16 v[28:31], v[230:233], v[186:189], v[28:31]
	s_add_i32 s33, s33, 2
	v_mfma_f32_16x16x32_bf16 v[24:27], v[238:241], v[186:189], v[24:27]
	s_add_u32 s4, s4, 0x100
	v_mfma_f32_16x16x32_bf16 v[20:23], v[230:233], v[194:197], v[20:23]
	s_addc_u32 s5, s5, 0
	v_mfma_f32_16x16x32_bf16 v[16:19], v[238:241], v[194:197], v[16:19]
	s_cmpk_gt_u32 s33, 0x55
	v_mfma_f32_16x16x32_bf16 v[12:15], v[230:233], v[206:209], v[12:15]
	s_mov_b64 s[16:17], s[18:19]
	v_mfma_f32_16x16x32_bf16 v[8:11], v[238:241], v[206:209], v[8:11]
	v_mfma_f32_16x16x32_bf16 v[4:7], v[230:233], v[214:217], v[4:7]
	s_setprio 0
	v_mfma_f32_16x16x32_bf16 v[0:3], v[238:241], v[214:217], v[0:3]
	s_barrier
	s_cbranch_scc0 .LBB0_134
	v_lshl_or_b32 v158, s2, 8, v200
	v_lshlrev_b64 v[100:101], 2, v[158:159]
	v_lshl_add_u64 v[150:151], s[12:13], 0, v[100:101]
	global_load_dwordx4 v[96:99], v[150:151], off
	v_lshl_add_u64 v[152:153], s[14:15], 0, v[100:101]
	v_lshl_add_u32 v203, s3, 8, v198
	v_lshlrev_b32_e32 v202, 11, v203
	v_add_u32_e32 v148, v202, v158
	v_mov_b32_e32 v149, v159
	v_lshlrev_b32_e32 v136, 1, v203
	v_mov_b32_e32 v137, v159
	v_lshlrev_b64 v[220:221], 2, v[148:149]
	v_lshl_add_u64 v[154:155], v[136:137], 2, s[96:97]
	v_lshl_add_u64 v[136:137], s[90:91], 0, v[220:221]
	v_or_b32_e32 v204, 16, v158
	v_or_b32_e32 v138, 16, v203
	v_lshlrev_b32_e32 v149, 11, v138
	s_waitcnt vmcnt(0)
	v_pk_mul_f32 v[192:193], v[98:99], s[78:79] op_sel_hi:[1,0]
	v_pk_mul_f32 v[194:195], v[96:97], s[78:79] op_sel_hi:[1,0]
	global_load_dwordx4 v[100:103], v[152:153], off
	global_load_dwordx4 v[96:99], v[150:151], off offset:64
	global_load_dwordx2 v[218:219], v[154:155], off
	global_load_dwordx4 v[206:209], v[136:137], off
	v_add_u32_e32 v136, v202, v204
	v_mov_b32_e32 v137, v159
	v_lshl_add_u64 v[136:137], v[136:137], 2, s[90:91]
	global_load_dwordx4 v[210:213], v[136:137], off
	v_lshlrev_b32_e32 v136, 1, v138
	v_mov_b32_e32 v137, v159
	v_lshl_add_u64 v[186:187], v[136:137], 2, s[96:97]
	v_add_u32_e32 v136, v149, v158
	v_lshl_add_u64 v[136:137], v[136:137], 2, s[90:91]
	global_load_dwordx2 v[196:197], v[186:187], off
	global_load_dwordx4 v[214:217], v[136:137], off
	v_add_u32_e32 v136, v149, v204
	v_mov_b32_e32 v137, v159
	v_lshl_add_u64 v[136:137], v[136:137], 2, s[90:91]
	global_load_dwordx4 v[136:139], v[136:137], off
	s_waitcnt vmcnt(0)
	v_pk_mul_f32 v[188:189], v[98:99], s[78:79] op_sel_hi:[1,0]
	v_pk_mul_f32 v[190:191], v[96:97], s[78:79] op_sel_hi:[1,0]
	global_load_dwordx4 v[96:99], v[152:153], off offset:64
	v_sub_f32_e32 v207, v207, v218
	v_sub_f32_e32 v206, v206, v218
	v_sub_f32_e32 v209, v209, v218
	v_sub_f32_e32 v208, v208, v218
	v_pk_mul_f32 v[208:209], v[218:219], v[208:209] op_sel:[1,0]
	v_pk_mul_f32 v[206:207], v[218:219], v[206:207] op_sel:[1,0]
	v_pk_fma_f32 v[134:135], v[192:193], v[208:209], v[134:135]
	v_pk_fma_f32 v[132:133], v[194:195], v[206:207], v[132:133]
	v_pk_fma_f32 v[134:135], v[102:103], s[78:79], v[134:135] op_sel_hi:[1,0,1]
	v_pk_fma_f32 v[132:133], v[100:101], s[78:79], v[132:133] op_sel_hi:[1,0,1]
	v_lshl_add_u64 v[206:207], s[88:89], 0, v[220:221]
	global_store_dwordx4 v[206:207], v[132:135], off
	s_nop 1
	v_sub_f32_e32 v133, v211, v218
	v_sub_f32_e32 v132, v210, v218
	v_sub_f32_e32 v135, v213, v218
	v_sub_f32_e32 v134, v212, v218
	v_pk_mul_f32 v[134:135], v[218:219], v[134:135] op_sel:[1,0]
	v_pk_mul_f32 v[132:133], v[218:219], v[132:133] op_sel:[1,0]
	v_pk_fma_f32 v[130:131], v[188:189], v[134:135], v[130:131]
	v_pk_fma_f32 v[128:129], v[190:191], v[132:133], v[128:129]
	v_or_b32_e32 v132, 16, v148
	v_mov_b32_e32 v133, v159
	v_lshl_add_u64 v[132:133], v[132:133], 2, s[88:89]
	s_waitcnt vmcnt(0)
;     template <bool LN, int BJ, int LO, int HI> DI void batch(const f32x4 (&acc)[2][2][4][2], unsigned row0, unsigned col0, const f32x4 (&gv)[2], const f32x4 (&bv)[2]) const {
;         f32x4 r[HI - LO]; float mean[(HI - LO) / 2], rstd[(HI - LO) / 2];
; #pragma unroll
;         for (int i = LO; i < HI; ++i) { const int ai = i >> 3, m = (i >> 1) & 3, n = i & 1; const unsigned row = row0 + ai * HALF + m * 16;
;             if (n == 0) { mean[(i - LO) >> 1] = 0.f; rstd[(i - LO) >> 1] = 1.f;
;                 if (LN) { const float2 st = *(const float2*)(stats + row * 2u); mean[(i - LO) >> 1] = st.x; rstd[(i - LO) >> 1] = st.y; } }
;             r[i - LO] = *(const f32x4*)(src + (row * (unsigned)DM + col0 + BJ * HALF + n * 16)); }
; #pragma unroll
;         for (int i = LO; i < HI; ++i) { const int ai = i >> 3, m = (i >> 1) & 3, n = i & 1; const unsigned row = row0 + ai * HALF + m * 16;
;             *(f32x4*)(Y + (row * (unsigned)DM + col0 + BJ * HALF + n * 16)) = acc[ai][BJ][m][n] + ((r[i - LO] - mean[(i - LO) >> 1]) * rstd[(i - LO) >> 1]) * gv[n] + bv[n]; }
;         __builtin_amdgcn_sched_barrier(0);
;     }
	v_pk_fma_f32 v[130:131], v[98:99], s[78:79], v[130:131] op_sel_hi:[1,0,1]
	v_pk_fma_f32 v[128:129], v[96:97], s[78:79], v[128:129] op_sel_hi:[1,0,1]
	global_store_dwordx4 v[132:133], v[128:131], off
	s_nop 1
	v_sub_f32_e32 v129, v215, v196
	v_sub_f32_e32 v128, v214, v196
	v_sub_f32_e32 v131, v217, v196
	v_sub_f32_e32 v130, v216, v196
	v_pk_mul_f32 v[130:131], v[196:197], v[130:131] op_sel:[1,0]
	v_pk_mul_f32 v[128:129], v[196:197], v[128:129] op_sel:[1,0]
	v_pk_fma_f32 v[126:127], v[192:193], v[130:131], v[126:127]
	v_pk_fma_f32 v[124:125], v[194:195], v[128:129], v[124:125]
	v_add_u32_e32 v128, 0x8000, v148
	v_mov_b32_e32 v129, v159
	v_pk_fma_f32 v[126:127], v[102:103], s[78:79], v[126:127] op_sel_hi:[1,0,1]
	v_pk_fma_f32 v[124:125], v[100:101], s[78:79], v[124:125] op_sel_hi:[1,0,1]
	v_lshl_add_u64 v[128:129], v[128:129], 2, s[88:89]
	global_store_dwordx4 v[128:129], v[124:127], off
	s_nop 1
	v_sub_f32_e32 v125, v137, v196
	v_sub_f32_e32 v124, v136, v196
	v_sub_f32_e32 v127, v139, v196
	v_sub_f32_e32 v126, v138, v196
	v_pk_mul_f32 v[126:127], v[196:197], v[126:127] op_sel:[1,0]
	v_pk_mul_f32 v[124:125], v[196:197], v[124:125] op_sel:[1,0]
	v_pk_fma_f32 v[122:123], v[188:189], v[126:127], v[122:123]
	v_pk_fma_f32 v[120:121], v[190:191], v[124:125], v[120:121]
	v_add_u32_e32 v124, 0x8010, v148
	v_mov_b32_e32 v125, v159
	v_pk_fma_f32 v[122:123], v[98:99], s[78:79], v[122:123] op_sel_hi:[1,0,1]
	v_pk_fma_f32 v[120:121], v[96:97], s[78:79], v[120:121] op_sel_hi:[1,0,1]
	v_lshl_add_u64 v[124:125], v[124:125], 2, s[88:89]
	global_store_dwordx4 v[124:125], v[120:123], off
	s_nop 1
	v_or_b32_e32 v122, 32, v203
	v_lshlrev_b32_e32 v124, 11, v122
	v_lshlrev_b32_e32 v120, 1, v122
	v_mov_b32_e32 v121, v159
	v_add_u32_e32 v122, v124, v158
	v_mov_b32_e32 v123, v159
	v_lshl_add_u64 v[120:121], v[120:121], 2, s[96:97]
	v_lshl_add_u64 v[122:123], v[122:123], 2, s[90:91]
	global_load_dwordx2 v[138:139], v[120:121], off
	global_load_dwordx4 v[126:129], v[122:123], off
	v_add_u32_e32 v122, v124, v204
	v_mov_b32_e32 v123, v159
	v_lshl_add_u64 v[122:123], v[122:123], 2, s[90:91]
	global_load_dwordx4 v[130:133], v[122:123], off
	v_or_b32_e32 v125, 48, v203
	v_lshlrev_b32_e32 v122, 1, v125
	v_lshlrev_b32_e32 v125, 11, v125
	v_mov_b32_e32 v123, v159
	v_add_u32_e32 v134, v125, v158
	v_mov_b32_e32 v135, v159
	v_lshl_add_u64 v[122:123], v[122:123], 2, s[96:97]
	v_lshl_add_u64 v[134:135], v[134:135], 2, s[90:91]
	global_load_dwordx2 v[196:197], v[122:123], off
	v_add_u32_e32 v206, v125, v204
	global_load_dwordx4 v[134:137], v[134:135], off
	v_mov_b32_e32 v207, v159
	v_lshl_add_u64 v[206:207], v[206:207], 2, s[90:91]
	global_load_dwordx4 v[206:209], v[206:207], off
	s_waitcnt vmcnt(0)
	v_sub_f32_e32 v127, v127, v138
	v_sub_f32_e32 v126, v126, v138
	v_sub_f32_e32 v129, v129, v138
	v_sub_f32_e32 v128, v128, v138
	v_pk_mul_f32 v[128:129], v[138:139], v[128:129] op_sel:[1,0]
	v_pk_mul_f32 v[126:127], v[138:139], v[126:127] op_sel:[1,0]
	v_pk_fma_f32 v[118:119], v[192:193], v[128:129], v[118:119]
	v_pk_fma_f32 v[116:117], v[194:195], v[126:127], v[116:117]
	v_add_u32_e32 v126, 0x10000, v148
	v_mov_b32_e32 v127, v159
	v_pk_fma_f32 v[118:119], v[102:103], s[78:79], v[118:119] op_sel_hi:[1,0,1]
	v_pk_fma_f32 v[116:117], v[100:101], s[78:79], v[116:117] op_sel_hi:[1,0,1]
	v_lshl_add_u64 v[126:127], v[126:127], 2, s[88:89]
	global_store_dwordx4 v[126:127], v[116:119], off
	s_nop 1
	v_sub_f32_e32 v117, v131, v138
	v_sub_f32_e32 v116, v130, v138
	v_sub_f32_e32 v119, v133, v138
	v_sub_f32_e32 v118, v132, v138
	v_pk_mul_f32 v[118:119], v[138:139], v[118:119] op_sel:[1,0]
	v_pk_mul_f32 v[116:117], v[138:139], v[116:117] op_sel:[1,0]
	v_pk_fma_f32 v[114:115], v[188:189], v[118:119], v[114:115]
	v_pk_fma_f32 v[112:113], v[190:191], v[116:117], v[112:113]
	v_add_u32_e32 v116, 0x10010, v148
	v_mov_b32_e32 v117, v159
	v_pk_fma_f32 v[114:115], v[98:99], s[78:79], v[114:115] op_sel_hi:[1,0,1]
	v_pk_fma_f32 v[112:113], v[96:97], s[78:79], v[112:113] op_sel_hi:[1,0,1]
	v_lshl_add_u64 v[116:117], v[116:117], 2, s[88:89]
	global_store_dwordx4 v[116:117], v[112:115], off
	s_nop 1
	v_sub_f32_e32 v113, v135, v196
	v_sub_f32_e32 v112, v134, v196
	v_sub_f32_e32 v115, v137, v196
	v_sub_f32_e32 v114, v136, v196
	v_pk_mul_f32 v[114:115], v[196:197], v[114:115] op_sel:[1,0]
	v_pk_mul_f32 v[112:113], v[196:197], v[112:113] op_sel:[1,0]
	v_pk_fma_f32 v[110:111], v[192:193], v[114:115], v[110:111]
	v_pk_fma_f32 v[108:109], v[194:195], v[112:113], v[108:109]
	v_add_u32_e32 v112, 0x18000, v148
	v_mov_b32_e32 v113, v159
	v_pk_fma_f32 v[110:111], v[102:103], s[78:79], v[110:111] op_sel_hi:[1,0,1]
	v_pk_fma_f32 v[108:109], v[100:101], s[78:79], v[108:109] op_sel_hi:[1,0,1]
	v_lshl_add_u64 v[112:113], v[112:113], 2, s[88:89]
	global_store_dwordx4 v[112:113], v[108:111], off
	s_nop 1
	v_sub_f32_e32 v109, v207, v196
	v_sub_f32_e32 v108, v206, v196
	v_sub_f32_e32 v111, v209, v196
	v_sub_f32_e32 v110, v208, v196
	v_pk_mul_f32 v[110:111], v[196:197], v[110:111] op_sel:[1,0]
	v_pk_mul_f32 v[108:109], v[196:197], v[108:109] op_sel:[1,0]
	v_pk_fma_f32 v[106:107], v[188:189], v[110:111], v[106:107]
	v_pk_fma_f32 v[104:105], v[190:191], v[108:109], v[104:105]
	v_add_u32_e32 v108, 0x18010, v148
	v_mov_b32_e32 v109, v159
	v_pk_fma_f32 v[106:107], v[98:99], s[78:79], v[106:107] op_sel_hi:[1,0,1]
	v_pk_fma_f32 v[104:105], v[96:97], s[78:79], v[104:105] op_sel_hi:[1,0,1]
	v_lshl_add_u64 v[108:109], v[108:109], 2, s[88:89]
	global_store_dwordx4 v[108:109], v[104:107], off
	s_nop 1
	v_add_u32_e32 v106, 0x80, v203
	v_lshlrev_b32_e32 v114, 11, v106
	v_lshlrev_b32_e32 v104, 1, v106
	v_mov_b32_e32 v105, v159
	v_add_u32_e32 v106, v114, v158
	v_mov_b32_e32 v107, v159
	v_lshl_add_u64 v[104:105], v[104:105], 2, s[96:97]
	v_lshl_add_u64 v[106:107], v[106:107], 2, s[90:91]
	global_load_dwordx2 v[112:113], v[104:105], off
	global_load_dwordx4 v[108:111], v[106:107], off
	v_add_u32_e32 v106, v114, v204
	v_mov_b32_e32 v107, v159
	v_lshl_add_u64 v[106:107], v[106:107], 2, s[90:91]
	global_load_dwordx4 v[116:119], v[106:107], off
	v_add_u32_e32 v115, 0x90, v203
	v_lshlrev_b32_e32 v106, 1, v115
	v_lshlrev_b32_e32 v115, 11, v115
	v_mov_b32_e32 v107, v159
	v_add_u32_e32 v126, v115, v158
	v_mov_b32_e32 v127, v159
	v_lshl_add_u64 v[106:107], v[106:107], 2, s[96:97]
	v_lshl_add_u64 v[126:127], v[126:127], 2, s[90:91]
	global_load_dwordx2 v[134:135], v[106:107], off
	v_add_u32_e32 v130, v115, v204
	global_load_dwordx4 v[126:129], v[126:127], off
	v_mov_b32_e32 v131, v159
	v_lshl_add_u64 v[130:131], v[130:131], 2, s[90:91]
	global_load_dwordx4 v[130:133], v[130:131], off
	s_waitcnt vmcnt(0)
;     template <bool LN, int BJ, int LO, int HI> DI void batch(const f32x4 (&acc)[2][2][4][2], unsigned row0, unsigned col0, const f32x4 (&gv)[2], const f32x4 (&bv)[2]) const {
;         f32x4 r[HI - LO]; float mean[(HI - LO) / 2], rstd[(HI - LO) / 2];
; #pragma unroll
;         for (int i = LO; i < HI; ++i) { const int ai = i >> 3, m = (i >> 1) & 3, n = i & 1; const unsigned row = row0 + ai * HALF + m * 16;
;             if (n == 0) { mean[(i - LO) >> 1] = 0.f; rstd[(i - LO) >> 1] = 1.f;
;                 if (LN) { const float2 st = *(const float2*)(stats + row * 2u); mean[(i - LO) >> 1] = st.x; rstd[(i - LO) >> 1] = st.y; } }
;             r[i - LO] = *(const f32x4*)(src + (row * (unsigned)DM + col0 + BJ * HALF + n * 16)); }
; #pragma unroll
;         for (int i = LO; i < HI; ++i) { const int ai = i >> 3, m = (i >> 1) & 3, n = i & 1; const unsigned row = row0 + ai * HALF + m * 16;
;             *(f32x4*)(Y + (row * (unsigned)DM + col0 + BJ * HALF + n * 16)) = acc[ai][BJ][m][n] + ((r[i - LO] - mean[(i - LO) >> 1]) * rstd[(i - LO) >> 1]) * gv[n] + bv[n]; }
;         __builtin_amdgcn_sched_barrier(0);
;     }
	v_sub_f32_e32 v109, v109, v112
	v_sub_f32_e32 v108, v108, v112
	v_sub_f32_e32 v111, v111, v112
	v_sub_f32_e32 v110, v110, v112
	v_pk_mul_f32 v[110:111], v[112:113], v[110:111] op_sel:[1,0]
	v_pk_mul_f32 v[108:109], v[112:113], v[108:109] op_sel:[1,0]
	v_pk_fma_f32 v[94:95], v[192:193], v[110:111], v[94:95]
	v_pk_fma_f32 v[92:93], v[194:195], v[108:109], v[92:93]
	v_add_u32_e32 v108, 0x40000, v148
	v_mov_b32_e32 v109, v159
	v_pk_fma_f32 v[94:95], v[102:103], s[78:79], v[94:95] op_sel_hi:[1,0,1]
	v_pk_fma_f32 v[92:93], v[100:101], s[78:79], v[92:93] op_sel_hi:[1,0,1]
	v_lshl_add_u64 v[108:109], v[108:109], 2, s[88:89]
	global_store_dwordx4 v[108:109], v[92:95], off
	s_nop 1
	v_sub_f32_e32 v93, v117, v112
	v_sub_f32_e32 v92, v116, v112
	v_sub_f32_e32 v95, v119, v112
	v_sub_f32_e32 v94, v118, v112
	v_pk_mul_f32 v[94:95], v[112:113], v[94:95] op_sel:[1,0]
	v_pk_mul_f32 v[92:93], v[112:113], v[92:93] op_sel:[1,0]
	v_pk_fma_f32 v[90:91], v[188:189], v[94:95], v[90:91]
	v_pk_fma_f32 v[88:89], v[190:191], v[92:93], v[88:89]
	v_add_u32_e32 v92, 0x40010, v148
	v_mov_b32_e32 v93, v159
	v_pk_fma_f32 v[90:91], v[98:99], s[78:79], v[90:91] op_sel_hi:[1,0,1]
	v_pk_fma_f32 v[88:89], v[96:97], s[78:79], v[88:89] op_sel_hi:[1,0,1]
	v_lshl_add_u64 v[92:93], v[92:93], 2, s[88:89]
	global_store_dwordx4 v[92:93], v[88:91], off
	s_nop 1
	v_sub_f32_e32 v89, v127, v134
	v_sub_f32_e32 v88, v126, v134
	v_sub_f32_e32 v91, v129, v134
	v_sub_f32_e32 v90, v128, v134
	v_pk_mul_f32 v[90:91], v[134:135], v[90:91] op_sel:[1,0]
	v_pk_mul_f32 v[88:89], v[134:135], v[88:89] op_sel:[1,0]
	v_pk_fma_f32 v[86:87], v[192:193], v[90:91], v[86:87]
	v_pk_fma_f32 v[84:85], v[194:195], v[88:89], v[84:85]
	v_add_u32_e32 v88, 0x48000, v148
	v_mov_b32_e32 v89, v159
	v_pk_fma_f32 v[86:87], v[102:103], s[78:79], v[86:87] op_sel_hi:[1,0,1]
	v_pk_fma_f32 v[84:85], v[100:101], s[78:79], v[84:85] op_sel_hi:[1,0,1]
	v_lshl_add_u64 v[88:89], v[88:89], 2, s[88:89]
	global_store_dwordx4 v[88:89], v[84:87], off
	s_nop 1
	v_sub_f32_e32 v85, v131, v134
	v_sub_f32_e32 v84, v130, v134
	v_sub_f32_e32 v87, v133, v134
	v_sub_f32_e32 v86, v132, v134
	v_pk_mul_f32 v[86:87], v[134:135], v[86:87] op_sel:[1,0]
	v_pk_mul_f32 v[84:85], v[134:135], v[84:85] op_sel:[1,0]
	v_pk_fma_f32 v[82:83], v[188:189], v[86:87], v[82:83]
	v_pk_fma_f32 v[80:81], v[190:191], v[84:85], v[80:81]
	v_add_u32_e32 v84, 0x48010, v148
	v_mov_b32_e32 v85, v159
	v_pk_fma_f32 v[82:83], v[98:99], s[78:79], v[82:83] op_sel_hi:[1,0,1]
	v_pk_fma_f32 v[80:81], v[96:97], s[78:79], v[80:81] op_sel_hi:[1,0,1]
	v_lshl_add_u64 v[84:85], v[84:85], 2, s[88:89]
	global_store_dwordx4 v[84:85], v[80:83], off
	s_nop 1
	v_add_u32_e32 v82, 0xa0, v203
	v_lshlrev_b32_e32 v80, 1, v82
	v_mov_b32_e32 v81, v159
	v_lshlrev_b32_e32 v116, 11, v82
	v_lshl_add_u64 v[108:109], v[80:81], 2, s[96:97]
	v_add_u32_e32 v80, v116, v158
	v_lshl_add_u64 v[80:81], v[80:81], 2, s[90:91]
	global_load_dwordx2 v[112:113], v[108:109], off
	v_add_u32_e32 v84, v116, v204
	global_load_dwordx4 v[80:83], v[80:81], off
	v_mov_b32_e32 v85, v159
	v_lshl_add_u64 v[84:85], v[84:85], 2, s[90:91]
	global_load_dwordx4 v[84:87], v[84:85], off
	v_add_u32_e32 v90, 0xb0, v203
	v_lshlrev_b32_e32 v88, 1, v90
	v_mov_b32_e32 v89, v159
	v_lshlrev_b32_e32 v117, 11, v90
	v_lshl_add_u64 v[110:111], v[88:89], 2, s[96:97]
	v_add_u32_e32 v88, v117, v158
	v_lshl_add_u64 v[88:89], v[88:89], 2, s[90:91]
	global_load_dwordx2 v[118:119], v[110:111], off
	v_add_u32_e32 v92, v117, v204
	global_load_dwordx4 v[88:91], v[88:89], off
	v_mov_b32_e32 v93, v159
	v_lshl_add_u64 v[92:93], v[92:93], 2, s[90:91]
	global_load_dwordx4 v[92:95], v[92:93], off
	s_waitcnt vmcnt(0)
	v_sub_f32_e32 v81, v81, v112
	v_sub_f32_e32 v80, v80, v112
	v_sub_f32_e32 v83, v83, v112
	v_sub_f32_e32 v82, v82, v112
	v_pk_mul_f32 v[82:83], v[112:113], v[82:83] op_sel:[1,0]
	v_pk_mul_f32 v[80:81], v[112:113], v[80:81] op_sel:[1,0]
	v_pk_fma_f32 v[78:79], v[192:193], v[82:83], v[78:79]
	v_pk_fma_f32 v[76:77], v[194:195], v[80:81], v[76:77]
	v_add_u32_e32 v80, 0x50000, v148
	v_mov_b32_e32 v81, v159
	v_pk_fma_f32 v[78:79], v[102:103], s[78:79], v[78:79] op_sel_hi:[1,0,1]
	v_pk_fma_f32 v[76:77], v[100:101], s[78:79], v[76:77] op_sel_hi:[1,0,1]
	v_lshl_add_u64 v[80:81], v[80:81], 2, s[88:89]
	global_store_dwordx4 v[80:81], v[76:79], off
	s_nop 1
	v_sub_f32_e32 v77, v85, v112
	v_sub_f32_e32 v76, v84, v112
	v_sub_f32_e32 v79, v87, v112
	v_sub_f32_e32 v78, v86, v112
	v_pk_mul_f32 v[78:79], v[112:113], v[78:79] op_sel:[1,0]
	v_pk_mul_f32 v[76:77], v[112:113], v[76:77] op_sel:[1,0]
	v_pk_fma_f32 v[74:75], v[188:189], v[78:79], v[74:75]
	v_pk_fma_f32 v[72:73], v[190:191], v[76:77], v[72:73]
	v_add_u32_e32 v76, 0x50010, v148
	v_mov_b32_e32 v77, v159
	v_pk_fma_f32 v[74:75], v[98:99], s[78:79], v[74:75] op_sel_hi:[1,0,1]
	v_pk_fma_f32 v[72:73], v[96:97], s[78:79], v[72:73] op_sel_hi:[1,0,1]
	v_lshl_add_u64 v[76:77], v[76:77], 2, s[88:89]
	global_store_dwordx4 v[76:77], v[72:75], off
	s_nop 1
	v_sub_f32_e32 v73, v89, v118
	v_sub_f32_e32 v72, v88, v118
	v_sub_f32_e32 v75, v91, v118
	v_sub_f32_e32 v74, v90, v118
	v_pk_mul_f32 v[74:75], v[118:119], v[74:75] op_sel:[1,0]
	v_pk_mul_f32 v[72:73], v[118:119], v[72:73] op_sel:[1,0]
	v_pk_fma_f32 v[70:71], v[192:193], v[74:75], v[70:71]
	v_pk_fma_f32 v[68:69], v[194:195], v[72:73], v[68:69]
	v_add_u32_e32 v72, 0x58000, v148
	v_mov_b32_e32 v73, v159
	v_pk_fma_f32 v[70:71], v[102:103], s[78:79], v[70:71] op_sel_hi:[1,0,1]
	v_pk_fma_f32 v[68:69], v[100:101], s[78:79], v[68:69] op_sel_hi:[1,0,1]
	v_lshl_add_u64 v[72:73], v[72:73], 2, s[88:89]
	global_store_dwordx4 v[72:73], v[68:71], off
	s_nop 1
	v_sub_f32_e32 v69, v93, v118
	v_sub_f32_e32 v68, v92, v118
	v_sub_f32_e32 v71, v95, v118
	v_sub_f32_e32 v70, v94, v118
	v_pk_mul_f32 v[70:71], v[118:119], v[70:71] op_sel:[1,0]
	v_pk_mul_f32 v[68:69], v[118:119], v[68:69] op_sel:[1,0]
	v_pk_fma_f32 v[66:67], v[188:189], v[70:71], v[66:67]
	v_pk_fma_f32 v[64:65], v[190:191], v[68:69], v[64:65]
	v_add_u32_e32 v68, 0x58010, v148
	v_mov_b32_e32 v69, v159
	v_pk_fma_f32 v[66:67], v[98:99], s[78:79], v[66:67] op_sel_hi:[1,0,1]
	v_pk_fma_f32 v[64:65], v[96:97], s[78:79], v[64:65] op_sel_hi:[1,0,1]
	v_lshl_add_u64 v[68:69], v[68:69], 2, s[88:89]
	global_store_dwordx4 v[68:69], v[64:67], off
	global_load_dwordx4 v[64:67], v[150:151], off offset:512
	v_or_b32_e32 v119, 0x80, v158
	v_add_u32_e32 v72, v202, v119
	v_mov_b32_e32 v73, v159
	v_lshl_add_u64 v[72:73], v[72:73], 2, s[90:91]
	v_or_b32_e32 v118, 0x90, v158
	v_add_u32_e32 v158, v202, v118
	s_waitcnt vmcnt(0)
;     template <bool LN, int BJ, int LO, int HI> DI void batch(const f32x4 (&acc)[2][2][4][2], unsigned row0, unsigned col0, const f32x4 (&gv)[2], const f32x4 (&bv)[2]) const {
;         f32x4 r[HI - LO]; float mean[(HI - LO) / 2], rstd[(HI - LO) / 2];
; #pragma unroll
;         for (int i = LO; i < HI; ++i) { const int ai = i >> 3, m = (i >> 1) & 3, n = i & 1; const unsigned row = row0 + ai * HALF + m * 16;
;             if (n == 0) { mean[(i - LO) >> 1] = 0.f; rstd[(i - LO) >> 1] = 1.f;
;                 if (LN) { const float2 st = *(const float2*)(stats + row * 2u); mean[(i - LO) >> 1] = st.x; rstd[(i - LO) >> 1] = st.y; } }
;             r[i - LO] = *(const f32x4*)(src + (row * (unsigned)DM + col0 + BJ * HALF + n * 16)); }
; #pragma unroll
;         for (int i = LO; i < HI; ++i) { const int ai = i >> 3, m = (i >> 1) & 3, n = i & 1; const unsigned row = row0 + ai * HALF + m * 16;
;             *(f32x4*)(Y + (row * (unsigned)DM + col0 + BJ * HALF + n * 16)) = acc[ai][BJ][m][n] + ((r[i - LO] - mean[(i - LO) >> 1]) * rstd[(i - LO) >> 1]) * gv[n] + bv[n]; }
;         __builtin_amdgcn_sched_barrier(0);
;     }
;     template <bool LN> DI void run(const f32x4 (&acc)[2][2][4][2], const Unit& u, int wr, int wc, int fr, int fq) const {
;     ...
;         load_gb<LN, 1>(col0, gv, bv);
;         batch<LN, 1, 0, 8>(acc, row0, col0, gv, bv);
	v_pk_mul_f32 v[96:97], v[66:67], s[78:79] op_sel_hi:[1,0]
	v_pk_mul_f32 v[98:99], v[64:65], s[78:79] op_sel_hi:[1,0]
	global_load_dwordx4 v[68:71], v[152:153], off offset:512
	global_load_dwordx4 v[64:67], v[150:151], off offset:576
	global_load_dwordx2 v[138:139], v[154:155], off
	global_load_dwordx4 v[126:129], v[72:73], off
	v_lshl_add_u64 v[72:73], v[158:159], 2, s[90:91]
	v_add_u32_e32 v158, v149, v119
	s_waitcnt vmcnt(0)
	v_pk_mul_f32 v[92:93], v[66:67], s[78:79] op_sel_hi:[1,0]
	v_pk_mul_f32 v[94:95], v[64:65], s[78:79] op_sel_hi:[1,0]
	global_load_dwordx4 v[64:67], v[152:153], off offset:576
	global_load_dwordx4 v[130:133], v[72:73], off
	global_load_dwordx2 v[112:113], v[186:187], off
	v_lshl_add_u64 v[72:73], v[158:159], 2, s[90:91]
	global_load_dwordx4 v[134:137], v[72:73], off
	v_add_u32_e32 v158, v149, v118
	v_lshl_add_u64 v[72:73], v[158:159], 2, s[90:91]
	global_load_dwordx4 v[88:91], v[72:73], off
	global_load_dwordx2 v[102:103], v[120:121], off
	v_add_u32_e32 v158, v124, v119
	v_lshl_add_u64 v[72:73], v[158:159], 2, s[90:91]
	global_load_dwordx4 v[84:87], v[72:73], off
	v_add_u32_e32 v158, v124, v118
	v_lshl_add_u64 v[72:73], v[158:159], 2, s[90:91]
	global_load_dwordx4 v[80:83], v[72:73], off
	global_load_dwordx2 v[100:101], v[122:123], off
	v_add_u32_e32 v158, v125, v119
	v_lshl_add_u64 v[72:73], v[158:159], 2, s[90:91]
	global_load_dwordx4 v[76:79], v[72:73], off
	v_add_u32_e32 v158, v125, v118
	v_lshl_add_u64 v[72:73], v[158:159], 2, s[90:91]
	global_load_dwordx4 v[72:75], v[72:73], off
	v_sub_f32_e32 v121, v127, v138
	v_sub_f32_e32 v120, v126, v138
	v_sub_f32_e32 v123, v129, v138
	v_sub_f32_e32 v122, v128, v138
	v_pk_mul_f32 v[122:123], v[138:139], v[122:123] op_sel:[1,0]
	v_pk_mul_f32 v[120:121], v[138:139], v[120:121] op_sel:[1,0]
	v_or_b32_e32 v158, 0x80, v148
	v_pk_fma_f32 v[60:61], v[98:99], v[120:121], v[60:61]
	v_pk_fma_f32 v[62:63], v[96:97], v[122:123], v[62:63]
	v_pk_fma_f32 v[60:61], v[68:69], s[78:79], v[60:61] op_sel_hi:[1,0,1]
	v_pk_fma_f32 v[62:63], v[70:71], s[78:79], v[62:63] op_sel_hi:[1,0,1]
	v_lshl_add_u64 v[120:121], v[158:159], 2, s[88:89]
	global_store_dwordx4 v[120:121], v[60:63], off
	v_or_b32_e32 v158, 0x90, v148
	s_waitcnt vmcnt(0)
	v_sub_f32_e32 v61, v131, v138
	v_sub_f32_e32 v60, v130, v138
	v_sub_f32_e32 v63, v133, v138
	v_sub_f32_e32 v62, v132, v138
	v_pk_mul_f32 v[62:63], v[138:139], v[62:63] op_sel:[1,0]
	v_pk_mul_f32 v[60:61], v[138:139], v[60:61] op_sel:[1,0]
	v_pk_fma_f32 v[58:59], v[92:93], v[62:63], v[58:59]
	v_pk_fma_f32 v[56:57], v[94:95], v[60:61], v[56:57]
	v_pk_fma_f32 v[58:59], v[66:67], s[78:79], v[58:59] op_sel_hi:[1,0,1]
	v_pk_fma_f32 v[56:57], v[64:65], s[78:79], v[56:57] op_sel_hi:[1,0,1]
	v_lshl_add_u64 v[60:61], v[158:159], 2, s[88:89]
	global_store_dwordx4 v[60:61], v[56:59], off
	v_add_u32_e32 v158, 0x8080, v148
	s_nop 0
	v_sub_f32_e32 v57, v135, v112
	v_sub_f32_e32 v56, v134, v112
	v_sub_f32_e32 v59, v137, v112
	v_sub_f32_e32 v58, v136, v112
	v_pk_mul_f32 v[58:59], v[112:113], v[58:59] op_sel:[1,0]
	v_pk_mul_f32 v[56:57], v[112:113], v[56:57] op_sel:[1,0]
	v_pk_fma_f32 v[54:55], v[96:97], v[58:59], v[54:55]
	v_pk_fma_f32 v[52:53], v[98:99], v[56:57], v[52:53]
	v_pk_fma_f32 v[54:55], v[70:71], s[78:79], v[54:55] op_sel_hi:[1,0,1]
	v_pk_fma_f32 v[52:53], v[68:69], s[78:79], v[52:53] op_sel_hi:[1,0,1]
	v_lshl_add_u64 v[56:57], v[158:159], 2, s[88:89]
	global_store_dwordx4 v[56:57], v[52:55], off
	v_add_u32_e32 v158, 0x8090, v148
	s_nop 0
	v_sub_f32_e32 v53, v89, v112
	v_sub_f32_e32 v52, v88, v112
	v_sub_f32_e32 v55, v91, v112
	v_sub_f32_e32 v54, v90, v112
	v_pk_mul_f32 v[54:55], v[112:113], v[54:55] op_sel:[1,0]
	v_pk_mul_f32 v[52:53], v[112:113], v[52:53] op_sel:[1,0]
	v_pk_fma_f32 v[50:51], v[92:93], v[54:55], v[50:51]
	v_pk_fma_f32 v[48:49], v[94:95], v[52:53], v[48:49]
	v_pk_fma_f32 v[50:51], v[66:67], s[78:79], v[50:51] op_sel_hi:[1,0,1]
	v_pk_fma_f32 v[48:49], v[64:65], s[78:79], v[48:49] op_sel_hi:[1,0,1]
	v_lshl_add_u64 v[52:53], v[158:159], 2, s[88:89]
	global_store_dwordx4 v[52:53], v[48:51], off
	v_add_u32_e32 v158, 0x10080, v148
	s_nop 0
	v_sub_f32_e32 v49, v85, v102
	v_sub_f32_e32 v48, v84, v102
	v_sub_f32_e32 v51, v87, v102
	v_sub_f32_e32 v50, v86, v102
	v_pk_mul_f32 v[50:51], v[102:103], v[50:51] op_sel:[1,0]
	v_pk_mul_f32 v[48:49], v[102:103], v[48:49] op_sel:[1,0]
	v_pk_fma_f32 v[46:47], v[96:97], v[50:51], v[46:47]
	v_pk_fma_f32 v[44:45], v[98:99], v[48:49], v[44:45]
	v_pk_fma_f32 v[46:47], v[70:71], s[78:79], v[46:47] op_sel_hi:[1,0,1]
	v_pk_fma_f32 v[44:45], v[68:69], s[78:79], v[44:45] op_sel_hi:[1,0,1]
	v_lshl_add_u64 v[48:49], v[158:159], 2, s[88:89]
	global_store_dwordx4 v[48:49], v[44:47], off
	v_add_u32_e32 v158, 0x10090, v148
	s_nop 0
	v_sub_f32_e32 v45, v81, v102
	v_sub_f32_e32 v44, v80, v102
	v_sub_f32_e32 v47, v83, v102
	v_sub_f32_e32 v46, v82, v102
	v_pk_mul_f32 v[46:47], v[102:103], v[46:47] op_sel:[1,0]
	v_pk_mul_f32 v[44:45], v[102:103], v[44:45] op_sel:[1,0]
	v_pk_fma_f32 v[42:43], v[92:93], v[46:47], v[42:43]
	v_pk_fma_f32 v[40:41], v[94:95], v[44:45], v[40:41]
	v_pk_fma_f32 v[42:43], v[66:67], s[78:79], v[42:43] op_sel_hi:[1,0,1]
	v_pk_fma_f32 v[40:41], v[64:65], s[78:79], v[40:41] op_sel_hi:[1,0,1]
	v_lshl_add_u64 v[44:45], v[158:159], 2, s[88:89]
	global_store_dwordx4 v[44:45], v[40:43], off
	v_add_u32_e32 v158, 0x18080, v148
	s_nop 0
	v_sub_f32_e32 v41, v77, v100
	v_sub_f32_e32 v40, v76, v100
	v_sub_f32_e32 v43, v79, v100
	v_sub_f32_e32 v42, v78, v100
	v_pk_mul_f32 v[42:43], v[100:101], v[42:43] op_sel:[1,0]
	v_pk_mul_f32 v[40:41], v[100:101], v[40:41] op_sel:[1,0]
	v_pk_fma_f32 v[38:39], v[96:97], v[42:43], v[38:39]
;     template <bool LN, int BJ, int LO, int HI> DI void batch(const f32x4 (&acc)[2][2][4][2], unsigned row0, unsigned col0, const f32x4 (&gv)[2], const f32x4 (&bv)[2]) const {
;         f32x4 r[HI - LO]; float mean[(HI - LO) / 2], rstd[(HI - LO) / 2];
; #pragma unroll
;         for (int i = LO; i < HI; ++i) { const int ai = i >> 3, m = (i >> 1) & 3, n = i & 1; const unsigned row = row0 + ai * HALF + m * 16;
;             if (n == 0) { mean[(i - LO) >> 1] = 0.f; rstd[(i - LO) >> 1] = 1.f;
;                 if (LN) { const float2 st = *(const float2*)(stats + row * 2u); mean[(i - LO) >> 1] = st.x; rstd[(i - LO) >> 1] = st.y; } }
;             r[i - LO] = *(const f32x4*)(src + (row * (unsigned)DM + col0 + BJ * HALF + n * 16)); }
; #pragma unroll
;         for (int i = LO; i < HI; ++i) { const int ai = i >> 3, m = (i >> 1) & 3, n = i & 1; const unsigned row = row0 + ai * HALF + m * 16;
;             *(f32x4*)(Y + (row * (unsigned)DM + col0 + BJ * HALF + n * 16)) = acc[ai][BJ][m][n] + ((r[i - LO] - mean[(i - LO) >> 1]) * rstd[(i - LO) >> 1]) * gv[n] + bv[n]; }
;         __builtin_amdgcn_sched_barrier(0);
;     }
	v_pk_fma_f32 v[36:37], v[98:99], v[40:41], v[36:37]
	v_pk_fma_f32 v[38:39], v[70:71], s[78:79], v[38:39] op_sel_hi:[1,0,1]
	v_pk_fma_f32 v[36:37], v[68:69], s[78:79], v[36:37] op_sel_hi:[1,0,1]
	v_lshl_add_u64 v[40:41], v[158:159], 2, s[88:89]
	global_store_dwordx4 v[40:41], v[36:39], off
	v_add_u32_e32 v158, 0x18090, v148
	s_nop 0
	v_sub_f32_e32 v37, v73, v100
	v_sub_f32_e32 v36, v72, v100
	v_sub_f32_e32 v39, v75, v100
	v_sub_f32_e32 v38, v74, v100
	v_pk_mul_f32 v[38:39], v[100:101], v[38:39] op_sel:[1,0]
	v_pk_mul_f32 v[36:37], v[100:101], v[36:37] op_sel:[1,0]
	v_pk_fma_f32 v[34:35], v[92:93], v[38:39], v[34:35]
	v_pk_fma_f32 v[32:33], v[94:95], v[36:37], v[32:33]
	v_pk_fma_f32 v[34:35], v[66:67], s[78:79], v[34:35] op_sel_hi:[1,0,1]
	v_pk_fma_f32 v[32:33], v[64:65], s[78:79], v[32:33] op_sel_hi:[1,0,1]
	v_lshl_add_u64 v[36:37], v[158:159], 2, s[88:89]
	global_store_dwordx4 v[36:37], v[32:35], off
	v_add_u32_e32 v158, v114, v119
	s_nop 0
	v_lshl_add_u64 v[32:33], v[158:159], 2, s[90:91]
	global_load_dwordx2 v[62:63], v[104:105], off
	global_load_dwordx4 v[54:57], v[32:33], off
	v_add_u32_e32 v158, v114, v118
	v_lshl_add_u64 v[32:33], v[158:159], 2, s[90:91]
	global_load_dwordx4 v[58:61], v[32:33], off
	global_load_dwordx2 v[52:53], v[106:107], off
	v_add_u32_e32 v158, v115, v119
	v_lshl_add_u64 v[32:33], v[158:159], 2, s[90:91]
	global_load_dwordx4 v[72:75], v[32:33], off
	v_add_u32_e32 v158, v115, v118
	v_lshl_add_u64 v[32:33], v[158:159], 2, s[90:91]
	global_load_dwordx4 v[76:79], v[32:33], off
	global_load_dwordx2 v[50:51], v[108:109], off
	v_add_u32_e32 v158, v116, v119
	v_lshl_add_u64 v[32:33], v[158:159], 2, s[90:91]
	global_load_dwordx4 v[44:47], v[32:33], off
	v_add_u32_e32 v158, v116, v118
	v_lshl_add_u64 v[32:33], v[158:159], 2, s[90:91]
	global_load_dwordx4 v[40:43], v[32:33], off
	global_load_dwordx2 v[48:49], v[110:111], off
	v_add_u32_e32 v158, v117, v119
	v_lshl_add_u64 v[32:33], v[158:159], 2, s[90:91]
	global_load_dwordx4 v[36:39], v[32:33], off
	v_add_u32_e32 v158, v117, v118
	v_lshl_add_u64 v[32:33], v[158:159], 2, s[90:91]
	global_load_dwordx4 v[32:35], v[32:33], off
	v_add_u32_e32 v158, 0x40080, v148
	s_waitcnt vmcnt(0)
; #define PG8_WAIT_V(n) asm volatile("s_waitcnt vmcnt(" #n ")" ::: "memory")
; #define PG8_BAR __builtin_amdgcn_s_barrier()
; template <class Epi>
; DI void gemm_phase(LAS unsigned char* lds, const Gemm g, const StaticOrder& S, const Epi& E) {
;     ...
;         E(acc, cur, wr, wc, fr, fq);
;         if (!has_next) break;
; #pragma unroll
;         for (int a = 0; a < 2; ++a)
; #pragma unroll
;             for (int b = 0; b < 2; ++b)
; #pragma unroll
;                 for (int m = 0; m < 4; ++m)
; #pragma unroll
;                     for (int n = 0; n < 2; ++n) acc[a][b][m][n] = (f32x4){0.f, 0.f, 0.f, 0.f};
;         cur = nxt; cA = nA; cB = nB; ++ui;
;     }
;     PG8_WAIT_V(0);
;     if (wr == 0) PG8_BAR;
;     template <bool LN, int BJ, int LO, int HI> DI void batch(const f32x4 (&acc)[2][2][4][2], unsigned row0, unsigned col0, const f32x4 (&gv)[2], const f32x4 (&bv)[2]) const {
;         f32x4 r[HI - LO]; float mean[(HI - LO) / 2], rstd[(HI - LO) / 2];
; #pragma unroll
;         for (int i = LO; i < HI; ++i) { const int ai = i >> 3, m = (i >> 1) & 3, n = i & 1; const unsigned row = row0 + ai * HALF + m * 16;
;             if (n == 0) { mean[(i - LO) >> 1] = 0.f; rstd[(i - LO) >> 1] = 1.f;
;                 if (LN) { const float2 st = *(const float2*)(stats + row * 2u); mean[(i - LO) >> 1] = st.x; rstd[(i - LO) >> 1] = st.y; } }
;             r[i - LO] = *(const f32x4*)(src + (row * (unsigned)DM + col0 + BJ * HALF + n * 16)); }
; #pragma unroll
;         for (int i = LO; i < HI; ++i) { const int ai = i >> 3, m = (i >> 1) & 3, n = i & 1; const unsigned row = row0 + ai * HALF + m * 16;
;             *(f32x4*)(Y + (row * (unsigned)DM + col0 + BJ * HALF + n * 16)) = acc[ai][BJ][m][n] + ((r[i - LO] - mean[(i - LO) >> 1]) * rstd[(i - LO) >> 1]) * gv[n] + bv[n]; }
;         __builtin_amdgcn_sched_barrier(0);
;     }
	v_sub_f32_e32 v55, v55, v62
	v_sub_f32_e32 v54, v54, v62
	v_sub_f32_e32 v57, v57, v62
	v_sub_f32_e32 v56, v56, v62
	v_pk_mul_f32 v[56:57], v[62:63], v[56:57] op_sel:[1,0]
	v_pk_mul_f32 v[54:55], v[62:63], v[54:55] op_sel:[1,0]
	v_pk_fma_f32 v[30:31], v[96:97], v[56:57], v[30:31]
	v_pk_fma_f32 v[28:29], v[98:99], v[54:55], v[28:29]
	v_pk_fma_f32 v[30:31], v[70:71], s[78:79], v[30:31] op_sel_hi:[1,0,1]
	v_pk_fma_f32 v[28:29], v[68:69], s[78:79], v[28:29] op_sel_hi:[1,0,1]
	v_lshl_add_u64 v[54:55], v[158:159], 2, s[88:89]
	global_store_dwordx4 v[54:55], v[28:31], off
	v_add_u32_e32 v158, 0x40090, v148
	s_nop 0
	v_sub_f32_e32 v29, v59, v62
	v_sub_f32_e32 v28, v58, v62
	v_sub_f32_e32 v31, v61, v62
	v_sub_f32_e32 v30, v60, v62
	v_pk_mul_f32 v[30:31], v[62:63], v[30:31] op_sel:[1,0]
	v_pk_mul_f32 v[28:29], v[62:63], v[28:29] op_sel:[1,0]
	v_pk_fma_f32 v[26:27], v[92:93], v[30:31], v[26:27]
	v_pk_fma_f32 v[24:25], v[94:95], v[28:29], v[24:25]
	v_pk_fma_f32 v[26:27], v[66:67], s[78:79], v[26:27] op_sel_hi:[1,0,1]
	v_pk_fma_f32 v[24:25], v[64:65], s[78:79], v[24:25] op_sel_hi:[1,0,1]
	v_lshl_add_u64 v[28:29], v[158:159], 2, s[88:89]
	global_store_dwordx4 v[28:29], v[24:27], off
	v_add_u32_e32 v158, 0x48080, v148
	s_nop 0
	v_sub_f32_e32 v25, v73, v52
	v_sub_f32_e32 v24, v72, v52
	v_sub_f32_e32 v27, v75, v52
	v_sub_f32_e32 v26, v74, v52
	v_pk_mul_f32 v[26:27], v[52:53], v[26:27] op_sel:[1,0]
	v_pk_mul_f32 v[24:25], v[52:53], v[24:25] op_sel:[1,0]
	v_pk_fma_f32 v[22:23], v[96:97], v[26:27], v[22:23]
	v_pk_fma_f32 v[20:21], v[98:99], v[24:25], v[20:21]
	v_pk_fma_f32 v[22:23], v[70:71], s[78:79], v[22:23] op_sel_hi:[1,0,1]
	v_pk_fma_f32 v[20:21], v[68:69], s[78:79], v[20:21] op_sel_hi:[1,0,1]
	v_lshl_add_u64 v[24:25], v[158:159], 2, s[88:89]
	global_store_dwordx4 v[24:25], v[20:23], off
	v_add_u32_e32 v158, 0x48090, v148
	s_nop 0
	v_sub_f32_e32 v21, v77, v52
	v_sub_f32_e32 v20, v76, v52
	v_sub_f32_e32 v23, v79, v52
	v_sub_f32_e32 v22, v78, v52
	v_pk_mul_f32 v[22:23], v[52:53], v[22:23] op_sel:[1,0]
	v_pk_mul_f32 v[20:21], v[52:53], v[20:21] op_sel:[1,0]
	v_pk_fma_f32 v[18:19], v[92:93], v[22:23], v[18:19]
	v_pk_fma_f32 v[16:17], v[94:95], v[20:21], v[16:17]
	v_pk_fma_f32 v[18:19], v[66:67], s[78:79], v[18:19] op_sel_hi:[1,0,1]
	v_pk_fma_f32 v[16:17], v[64:65], s[78:79], v[16:17] op_sel_hi:[1,0,1]
	v_lshl_add_u64 v[20:21], v[158:159], 2, s[88:89]
	global_store_dwordx4 v[20:21], v[16:19], off
	v_add_u32_e32 v158, 0x50080, v148
	s_nop 0
	v_sub_f32_e32 v17, v45, v50
	v_sub_f32_e32 v16, v44, v50
	v_sub_f32_e32 v19, v47, v50
	v_sub_f32_e32 v18, v46, v50
	v_pk_mul_f32 v[18:19], v[50:51], v[18:19] op_sel:[1,0]
	v_pk_mul_f32 v[16:17], v[50:51], v[16:17] op_sel:[1,0]
	v_pk_fma_f32 v[14:15], v[96:97], v[18:19], v[14:15]
	v_pk_fma_f32 v[12:13], v[98:99], v[16:17], v[12:13]
	v_pk_fma_f32 v[14:15], v[70:71], s[78:79], v[14:15] op_sel_hi:[1,0,1]
	v_pk_fma_f32 v[12:13], v[68:69], s[78:79], v[12:13] op_sel_hi:[1,0,1]
	v_lshl_add_u64 v[16:17], v[158:159], 2, s[88:89]
	global_store_dwordx4 v[16:17], v[12:15], off
	v_add_u32_e32 v158, 0x50090, v148
	s_nop 0
	v_sub_f32_e32 v13, v41, v50
	v_sub_f32_e32 v12, v40, v50
	v_sub_f32_e32 v15, v43, v50
	v_sub_f32_e32 v14, v42, v50
	v_pk_mul_f32 v[14:15], v[50:51], v[14:15] op_sel:[1,0]
	v_pk_mul_f32 v[12:13], v[50:51], v[12:13] op_sel:[1,0]
	v_pk_fma_f32 v[10:11], v[92:93], v[14:15], v[10:11]
	v_pk_fma_f32 v[8:9], v[94:95], v[12:13], v[8:9]
	v_pk_fma_f32 v[10:11], v[66:67], s[78:79], v[10:11] op_sel_hi:[1,0,1]
	v_pk_fma_f32 v[8:9], v[64:65], s[78:79], v[8:9] op_sel_hi:[1,0,1]
	v_lshl_add_u64 v[12:13], v[158:159], 2, s[88:89]
	global_store_dwordx4 v[12:13], v[8:11], off
	v_add_u32_e32 v158, 0x58080, v148
	s_nop 0
	v_sub_f32_e32 v9, v37, v48
	v_sub_f32_e32 v8, v36, v48
	v_sub_f32_e32 v11, v39, v48
	v_sub_f32_e32 v10, v38, v48
	v_pk_mul_f32 v[10:11], v[48:49], v[10:11] op_sel:[1,0]
	v_pk_mul_f32 v[8:9], v[48:49], v[8:9] op_sel:[1,0]
	v_pk_fma_f32 v[6:7], v[96:97], v[10:11], v[6:7]
	v_pk_fma_f32 v[4:5], v[98:99], v[8:9], v[4:5]
	v_pk_fma_f32 v[6:7], v[70:71], s[78:79], v[6:7] op_sel_hi:[1,0,1]
	v_pk_fma_f32 v[4:5], v[68:69], s[78:79], v[4:5] op_sel_hi:[1,0,1]
	v_lshl_add_u64 v[8:9], v[158:159], 2, s[88:89]
	global_store_dwordx4 v[8:9], v[4:7], off
	v_add_u32_e32 v158, 0x58090, v148
	s_nop 0
	v_sub_f32_e32 v5, v33, v48
	v_sub_f32_e32 v4, v32, v48
	v_sub_f32_e32 v7, v35, v48
	v_sub_f32_e32 v6, v34, v48
	v_pk_mul_f32 v[6:7], v[48:49], v[6:7] op_sel:[1,0]
	v_pk_mul_f32 v[4:5], v[48:49], v[4:5] op_sel:[1,0]
	v_pk_fma_f32 v[2:3], v[92:93], v[6:7], v[2:3]
	v_pk_fma_f32 v[0:1], v[94:95], v[4:5], v[0:1]
	v_pk_fma_f32 v[2:3], v[66:67], s[78:79], v[2:3] op_sel_hi:[1,0,1]
	v_pk_fma_f32 v[0:1], v[64:65], s[78:79], v[0:1] op_sel_hi:[1,0,1]
	v_lshl_add_u64 v[4:5], v[158:159], 2, s[88:89]
	global_store_dwordx4 v[4:5], v[0:3], off
	s_and_b64 vcc, exec, s[6:7]
	s_mov_b32 s2, s37
	s_mov_b32 s3, s38
	s_mov_b64 s[18:19], s[10:11]
	s_mov_b64 s[16:17], s[8:9]
	v_readlane_b32 s33, v255, 39
	s_cbranch_vccz .LBB0_123
	s_waitcnt vmcnt(0)
	s_cmpk_gt_u32 s24, 0xff
	s_cbranch_scc1 .LBB0_138
	s_barrier

; #define PG8_STAGE(bufoff, gbase) do { _Pragma("unroll") for (int _i = 0; _i < 2; ++_i) \
;         __builtin_amdgcn_global_load_lds((const unsigned*)((const char*)(gbase) + voff[_i]), (LAS unsigned*)(lds + (bufoff) + ldsw + _i * 8192), 16, 0, 0); } while (0)
; #define PG8_LDA(dst, b, h) do { _Pragma("unroll") for (int m = 0; m < 4; ++m) _Pragma("unroll") for (int k = 0; k < 2; ++k) dst[m][k] = *(const LAS bf16x8*)(lds + PG8_SA(b, h) + aoff + m * 2048 + k * 1024); } while (0)
; #define PG8_LDB(dst, b, h) do { _Pragma("unroll") for (int n = 0; n < 2; ++n) _Pragma("unroll") for (int k = 0; k < 2; ++k) dst[n][k] = *(const LAS bf16x8*)(lds + PG8_SB(b, h) + boff + n * 2048 + k * 1024); } while (0)
; #define PG8_MMA(ai, bj, At, Bt) do { __builtin_amdgcn_s_setprio(1); _Pragma("unroll") for (int m = 0; m < 4; ++m) _Pragma("unroll") for (int n = 0; n < 2; ++n) _Pragma("unroll") for (int k = 0; k < 2; ++k) \
;         acc[ai][bj][m][n] = __builtin_amdgcn_mfma_f32_16x16x32_bf16(Bt[n][k], At[m][k], acc[ai][bj][m][n], 0, 0, 0); __builtin_amdgcn_s_setprio(0); } while (0)
; #define PG8_WAIT_V(n) asm volatile("s_waitcnt vmcnt(" #n ")" ::: "memory")
; #define PG8_WAIT_L(n) asm volatile("s_waitcnt lgkmcnt(" #n ")" ::: "memory")
; #define PG8_BAR __builtin_amdgcn_s_barrier()
; #define PG8_SCHED __builtin_amdgcn_sched_barrier(0)
; template <class Epi>
; DI void gemm_phase(LAS unsigned char* lds, const Gemm g, const StaticOrder& S, const Epi& E) {
;     ...
;             const bool last = (t == nt - 2);
;             const char* a1 = cA + (size_t)(t + 1) * kstep;
;             const char* a2 = last ? nA : cA + (size_t)(t + 2) * kstep; const char* b2 = last ? nB : cB + (size_t)(t + 2) * kstep;
;             const char* a3 = a2 + kstep; const char* b3 = b2 + kstep;
;             PG8_LDB(B0, 0, 0); PG8_SCHED; PG8_LDA(At, 0, 0); PG8_STAGE(PG8_SA(1, 1), a1 + hstep);
;             PG8_WAIT_L(8); PG8_BAR; PG8_WAIT_L(0); PG8_MMA(0, 0, At, B0); PG8_BAR; PG8_SCHED;
;             PG8_LDB(B1, 0, 1); PG8_STAGE(PG8_SB(0, 0), b2);
;             PG8_BAR; PG8_WAIT_L(0); PG8_MMA(0, 1, At, B1); PG8_BAR;
;             PG8_LDA(At, 0, 1); PG8_STAGE(PG8_SA(0, 0), a2);
;             PG8_BAR; PG8_WAIT_L(0); PG8_MMA(1, 0, At, B0); PG8_BAR; PG8_SCHED;
;             PG8_STAGE(PG8_SB(0, 1), b2 + hstep);
;             PG8_WAIT_V(6); PG8_BAR; PG8_MMA(1, 1, At, B1); PG8_BAR;
.LBB0_202:
	s_add_u32 s18, s8, 0xfff80080
	s_addc_u32 s19, s9, -1
	s_add_i32 s37, 0, 0x10000
	s_waitcnt lgkmcnt(0)
	ds_read_b128 v[128:131], v187
	ds_read_b128 v[132:135], v187 offset:1024
	ds_read_b128 v[136:139], v187 offset:2048
	ds_read_b128 v[190:193], v187 offset:3072
	s_cmp_eq_u32 s36, 28
	s_cselect_b32 s21, s4, s19
	s_cselect_b32 s20, s5, s18
	s_cselect_b32 s19, s11, s35
	s_cselect_b32 s18, s13, s33
	s_add_i32 m0, s26, 0xc000
	ds_read_b128 v[194:197], v189
	ds_read_b128 v[198:201], v189 offset:1024
	ds_read_b128 v[202:205], v189 offset:2048
	ds_read_b128 v[206:209], v189 offset:3072
	ds_read_b128 v[210:213], v189 offset:4096
	ds_read_b128 v[214:217], v189 offset:5120
	ds_read_b128 v[226:229], v189 offset:6144
	ds_read_b128 v[230:233], v189 offset:7168
	global_load_lds_dwordx4 v150, s[8:9]
	s_add_i32 m0, s26, 0xe000
	s_nop 0
	global_load_lds_dwordx4 v152, s[8:9]
	s_waitcnt lgkmcnt(0)
	s_setprio 1
	s_barrier
	v_mfma_f32_16x16x32_bf16 v[124:127], v[128:131], v[194:197], v[124:127]
	v_mfma_f32_16x16x32_bf16 v[120:123], v[136:139], v[194:197], v[120:123]
	v_mfma_f32_16x16x32_bf16 v[108:111], v[128:131], v[202:205], v[108:111]
	v_mfma_f32_16x16x32_bf16 v[104:107], v[136:139], v[202:205], v[104:107]
	v_mfma_f32_16x16x32_bf16 v[92:95], v[128:131], v[210:213], v[92:95]
	v_mfma_f32_16x16x32_bf16 v[88:91], v[136:139], v[210:213], v[88:91]
	v_mfma_f32_16x16x32_bf16 v[76:79], v[128:131], v[226:229], v[76:79]
	v_mfma_f32_16x16x32_bf16 v[72:75], v[136:139], v[226:229], v[72:75]
	v_mfma_f32_16x16x32_bf16 v[124:127], v[132:135], v[198:201], v[124:127]
	v_mfma_f32_16x16x32_bf16 v[120:123], v[190:193], v[198:201], v[120:123]
	v_mfma_f32_16x16x32_bf16 v[108:111], v[132:135], v[206:209], v[108:111]
	v_mfma_f32_16x16x32_bf16 v[104:107], v[190:193], v[206:209], v[104:107]
	v_mfma_f32_16x16x32_bf16 v[92:95], v[132:135], v[214:217], v[92:95]
	v_mfma_f32_16x16x32_bf16 v[88:91], v[190:193], v[214:217], v[88:91]
	v_mfma_f32_16x16x32_bf16 v[76:79], v[132:135], v[230:233], v[76:79]
	s_setprio 0
	v_mfma_f32_16x16x32_bf16 v[72:75], v[190:193], v[230:233], v[72:75]
	s_barrier
	ds_read_b128 v[234:237], v187 offset:16384
	ds_read_b128 v[238:241], v187 offset:17408
	ds_read_b128 v[242:245], v187 offset:18432
	ds_read_b128 v[246:249], v187 offset:19456
	s_add_i32 s40, 0, 0x14000
	s_add_i32 s37, s37, s25
	s_mov_b32 m0, s37
	s_nop 0
	global_load_lds_dwordx4 v144, s[18:19]
	s_add_i32 m0, s37, 0x2000
	s_nop 0
	global_load_lds_dwordx4 v142, s[18:19]
	s_waitcnt lgkmcnt(0)
	s_setprio 1
	s_barrier
	v_mfma_f32_16x16x32_bf16 v[116:119], v[234:237], v[194:197], v[116:119]
	v_mfma_f32_16x16x32_bf16 v[112:115], v[242:245], v[194:197], v[112:115]
	v_mfma_f32_16x16x32_bf16 v[100:103], v[234:237], v[202:205], v[100:103]
	v_mfma_f32_16x16x32_bf16 v[96:99], v[242:245], v[202:205], v[96:99]
	v_mfma_f32_16x16x32_bf16 v[84:87], v[234:237], v[210:213], v[84:87]
	v_mfma_f32_16x16x32_bf16 v[80:83], v[242:245], v[210:213], v[80:83]
	v_mfma_f32_16x16x32_bf16 v[68:71], v[234:237], v[226:229], v[68:71]
	v_mfma_f32_16x16x32_bf16 v[64:67], v[242:245], v[226:229], v[64:67]
	v_mfma_f32_16x16x32_bf16 v[116:119], v[238:241], v[198:201], v[116:119]
	s_mov_b32 m0, s26
	v_mfma_f32_16x16x32_bf16 v[112:115], v[246:249], v[198:201], v[112:115]
	v_mfma_f32_16x16x32_bf16 v[100:103], v[238:241], v[206:209], v[100:103]
	v_mfma_f32_16x16x32_bf16 v[96:99], v[246:249], v[206:209], v[96:99]
	v_mfma_f32_16x16x32_bf16 v[84:87], v[238:241], v[214:217], v[84:87]
	v_mfma_f32_16x16x32_bf16 v[80:83], v[246:249], v[214:217], v[80:83]
	v_mfma_f32_16x16x32_bf16 v[68:71], v[238:241], v[230:233], v[68:71]
	s_setprio 0
	v_mfma_f32_16x16x32_bf16 v[64:67], v[246:249], v[230:233], v[64:67]
	s_barrier
	ds_read_b128 v[194:197], v189 offset:16384
	ds_read_b128 v[198:201], v189 offset:17408
	ds_read_b128 v[202:205], v189 offset:18432
	ds_read_b128 v[206:209], v189 offset:19456
	ds_read_b128 v[210:213], v189 offset:20480
	ds_read_b128 v[214:217], v189 offset:21504
	ds_read_b128 v[226:229], v189 offset:22528
	ds_read_b128 v[230:233], v189 offset:23552
	global_load_lds_dwordx4 v144, s[20:21]
	s_mov_b64 s[100:101], s[20:21]
	s_mov_b32 m0, s27
	s_nop 0
	global_load_lds_dwordx4 v142, s[20:21]
	s_waitcnt lgkmcnt(0)
	s_setprio 1
	s_barrier
	v_mfma_f32_16x16x32_bf16 v[60:63], v[128:131], v[194:197], v[60:63]
	v_mfma_f32_16x16x32_bf16 v[56:59], v[136:139], v[194:197], v[56:59]
	v_mfma_f32_16x16x32_bf16 v[44:47], v[128:131], v[202:205], v[44:47]
	v_mfma_f32_16x16x32_bf16 v[40:43], v[136:139], v[202:205], v[40:43]
	v_mfma_f32_16x16x32_bf16 v[28:31], v[128:131], v[210:213], v[28:31]
	v_mfma_f32_16x16x32_bf16 v[24:27], v[136:139], v[210:213], v[24:27]
	v_mfma_f32_16x16x32_bf16 v[12:15], v[128:131], v[226:229], v[12:15]
	v_mfma_f32_16x16x32_bf16 v[8:11], v[136:139], v[226:229], v[8:11]
	v_mfma_f32_16x16x32_bf16 v[60:63], v[132:135], v[198:201], v[60:63]
	v_mfma_f32_16x16x32_bf16 v[56:59], v[190:193], v[198:201], v[56:59]
	v_mfma_f32_16x16x32_bf16 v[44:47], v[132:135], v[206:209], v[44:47]
	v_mfma_f32_16x16x32_bf16 v[40:43], v[190:193], v[206:209], v[40:43]
	v_mfma_f32_16x16x32_bf16 v[28:31], v[132:135], v[214:217], v[28:31]
	v_mfma_f32_16x16x32_bf16 v[24:27], v[190:193], v[214:217], v[24:27]
	v_mfma_f32_16x16x32_bf16 v[12:15], v[132:135], v[230:233], v[12:15]
	s_setprio 0
	v_mfma_f32_16x16x32_bf16 v[8:11], v[190:193], v[230:233], v[8:11]
	s_barrier
	s_add_u32 s38, s18, 0x80000
	s_addc_u32 s39, s19, 0
	s_add_i32 s37, s40, s25
	s_mov_b32 m0, s37
	s_nop 0
	global_load_lds_dwordx4 v144, s[38:39]
	s_add_i32 m0, s37, 0x2000
	s_nop 0
	global_load_lds_dwordx4 v142, s[38:39]
	s_waitcnt vmcnt(6)
	s_setprio 1
	s_barrier
; #define PG8_STAGE(bufoff, gbase) do { _Pragma("unroll") for (int _i = 0; _i < 2; ++_i) \
;         __builtin_amdgcn_global_load_lds((const unsigned*)((const char*)(gbase) + voff[_i]), (LAS unsigned*)(lds + (bufoff) + ldsw + _i * 8192), 16, 0, 0); } while (0)
; #define PG8_LDA(dst, b, h) do { _Pragma("unroll") for (int m = 0; m < 4; ++m) _Pragma("unroll") for (int k = 0; k < 2; ++k) dst[m][k] = *(const LAS bf16x8*)(lds + PG8_SA(b, h) + aoff + m * 2048 + k * 1024); } while (0)
; #define PG8_LDB(dst, b, h) do { _Pragma("unroll") for (int n = 0; n < 2; ++n) _Pragma("unroll") for (int k = 0; k < 2; ++k) dst[n][k] = *(const LAS bf16x8*)(lds + PG8_SB(b, h) + boff + n * 2048 + k * 1024); } while (0)
; #define PG8_MMA(ai, bj, At, Bt) do { __builtin_amdgcn_s_setprio(1); _Pragma("unroll") for (int m = 0; m < 4; ++m) _Pragma("unroll") for (int n = 0; n < 2; ++n) _Pragma("unroll") for (int k = 0; k < 2; ++k) \
;         acc[ai][bj][m][n] = __builtin_amdgcn_mfma_f32_16x16x32_bf16(Bt[n][k], At[m][k], acc[ai][bj][m][n], 0, 0, 0); __builtin_amdgcn_s_setprio(0); } while (0)
; #define PG8_WAIT_V(n) asm volatile("s_waitcnt vmcnt(" #n ")" ::: "memory")
; #define PG8_WAIT_L(n) asm volatile("s_waitcnt lgkmcnt(" #n ")" ::: "memory")
; #define PG8_BAR __builtin_amdgcn_s_barrier()
; #define PG8_SCHED __builtin_amdgcn_sched_barrier(0)
; template <class Epi>
; DI void gemm_phase(LAS unsigned char* lds, const Gemm g, const StaticOrder& S, const Epi& E) {
;     ...
;             PG8_WAIT_V(6); PG8_BAR; PG8_MMA(1, 1, At, B1); PG8_BAR;
;             PG8_LDB(B0, 1, 0); PG8_SCHED; PG8_LDA(At, 1, 0); PG8_STAGE(PG8_SA(0, 1), a2 + hstep);
;             PG8_WAIT_L(8); PG8_BAR; PG8_WAIT_L(0); PG8_MMA(0, 0, At, B0); PG8_BAR; PG8_SCHED;
;             PG8_LDB(B1, 1, 1); PG8_STAGE(PG8_SB(1, 0), b3);
;             PG8_BAR; PG8_WAIT_L(0); PG8_MMA(0, 1, At, B1); PG8_BAR;
	v_mfma_f32_16x16x32_bf16 v[52:55], v[234:237], v[194:197], v[52:55]
	v_mfma_f32_16x16x32_bf16 v[48:51], v[242:245], v[194:197], v[48:51]
	v_mfma_f32_16x16x32_bf16 v[36:39], v[234:237], v[202:205], v[36:39]
	v_mfma_f32_16x16x32_bf16 v[32:35], v[242:245], v[202:205], v[32:35]
	v_mfma_f32_16x16x32_bf16 v[20:23], v[234:237], v[210:213], v[20:23]
	v_mfma_f32_16x16x32_bf16 v[16:19], v[242:245], v[210:213], v[16:19]
	v_mfma_f32_16x16x32_bf16 v[4:7], v[234:237], v[226:229], v[4:7]
	v_mfma_f32_16x16x32_bf16 v[0:3], v[242:245], v[226:229], v[0:3]
	v_mfma_f32_16x16x32_bf16 v[52:55], v[238:241], v[198:201], v[52:55]
	s_add_i32 s37, 0, 0x18000
	v_mfma_f32_16x16x32_bf16 v[48:51], v[246:249], v[198:201], v[48:51]
	v_mfma_f32_16x16x32_bf16 v[36:39], v[238:241], v[206:209], v[36:39]
	v_mfma_f32_16x16x32_bf16 v[32:35], v[246:249], v[206:209], v[32:35]
	v_mfma_f32_16x16x32_bf16 v[20:23], v[238:241], v[214:217], v[20:23]
	v_mfma_f32_16x16x32_bf16 v[16:19], v[246:249], v[214:217], v[16:19]
	v_mfma_f32_16x16x32_bf16 v[4:7], v[238:241], v[230:233], v[4:7]
	s_setprio 0
	v_mfma_f32_16x16x32_bf16 v[0:3], v[246:249], v[230:233], v[0:3]
	s_barrier
	ds_read_b128 v[128:131], v187 offset:32768
	ds_read_b128 v[132:135], v187 offset:33792
	ds_read_b128 v[136:139], v187 offset:34816
	ds_read_b128 v[190:193], v187 offset:35840
	ds_read_b128 v[194:197], v189 offset:32768
	ds_read_b128 v[198:201], v189 offset:33792
	ds_read_b128 v[202:205], v189 offset:34816
	ds_read_b128 v[206:209], v189 offset:35840
	ds_read_b128 v[210:213], v189 offset:36864
	ds_read_b128 v[214:217], v189 offset:37888
	ds_read_b128 v[226:229], v189 offset:38912
	ds_read_b128 v[230:233], v189 offset:39936
	s_add_u32 s20, s20, 0x80000
	s_addc_u32 s21, s21, 0
	s_mov_b32 m0, s28
	s_nop 0
	global_load_lds_dwordx4 v144, s[20:21]
	s_mov_b32 m0, s29
	s_nop 0
	global_load_lds_dwordx4 v142, s[20:21]
	s_waitcnt lgkmcnt(0)
	s_setprio 1
	s_barrier
	v_mfma_f32_16x16x32_bf16 v[124:127], v[128:131], v[194:197], v[124:127]
	v_mfma_f32_16x16x32_bf16 v[120:123], v[136:139], v[194:197], v[120:123]
	v_mfma_f32_16x16x32_bf16 v[108:111], v[128:131], v[202:205], v[108:111]
	v_mfma_f32_16x16x32_bf16 v[104:107], v[136:139], v[202:205], v[104:107]
	v_mfma_f32_16x16x32_bf16 v[92:95], v[128:131], v[210:213], v[92:95]
	v_mfma_f32_16x16x32_bf16 v[88:91], v[136:139], v[210:213], v[88:91]
	v_mfma_f32_16x16x32_bf16 v[76:79], v[128:131], v[226:229], v[76:79]
	v_mfma_f32_16x16x32_bf16 v[72:75], v[136:139], v[226:229], v[72:75]
	v_mfma_f32_16x16x32_bf16 v[124:127], v[132:135], v[198:201], v[124:127]
	v_mfma_f32_16x16x32_bf16 v[120:123], v[190:193], v[198:201], v[120:123]
	v_mfma_f32_16x16x32_bf16 v[108:111], v[132:135], v[206:209], v[108:111]
	v_mfma_f32_16x16x32_bf16 v[104:107], v[190:193], v[206:209], v[104:107]
	v_mfma_f32_16x16x32_bf16 v[92:95], v[132:135], v[214:217], v[92:95]
	v_mfma_f32_16x16x32_bf16 v[88:91], v[190:193], v[214:217], v[88:91]
	v_mfma_f32_16x16x32_bf16 v[76:79], v[132:135], v[230:233], v[76:79]
	s_setprio 0
	v_mfma_f32_16x16x32_bf16 v[72:75], v[190:193], v[230:233], v[72:75]
	s_barrier
	ds_read_b128 v[234:237], v187 offset:49152
	ds_read_b128 v[238:241], v187 offset:50176
	ds_read_b128 v[242:245], v187 offset:51200
	ds_read_b128 v[246:249], v187 offset:52224
	s_add_i32 s20, 0, 0x1c000
	s_add_i32 s21, s37, s25
	s_add_i32 m0, s21, 0xffffff80
	s_nop 0
	global_load_lds_dwordx4 v144, s[18:19] offset:128
	s_add_i32 m0, s21, 0x1f80
	s_nop 0
	global_load_lds_dwordx4 v142, s[18:19] offset:128
	s_waitcnt lgkmcnt(0)
	s_setprio 1
	s_barrier
	v_mfma_f32_16x16x32_bf16 v[116:119], v[234:237], v[194:197], v[116:119]
	v_mfma_f32_16x16x32_bf16 v[112:115], v[242:245], v[194:197], v[112:115]
	v_mfma_f32_16x16x32_bf16 v[100:103], v[234:237], v[202:205], v[100:103]
	v_mfma_f32_16x16x32_bf16 v[96:99], v[242:245], v[202:205], v[96:99]
	v_mfma_f32_16x16x32_bf16 v[84:87], v[234:237], v[210:213], v[84:87]
	v_mfma_f32_16x16x32_bf16 v[80:83], v[242:245], v[210:213], v[80:83]
	v_mfma_f32_16x16x32_bf16 v[68:71], v[234:237], v[226:229], v[68:71]
	v_mfma_f32_16x16x32_bf16 v[64:67], v[242:245], v[226:229], v[64:67]
	v_mfma_f32_16x16x32_bf16 v[116:119], v[238:241], v[198:201], v[116:119]
	s_add_i32 m0, s30, 0xffffff80
	v_mfma_f32_16x16x32_bf16 v[112:115], v[246:249], v[198:201], v[112:115]
	v_mfma_f32_16x16x32_bf16 v[100:103], v[238:241], v[206:209], v[100:103]
	v_mfma_f32_16x16x32_bf16 v[96:99], v[246:249], v[206:209], v[96:99]
	v_mfma_f32_16x16x32_bf16 v[84:87], v[238:241], v[214:217], v[84:87]
	v_mfma_f32_16x16x32_bf16 v[80:83], v[246:249], v[214:217], v[80:83]
	v_mfma_f32_16x16x32_bf16 v[68:71], v[238:241], v[230:233], v[68:71]
	s_setprio 0
	v_mfma_f32_16x16x32_bf16 v[64:67], v[246:249], v[230:233], v[64:67]
	s_barrier
; #define PG8_STAGE(bufoff, gbase) do { _Pragma("unroll") for (int _i = 0; _i < 2; ++_i) \
;         __builtin_amdgcn_global_load_lds((const unsigned*)((const char*)(gbase) + voff[_i]), (LAS unsigned*)(lds + (bufoff) + ldsw + _i * 8192), 16, 0, 0); } while (0)
; #define PG8_LDA(dst, b, h) do { _Pragma("unroll") for (int m = 0; m < 4; ++m) _Pragma("unroll") for (int k = 0; k < 2; ++k) dst[m][k] = *(const LAS bf16x8*)(lds + PG8_SA(b, h) + aoff + m * 2048 + k * 1024); } while (0)
; #define PG8_MMA(ai, bj, At, Bt) do { __builtin_amdgcn_s_setprio(1); _Pragma("unroll") for (int m = 0; m < 4; ++m) _Pragma("unroll") for (int n = 0; n < 2; ++n) _Pragma("unroll") for (int k = 0; k < 2; ++k) \
;         acc[ai][bj][m][n] = __builtin_amdgcn_mfma_f32_16x16x32_bf16(Bt[n][k], At[m][k], acc[ai][bj][m][n], 0, 0, 0); __builtin_amdgcn_s_setprio(0); } while (0)
; #define PG8_WAIT_V(n) asm volatile("s_waitcnt vmcnt(" #n ")" ::: "memory")
; #define PG8_WAIT_L(n) asm volatile("s_waitcnt lgkmcnt(" #n ")" ::: "memory")
; #define PG8_BAR __builtin_amdgcn_s_barrier()
; #define PG8_SCHED __builtin_amdgcn_sched_barrier(0)
; template <class Epi>
; DI void gemm_phase(LAS unsigned char* lds, const Gemm g, const StaticOrder& S, const Epi& E) {
;     ...
;             PG8_LDA(At, 1, 1); PG8_STAGE(PG8_SA(1, 0), a3);
;             PG8_BAR; PG8_WAIT_L(0); PG8_MMA(1, 0, At, B0); PG8_BAR; PG8_SCHED;
;             PG8_STAGE(PG8_SB(1, 1), b3 + hstep);
;             PG8_WAIT_V(6); PG8_BAR; PG8_MMA(1, 1, At, B1); PG8_BAR;
;     DI void operator()(const f32x4 (&acc)[2][2][4][2], const Unit& u, int wr, int wc, int fr, int fq) const {
;         const int row0 = u.pm * BM + wr * 64 + fr, col0 = u.pn * BM + wc * 16 + 4 * fq;
;         const bool rot = u.pn < 18;
; #pragma unroll
;         for (int ai = 0; ai < 2; ++ai)
; #pragma unroll
;             for (int m = 0; m < 4; ++m) { const int row = row0 + ai * HALF + m * 16; u16* rowp = O + (size_t)row * NQKV_DIL + col0;
;                 f32x4 c4 = (f32x4){1.f, 1.f, 1.f, 1.f}, s4 = (f32x4){0.f, 0.f, 0.f, 0.f};
;                 if (rot) { const int pos = row & (SEQ - 1); c4 = *(const f32x4*)(cs + pos * 64 + wc * 16 + 4 * fq); s4 = *(const f32x4*)(sn + pos * 64 + wc * 16 + 4 * fq); }
	ds_read_b128 v[194:197], v189 offset:49152
	ds_read_b128 v[198:201], v189 offset:50176
	ds_read_b128 v[202:205], v189 offset:51200
	ds_read_b128 v[206:209], v189 offset:52224
	ds_read_b128 v[210:213], v189 offset:53248
	ds_read_b128 v[214:217], v189 offset:54272
	ds_read_b128 v[226:229], v189 offset:55296
	ds_read_b128 v[230:233], v189 offset:56320
	global_load_lds_dwordx4 v144, s[100:101] offset:128
	s_add_i32 m0, s31, 0xffffff80
	s_nop 0
	global_load_lds_dwordx4 v142, s[100:101] offset:128
	s_waitcnt lgkmcnt(0)
	s_setprio 1
	s_barrier
	v_mfma_f32_16x16x32_bf16 v[60:63], v[128:131], v[194:197], v[60:63]
	v_mfma_f32_16x16x32_bf16 v[56:59], v[136:139], v[194:197], v[56:59]
	v_mfma_f32_16x16x32_bf16 v[44:47], v[128:131], v[202:205], v[44:47]
	v_mfma_f32_16x16x32_bf16 v[40:43], v[136:139], v[202:205], v[40:43]
	v_mfma_f32_16x16x32_bf16 v[28:31], v[128:131], v[210:213], v[28:31]
	v_mfma_f32_16x16x32_bf16 v[24:27], v[136:139], v[210:213], v[24:27]
	v_mfma_f32_16x16x32_bf16 v[12:15], v[128:131], v[226:229], v[12:15]
	v_mfma_f32_16x16x32_bf16 v[8:11], v[136:139], v[226:229], v[8:11]
	v_mfma_f32_16x16x32_bf16 v[60:63], v[132:135], v[198:201], v[60:63]
	v_mfma_f32_16x16x32_bf16 v[56:59], v[190:193], v[198:201], v[56:59]
	v_mfma_f32_16x16x32_bf16 v[44:47], v[132:135], v[206:209], v[44:47]
	v_mfma_f32_16x16x32_bf16 v[40:43], v[190:193], v[206:209], v[40:43]
	v_mfma_f32_16x16x32_bf16 v[28:31], v[132:135], v[214:217], v[28:31]
	v_mfma_f32_16x16x32_bf16 v[24:27], v[190:193], v[214:217], v[24:27]
	v_mfma_f32_16x16x32_bf16 v[12:15], v[132:135], v[230:233], v[12:15]
	s_setprio 0
	v_mfma_f32_16x16x32_bf16 v[8:11], v[190:193], v[230:233], v[8:11]
	s_barrier
	s_add_u32 s18, s18, 0x80080
	s_addc_u32 s19, s19, 0
	s_add_i32 s20, s20, s25
	s_mov_b32 m0, s20
	s_nop 0
	global_load_lds_dwordx4 v144, s[18:19]
	s_add_i32 m0, s20, 0x2000
	s_nop 0
	global_load_lds_dwordx4 v142, s[18:19]
	s_waitcnt vmcnt(6)
	s_setprio 1
	s_barrier
	v_mfma_f32_16x16x32_bf16 v[52:55], v[234:237], v[194:197], v[52:55]
	v_mfma_f32_16x16x32_bf16 v[48:51], v[242:245], v[194:197], v[48:51]
	v_mfma_f32_16x16x32_bf16 v[36:39], v[234:237], v[202:205], v[36:39]
	v_mfma_f32_16x16x32_bf16 v[32:35], v[242:245], v[202:205], v[32:35]
	v_mfma_f32_16x16x32_bf16 v[20:23], v[234:237], v[210:213], v[20:23]
	v_mfma_f32_16x16x32_bf16 v[16:19], v[242:245], v[210:213], v[16:19]
	v_mfma_f32_16x16x32_bf16 v[4:7], v[234:237], v[226:229], v[4:7]
	v_mfma_f32_16x16x32_bf16 v[0:3], v[242:245], v[226:229], v[0:3]
	v_mfma_f32_16x16x32_bf16 v[52:55], v[238:241], v[198:201], v[52:55]
	s_add_i32 s36, s36, 2
	v_mfma_f32_16x16x32_bf16 v[48:51], v[246:249], v[198:201], v[48:51]
	s_add_u32 s8, s8, 0x100
	v_mfma_f32_16x16x32_bf16 v[36:39], v[238:241], v[206:209], v[36:39]
	s_addc_u32 s9, s9, 0
	v_mfma_f32_16x16x32_bf16 v[32:35], v[246:249], v[206:209], v[32:35]
	s_add_u32 s33, s33, 0x100
	v_mfma_f32_16x16x32_bf16 v[20:23], v[238:241], v[214:217], v[20:23]
	s_addc_u32 s35, s35, 0
	v_mfma_f32_16x16x32_bf16 v[16:19], v[246:249], v[214:217], v[16:19]
	s_cmp_gt_u32 s36, 29
	v_mfma_f32_16x16x32_bf16 v[4:7], v[238:241], v[230:233], v[4:7]
	s_setprio 0
	v_mfma_f32_16x16x32_bf16 v[0:3], v[246:249], v[230:233], v[0:3]
	s_barrier
	s_cbranch_scc0 .LBB0_202
	s_cmp_lt_i32 s2, 18
	v_lshl_add_u32 v190, s3, 8, v186
	v_mov_b32_e32 v128, 1.0
	v_mov_b32_e32 v132, 0
	s_cselect_b64 s[18:19], -1, 0
	s_cmp_gt_i32 s2, 17
	v_mov_b32_e32 v134, 0
	v_mov_b32_e32 v135, 0
	v_mov_b32_e32 v136, 0
	v_mov_b32_e32 v137, 0
	v_mov_b32_e32 v138, 1.0
	v_mov_b32_e32 v139, 1.0
	v_mov_b32_e32 v140, 1.0
	v_mov_b32_e32 v141, 1.0
	s_cbranch_scc1 .LBB0_205
	v_lshlrev_b32_e32 v129, 8, v190
	v_and_b32_e32 v158, 0xfcf00, v129
	v_lshl_add_u64 v[130:131], v[146:147], 0, v[158:159]
	v_lshl_add_u64 v[134:135], v[148:149], 0, v[158:159]
	global_load_dwordx4 v[138:141], v[130:131], off
	s_nop 0
	global_load_dwordx4 v[134:137], v[134:135], off

; #define PG8_STAGE(bufoff, gbase) do { _Pragma("unroll") for (int _i = 0; _i < 2; ++_i) \
;         __builtin_amdgcn_global_load_lds((const unsigned*)((const char*)(gbase) + voff[_i]), (LAS unsigned*)(lds + (bufoff) + ldsw + _i * 8192), 16, 0, 0); } while (0)
; #define PG8_LDA(dst, b, h) do { _Pragma("unroll") for (int m = 0; m < 4; ++m) _Pragma("unroll") for (int k = 0; k < 2; ++k) dst[m][k] = *(const LAS bf16x8*)(lds + PG8_SA(b, h) + aoff + m * 2048 + k * 1024); } while (0)
; #define PG8_LDB(dst, b, h) do { _Pragma("unroll") for (int n = 0; n < 2; ++n) _Pragma("unroll") for (int k = 0; k < 2; ++k) dst[n][k] = *(const LAS bf16x8*)(lds + PG8_SB(b, h) + boff + n * 2048 + k * 1024); } while (0)
; #define PG8_MMA(ai, bj, At, Bt) do { __builtin_amdgcn_s_setprio(1); _Pragma("unroll") for (int m = 0; m < 4; ++m) _Pragma("unroll") for (int n = 0; n < 2; ++n) _Pragma("unroll") for (int k = 0; k < 2; ++k) \
;         acc[ai][bj][m][n] = __builtin_amdgcn_mfma_f32_16x16x32_bf16(Bt[n][k], At[m][k], acc[ai][bj][m][n], 0, 0, 0); __builtin_amdgcn_s_setprio(0); } while (0)
; #define PG8_WAIT_V(n) asm volatile("s_waitcnt vmcnt(" #n ")" ::: "memory")
; #define PG8_WAIT_L(n) asm volatile("s_waitcnt lgkmcnt(" #n ")" ::: "memory")
; #define PG8_BAR __builtin_amdgcn_s_barrier()
; #define PG8_SCHED __builtin_amdgcn_sched_barrier(0)
; template <class Epi>
; DI void gemm_phase(LAS unsigned char* lds, const Gemm g, const StaticOrder& S, const Epi& E) {
;     ...
;         for (int t = 0; t < nt; t += 2) {
;             const bool last = (t == nt - 2);
;             const char* a1 = cA + (size_t)(t + 1) * kstep;
;             const char* a2 = last ? nA : cA + (size_t)(t + 2) * kstep; const char* b2 = last ? nB : cB + (size_t)(t + 2) * kstep;
;             const char* a3 = a2 + kstep; const char* b3 = b2 + kstep;
;             PG8_LDB(B0, 0, 0); PG8_SCHED; PG8_LDA(At, 0, 0); PG8_STAGE(PG8_SA(1, 1), a1 + hstep);
;             PG8_WAIT_L(8); PG8_BAR; PG8_WAIT_L(0); PG8_MMA(0, 0, At, B0); PG8_BAR; PG8_SCHED;
;             PG8_LDB(B1, 0, 1); PG8_STAGE(PG8_SB(0, 0), b2);
;             PG8_BAR; PG8_WAIT_L(0); PG8_MMA(0, 1, At, B1); PG8_BAR;
;             PG8_LDA(At, 0, 1); PG8_STAGE(PG8_SA(0, 0), a2);
;             PG8_BAR; PG8_WAIT_L(0); PG8_MMA(1, 0, At, B0); PG8_BAR; PG8_SCHED;
;             PG8_STAGE(PG8_SB(0, 1), b2 + hstep);
;             PG8_WAIT_V(6); PG8_BAR; PG8_MMA(1, 1, At, B1); PG8_BAR;
.LBB0_231:
	ds_read_b128 v[138:141], v135
	ds_read_b128 v[142:145], v135 offset:1024
	ds_read_b128 v[146:149], v135 offset:2048
	ds_read_b128 v[150:153], v135 offset:3072
	ds_read_b128 v[186:189], v137
	ds_read_b128 v[190:193], v137 offset:1024
	ds_read_b128 v[194:197], v137 offset:2048
	ds_read_b128 v[198:201], v137 offset:3072
	ds_read_b128 v[202:205], v137 offset:4096
	ds_read_b128 v[206:209], v137 offset:5120
	ds_read_b128 v[210:213], v137 offset:6144
	ds_read_b128 v[214:217], v137 offset:7168
	s_add_u32 s18, s16, 0xfff80080
	s_addc_u32 s19, s17, -1
	s_add_i32 s37, 0, 0x10000
	s_cmp_eq_u32 s36, 28
	s_cselect_b32 s21, s4, s19
	s_cselect_b32 s20, s5, s18
	s_cselect_b32 s19, s9, s35
	s_cselect_b32 s18, s11, s34
	s_add_i32 m0, s24, 0xc000
	s_nop 0
	global_load_lds_dwordx4 v130, s[16:17]
	s_add_i32 m0, s24, 0xe000
	s_nop 0
	global_load_lds_dwordx4 v132, s[16:17]
	s_waitcnt lgkmcnt(0)
	s_setprio 1
	s_barrier
	v_mfma_f32_16x16x32_bf16 v[124:127], v[138:141], v[186:189], v[124:127]
	v_mfma_f32_16x16x32_bf16 v[120:123], v[146:149], v[186:189], v[120:123]
	v_mfma_f32_16x16x32_bf16 v[116:119], v[138:141], v[194:197], v[116:119]
	v_mfma_f32_16x16x32_bf16 v[112:115], v[146:149], v[194:197], v[112:115]
	v_mfma_f32_16x16x32_bf16 v[100:103], v[138:141], v[202:205], v[100:103]
	v_mfma_f32_16x16x32_bf16 v[96:99], v[146:149], v[202:205], v[96:99]
	v_mfma_f32_16x16x32_bf16 v[84:87], v[138:141], v[210:213], v[84:87]
	v_mfma_f32_16x16x32_bf16 v[80:83], v[146:149], v[210:213], v[80:83]
	v_mfma_f32_16x16x32_bf16 v[124:127], v[142:145], v[190:193], v[124:127]
	v_mfma_f32_16x16x32_bf16 v[120:123], v[150:153], v[190:193], v[120:123]
	v_mfma_f32_16x16x32_bf16 v[116:119], v[142:145], v[198:201], v[116:119]
	v_mfma_f32_16x16x32_bf16 v[112:115], v[150:153], v[198:201], v[112:115]
	v_mfma_f32_16x16x32_bf16 v[100:103], v[142:145], v[206:209], v[100:103]
	v_mfma_f32_16x16x32_bf16 v[96:99], v[150:153], v[206:209], v[96:99]
	v_mfma_f32_16x16x32_bf16 v[84:87], v[142:145], v[214:217], v[84:87]
	s_setprio 0
	v_mfma_f32_16x16x32_bf16 v[80:83], v[150:153], v[214:217], v[80:83]
	s_barrier
	ds_read_b128 v[226:229], v135 offset:16384
	ds_read_b128 v[230:233], v135 offset:17408
	ds_read_b128 v[234:237], v135 offset:18432
	ds_read_b128 v[238:241], v135 offset:19456
	s_add_i32 s40, 0, 0x14000
	s_add_i32 s37, s37, s23
	s_mov_b32 m0, s37
	s_nop 0
	global_load_lds_dwordx4 v158, s[18:19]
	s_add_i32 m0, s37, 0x2000
	s_nop 0
	global_load_lds_dwordx4 v128, s[18:19]
	s_waitcnt lgkmcnt(0)
	s_setprio 1
	s_barrier
	v_mfma_f32_16x16x32_bf16 v[108:111], v[226:229], v[186:189], v[108:111]
	v_mfma_f32_16x16x32_bf16 v[104:107], v[234:237], v[186:189], v[104:107]
	v_mfma_f32_16x16x32_bf16 v[92:95], v[226:229], v[194:197], v[92:95]
	v_mfma_f32_16x16x32_bf16 v[88:91], v[234:237], v[194:197], v[88:91]
	v_mfma_f32_16x16x32_bf16 v[76:79], v[226:229], v[202:205], v[76:79]
	v_mfma_f32_16x16x32_bf16 v[72:75], v[234:237], v[202:205], v[72:75]
	v_mfma_f32_16x16x32_bf16 v[68:71], v[226:229], v[210:213], v[68:71]
	v_mfma_f32_16x16x32_bf16 v[64:67], v[234:237], v[210:213], v[64:67]
	v_mfma_f32_16x16x32_bf16 v[108:111], v[230:233], v[190:193], v[108:111]
	s_mov_b32 m0, s24
	v_mfma_f32_16x16x32_bf16 v[104:107], v[238:241], v[190:193], v[104:107]
	v_mfma_f32_16x16x32_bf16 v[92:95], v[230:233], v[198:201], v[92:95]
	v_mfma_f32_16x16x32_bf16 v[88:91], v[238:241], v[198:201], v[88:91]
	v_mfma_f32_16x16x32_bf16 v[76:79], v[230:233], v[206:209], v[76:79]
	v_mfma_f32_16x16x32_bf16 v[72:75], v[238:241], v[206:209], v[72:75]
	v_mfma_f32_16x16x32_bf16 v[68:71], v[230:233], v[214:217], v[68:71]
	s_setprio 0
	v_mfma_f32_16x16x32_bf16 v[64:67], v[238:241], v[214:217], v[64:67]
	s_barrier
	ds_read_b128 v[186:189], v137 offset:16384
	ds_read_b128 v[190:193], v137 offset:17408
	ds_read_b128 v[194:197], v137 offset:18432
	ds_read_b128 v[198:201], v137 offset:19456
	ds_read_b128 v[202:205], v137 offset:20480
	ds_read_b128 v[206:209], v137 offset:21504
	ds_read_b128 v[210:213], v137 offset:22528
	ds_read_b128 v[214:217], v137 offset:23552
	global_load_lds_dwordx4 v158, s[20:21]
	s_mov_b64 s[100:101], s[20:21]
	s_mov_b32 m0, s25
	s_nop 0
	global_load_lds_dwordx4 v128, s[20:21]
	s_waitcnt lgkmcnt(0)
	s_setprio 1
	s_barrier
	v_mfma_f32_16x16x32_bf16 v[60:63], v[138:141], v[186:189], v[60:63]
	v_mfma_f32_16x16x32_bf16 v[56:59], v[146:149], v[186:189], v[56:59]
	v_mfma_f32_16x16x32_bf16 v[52:55], v[138:141], v[194:197], v[52:55]
	v_mfma_f32_16x16x32_bf16 v[48:51], v[146:149], v[194:197], v[48:51]
	v_mfma_f32_16x16x32_bf16 v[36:39], v[138:141], v[202:205], v[36:39]
	v_mfma_f32_16x16x32_bf16 v[32:35], v[146:149], v[202:205], v[32:35]
	v_mfma_f32_16x16x32_bf16 v[20:23], v[138:141], v[210:213], v[20:23]
	v_mfma_f32_16x16x32_bf16 v[16:19], v[146:149], v[210:213], v[16:19]
	v_mfma_f32_16x16x32_bf16 v[60:63], v[142:145], v[190:193], v[60:63]
	v_mfma_f32_16x16x32_bf16 v[56:59], v[150:153], v[190:193], v[56:59]
	v_mfma_f32_16x16x32_bf16 v[52:55], v[142:145], v[198:201], v[52:55]
	v_mfma_f32_16x16x32_bf16 v[48:51], v[150:153], v[198:201], v[48:51]
	v_mfma_f32_16x16x32_bf16 v[36:39], v[142:145], v[206:209], v[36:39]
	v_mfma_f32_16x16x32_bf16 v[32:35], v[150:153], v[206:209], v[32:35]
	v_mfma_f32_16x16x32_bf16 v[20:23], v[142:145], v[214:217], v[20:23]
	s_setprio 0
	v_mfma_f32_16x16x32_bf16 v[16:19], v[150:153], v[214:217], v[16:19]
	s_barrier
	s_add_u32 s38, s18, 0x80000
	s_addc_u32 s39, s19, 0
	s_add_i32 s37, s40, s23
	s_mov_b32 m0, s37
	s_nop 0
	global_load_lds_dwordx4 v158, s[38:39]
	s_add_i32 m0, s37, 0x2000
	s_nop 0
	global_load_lds_dwordx4 v128, s[38:39]
	s_waitcnt vmcnt(6)
	s_setprio 1
	s_barrier
; #define PG8_STAGE(bufoff, gbase) do { _Pragma("unroll") for (int _i = 0; _i < 2; ++_i) \
;         __builtin_amdgcn_global_load_lds((const unsigned*)((const char*)(gbase) + voff[_i]), (LAS unsigned*)(lds + (bufoff) + ldsw + _i * 8192), 16, 0, 0); } while (0)
; #define PG8_LDA(dst, b, h) do { _Pragma("unroll") for (int m = 0; m < 4; ++m) _Pragma("unroll") for (int k = 0; k < 2; ++k) dst[m][k] = *(const LAS bf16x8*)(lds + PG8_SA(b, h) + aoff + m * 2048 + k * 1024); } while (0)
; #define PG8_LDB(dst, b, h) do { _Pragma("unroll") for (int n = 0; n < 2; ++n) _Pragma("unroll") for (int k = 0; k < 2; ++k) dst[n][k] = *(const LAS bf16x8*)(lds + PG8_SB(b, h) + boff + n * 2048 + k * 1024); } while (0)
; #define PG8_MMA(ai, bj, At, Bt) do { __builtin_amdgcn_s_setprio(1); _Pragma("unroll") for (int m = 0; m < 4; ++m) _Pragma("unroll") for (int n = 0; n < 2; ++n) _Pragma("unroll") for (int k = 0; k < 2; ++k) \
;         acc[ai][bj][m][n] = __builtin_amdgcn_mfma_f32_16x16x32_bf16(Bt[n][k], At[m][k], acc[ai][bj][m][n], 0, 0, 0); __builtin_amdgcn_s_setprio(0); } while (0)
; #define PG8_WAIT_V(n) asm volatile("s_waitcnt vmcnt(" #n ")" ::: "memory")
; #define PG8_WAIT_L(n) asm volatile("s_waitcnt lgkmcnt(" #n ")" ::: "memory")
; #define PG8_BAR __builtin_amdgcn_s_barrier()
; #define PG8_SCHED __builtin_amdgcn_sched_barrier(0)
; template <class Epi>
; DI void gemm_phase(LAS unsigned char* lds, const Gemm g, const StaticOrder& S, const Epi& E) {
;     ...
;             PG8_WAIT_V(6); PG8_BAR; PG8_MMA(1, 1, At, B1); PG8_BAR;
;             PG8_LDB(B0, 1, 0); PG8_SCHED; PG8_LDA(At, 1, 0); PG8_STAGE(PG8_SA(0, 1), a2 + hstep);
;             PG8_WAIT_L(8); PG8_BAR; PG8_WAIT_L(0); PG8_MMA(0, 0, At, B0); PG8_BAR; PG8_SCHED;
;             PG8_LDB(B1, 1, 1); PG8_STAGE(PG8_SB(1, 0), b3);
;             PG8_BAR; PG8_WAIT_L(0); PG8_MMA(0, 1, At, B1); PG8_BAR;
;             PG8_LDA(At, 1, 1); PG8_STAGE(PG8_SA(1, 0), a3);
	v_mfma_f32_16x16x32_bf16 v[44:47], v[226:229], v[186:189], v[44:47]
	v_mfma_f32_16x16x32_bf16 v[40:43], v[234:237], v[186:189], v[40:43]
	v_mfma_f32_16x16x32_bf16 v[28:31], v[226:229], v[194:197], v[28:31]
	v_mfma_f32_16x16x32_bf16 v[24:27], v[234:237], v[194:197], v[24:27]
	v_mfma_f32_16x16x32_bf16 v[12:15], v[226:229], v[202:205], v[12:15]
	v_mfma_f32_16x16x32_bf16 v[8:11], v[234:237], v[202:205], v[8:11]
	v_mfma_f32_16x16x32_bf16 v[4:7], v[226:229], v[210:213], v[4:7]
	v_mfma_f32_16x16x32_bf16 v[0:3], v[234:237], v[210:213], v[0:3]
	v_mfma_f32_16x16x32_bf16 v[44:47], v[230:233], v[190:193], v[44:47]
	s_add_i32 s37, 0, 0x18000
	v_mfma_f32_16x16x32_bf16 v[40:43], v[238:241], v[190:193], v[40:43]
	v_mfma_f32_16x16x32_bf16 v[28:31], v[230:233], v[198:201], v[28:31]
	v_mfma_f32_16x16x32_bf16 v[24:27], v[238:241], v[198:201], v[24:27]
	v_mfma_f32_16x16x32_bf16 v[12:15], v[230:233], v[206:209], v[12:15]
	v_mfma_f32_16x16x32_bf16 v[8:11], v[238:241], v[206:209], v[8:11]
	v_mfma_f32_16x16x32_bf16 v[4:7], v[230:233], v[214:217], v[4:7]
	s_setprio 0
	v_mfma_f32_16x16x32_bf16 v[0:3], v[238:241], v[214:217], v[0:3]
	s_barrier
	ds_read_b128 v[138:141], v135 offset:32768
	ds_read_b128 v[142:145], v135 offset:33792
	ds_read_b128 v[146:149], v135 offset:34816
	ds_read_b128 v[150:153], v135 offset:35840
	ds_read_b128 v[186:189], v137 offset:32768
	ds_read_b128 v[190:193], v137 offset:33792
	ds_read_b128 v[194:197], v137 offset:34816
	ds_read_b128 v[198:201], v137 offset:35840
	ds_read_b128 v[202:205], v137 offset:36864
	ds_read_b128 v[206:209], v137 offset:37888
	ds_read_b128 v[210:213], v137 offset:38912
	ds_read_b128 v[214:217], v137 offset:39936
	s_add_u32 s20, s20, 0x80000
	s_addc_u32 s21, s21, 0
	s_mov_b32 m0, s26
	s_nop 0
	global_load_lds_dwordx4 v158, s[20:21]
	s_mov_b32 m0, s27
	s_nop 0
	global_load_lds_dwordx4 v128, s[20:21]
	s_waitcnt lgkmcnt(0)
	s_setprio 1
	s_barrier
	v_mfma_f32_16x16x32_bf16 v[124:127], v[138:141], v[186:189], v[124:127]
	v_mfma_f32_16x16x32_bf16 v[120:123], v[146:149], v[186:189], v[120:123]
	v_mfma_f32_16x16x32_bf16 v[116:119], v[138:141], v[194:197], v[116:119]
	v_mfma_f32_16x16x32_bf16 v[112:115], v[146:149], v[194:197], v[112:115]
	v_mfma_f32_16x16x32_bf16 v[100:103], v[138:141], v[202:205], v[100:103]
	v_mfma_f32_16x16x32_bf16 v[96:99], v[146:149], v[202:205], v[96:99]
	v_mfma_f32_16x16x32_bf16 v[84:87], v[138:141], v[210:213], v[84:87]
	v_mfma_f32_16x16x32_bf16 v[80:83], v[146:149], v[210:213], v[80:83]
	v_mfma_f32_16x16x32_bf16 v[124:127], v[142:145], v[190:193], v[124:127]
	v_mfma_f32_16x16x32_bf16 v[120:123], v[150:153], v[190:193], v[120:123]
	v_mfma_f32_16x16x32_bf16 v[116:119], v[142:145], v[198:201], v[116:119]
	v_mfma_f32_16x16x32_bf16 v[112:115], v[150:153], v[198:201], v[112:115]
	v_mfma_f32_16x16x32_bf16 v[100:103], v[142:145], v[206:209], v[100:103]
	v_mfma_f32_16x16x32_bf16 v[96:99], v[150:153], v[206:209], v[96:99]
	v_mfma_f32_16x16x32_bf16 v[84:87], v[142:145], v[214:217], v[84:87]
	s_setprio 0
	v_mfma_f32_16x16x32_bf16 v[80:83], v[150:153], v[214:217], v[80:83]
	s_barrier
	ds_read_b128 v[226:229], v135 offset:49152
	ds_read_b128 v[230:233], v135 offset:50176
	ds_read_b128 v[234:237], v135 offset:51200
	ds_read_b128 v[238:241], v135 offset:52224
	s_add_i32 s20, 0, 0x1c000
	s_add_i32 s21, s37, s23
	s_add_i32 m0, s21, 0xffffff80
	s_nop 0
	global_load_lds_dwordx4 v158, s[18:19] offset:128
	s_add_i32 m0, s21, 0x1f80
	s_nop 0
	global_load_lds_dwordx4 v128, s[18:19] offset:128
	s_waitcnt lgkmcnt(0)
	s_setprio 1
	s_barrier
	v_mfma_f32_16x16x32_bf16 v[108:111], v[226:229], v[186:189], v[108:111]
	v_mfma_f32_16x16x32_bf16 v[104:107], v[234:237], v[186:189], v[104:107]
	v_mfma_f32_16x16x32_bf16 v[92:95], v[226:229], v[194:197], v[92:95]
	v_mfma_f32_16x16x32_bf16 v[88:91], v[234:237], v[194:197], v[88:91]
	v_mfma_f32_16x16x32_bf16 v[76:79], v[226:229], v[202:205], v[76:79]
	v_mfma_f32_16x16x32_bf16 v[72:75], v[234:237], v[202:205], v[72:75]
	v_mfma_f32_16x16x32_bf16 v[68:71], v[226:229], v[210:213], v[68:71]
	v_mfma_f32_16x16x32_bf16 v[64:67], v[234:237], v[210:213], v[64:67]
	v_mfma_f32_16x16x32_bf16 v[108:111], v[230:233], v[190:193], v[108:111]
	s_add_i32 m0, s28, 0xffffff80
	v_mfma_f32_16x16x32_bf16 v[104:107], v[238:241], v[190:193], v[104:107]
	v_mfma_f32_16x16x32_bf16 v[92:95], v[230:233], v[198:201], v[92:95]
	v_mfma_f32_16x16x32_bf16 v[88:91], v[238:241], v[198:201], v[88:91]
	v_mfma_f32_16x16x32_bf16 v[76:79], v[230:233], v[206:209], v[76:79]
	v_mfma_f32_16x16x32_bf16 v[72:75], v[238:241], v[206:209], v[72:75]
	v_mfma_f32_16x16x32_bf16 v[68:71], v[230:233], v[214:217], v[68:71]
	s_setprio 0
	v_mfma_f32_16x16x32_bf16 v[64:67], v[238:241], v[214:217], v[64:67]
	s_barrier
	ds_read_b128 v[186:189], v137 offset:49152
	ds_read_b128 v[190:193], v137 offset:50176
	ds_read_b128 v[194:197], v137 offset:51200
	ds_read_b128 v[198:201], v137 offset:52224
	ds_read_b128 v[202:205], v137 offset:53248
	ds_read_b128 v[206:209], v137 offset:54272
	ds_read_b128 v[210:213], v137 offset:55296
	ds_read_b128 v[214:217], v137 offset:56320
	global_load_lds_dwordx4 v158, s[100:101] offset:128
	s_add_i32 m0, s29, 0xffffff80
	s_nop 0
	global_load_lds_dwordx4 v128, s[100:101] offset:128
	s_waitcnt lgkmcnt(0)
	s_setprio 1
	s_barrier
; #define PG8_STAGE(bufoff, gbase) do { _Pragma("unroll") for (int _i = 0; _i < 2; ++_i) \
;         __builtin_amdgcn_global_load_lds((const unsigned*)((const char*)(gbase) + voff[_i]), (LAS unsigned*)(lds + (bufoff) + ldsw + _i * 8192), 16, 0, 0); } while (0)
; #define PG8_MMA(ai, bj, At, Bt) do { __builtin_amdgcn_s_setprio(1); _Pragma("unroll") for (int m = 0; m < 4; ++m) _Pragma("unroll") for (int n = 0; n < 2; ++n) _Pragma("unroll") for (int k = 0; k < 2; ++k) \
;         acc[ai][bj][m][n] = __builtin_amdgcn_mfma_f32_16x16x32_bf16(Bt[n][k], At[m][k], acc[ai][bj][m][n], 0, 0, 0); __builtin_amdgcn_s_setprio(0); } while (0)
; #define PG8_WAIT_V(n) asm volatile("s_waitcnt vmcnt(" #n ")" ::: "memory")
; #define PG8_WAIT_L(n) asm volatile("s_waitcnt lgkmcnt(" #n ")" ::: "memory")
; #define PG8_BAR __builtin_amdgcn_s_barrier()
; #define PG8_SCHED __builtin_amdgcn_sched_barrier(0)
; template <class Epi>
; DI void gemm_phase(LAS unsigned char* lds, const Gemm g, const StaticOrder& S, const Epi& E) {
;     ...
;             PG8_BAR; PG8_WAIT_L(0); PG8_MMA(1, 0, At, B0); PG8_BAR; PG8_SCHED;
;             PG8_STAGE(PG8_SB(1, 1), b3 + hstep);
;             PG8_WAIT_V(6); PG8_BAR; PG8_MMA(1, 1, At, B1); PG8_BAR;
;         }
	v_mfma_f32_16x16x32_bf16 v[60:63], v[138:141], v[186:189], v[60:63]
	v_mfma_f32_16x16x32_bf16 v[56:59], v[146:149], v[186:189], v[56:59]
	v_mfma_f32_16x16x32_bf16 v[52:55], v[138:141], v[194:197], v[52:55]
	v_mfma_f32_16x16x32_bf16 v[48:51], v[146:149], v[194:197], v[48:51]
	v_mfma_f32_16x16x32_bf16 v[36:39], v[138:141], v[202:205], v[36:39]
	v_mfma_f32_16x16x32_bf16 v[32:35], v[146:149], v[202:205], v[32:35]
	v_mfma_f32_16x16x32_bf16 v[20:23], v[138:141], v[210:213], v[20:23]
	v_mfma_f32_16x16x32_bf16 v[16:19], v[146:149], v[210:213], v[16:19]
	v_mfma_f32_16x16x32_bf16 v[60:63], v[142:145], v[190:193], v[60:63]
	v_mfma_f32_16x16x32_bf16 v[56:59], v[150:153], v[190:193], v[56:59]
	v_mfma_f32_16x16x32_bf16 v[52:55], v[142:145], v[198:201], v[52:55]
	v_mfma_f32_16x16x32_bf16 v[48:51], v[150:153], v[198:201], v[48:51]
	v_mfma_f32_16x16x32_bf16 v[36:39], v[142:145], v[206:209], v[36:39]
	v_mfma_f32_16x16x32_bf16 v[32:35], v[150:153], v[206:209], v[32:35]
	v_mfma_f32_16x16x32_bf16 v[20:23], v[142:145], v[214:217], v[20:23]
	s_setprio 0
	v_mfma_f32_16x16x32_bf16 v[16:19], v[150:153], v[214:217], v[16:19]
	s_barrier
	s_add_u32 s18, s18, 0x80080
	s_addc_u32 s19, s19, 0
	s_add_i32 s20, s20, s23
	s_mov_b32 m0, s20
	s_nop 0
	global_load_lds_dwordx4 v158, s[18:19]
	s_add_i32 m0, s20, 0x2000
	s_nop 0
	global_load_lds_dwordx4 v128, s[18:19]
	s_waitcnt vmcnt(6)
	s_setprio 1
	s_barrier
	v_mfma_f32_16x16x32_bf16 v[44:47], v[226:229], v[186:189], v[44:47]
	v_mfma_f32_16x16x32_bf16 v[40:43], v[234:237], v[186:189], v[40:43]
	v_mfma_f32_16x16x32_bf16 v[28:31], v[226:229], v[194:197], v[28:31]
	v_mfma_f32_16x16x32_bf16 v[24:27], v[234:237], v[194:197], v[24:27]
	v_mfma_f32_16x16x32_bf16 v[12:15], v[226:229], v[202:205], v[12:15]
	v_mfma_f32_16x16x32_bf16 v[8:11], v[234:237], v[202:205], v[8:11]
	v_mfma_f32_16x16x32_bf16 v[4:7], v[226:229], v[210:213], v[4:7]
	v_mfma_f32_16x16x32_bf16 v[0:3], v[234:237], v[210:213], v[0:3]
	v_mfma_f32_16x16x32_bf16 v[44:47], v[230:233], v[190:193], v[44:47]
	s_add_i32 s36, s36, 2
	v_mfma_f32_16x16x32_bf16 v[40:43], v[238:241], v[190:193], v[40:43]
	s_add_u32 s16, s16, 0x100
	v_mfma_f32_16x16x32_bf16 v[28:31], v[230:233], v[198:201], v[28:31]
	s_addc_u32 s17, s17, 0
	v_mfma_f32_16x16x32_bf16 v[24:27], v[238:241], v[198:201], v[24:27]
	s_add_u32 s34, s34, 0x100
	v_mfma_f32_16x16x32_bf16 v[12:15], v[230:233], v[206:209], v[12:15]
	s_addc_u32 s35, s35, 0
	v_mfma_f32_16x16x32_bf16 v[8:11], v[238:241], v[206:209], v[8:11]
	s_cmp_gt_u32 s36, 29
	v_mfma_f32_16x16x32_bf16 v[4:7], v[230:233], v[214:217], v[4:7]
	s_setprio 0
	v_mfma_f32_16x16x32_bf16 v[0:3], v[238:241], v[214:217], v[0:3]
	s_barrier
	s_cbranch_scc0 .LBB0_231
; #define PG8_WAIT_V(n) asm volatile("s_waitcnt vmcnt(" #n ")" ::: "memory")
; #define PG8_BAR __builtin_amdgcn_s_barrier()
; template <class Epi>
; DI void gemm_phase(LAS unsigned char* lds, const Gemm g, const StaticOrder& S, const Epi& E) {
;     ...
;         E(acc, cur, wr, wc, fr, fq);
;         if (!has_next) break;
; #pragma unroll
;         for (int a = 0; a < 2; ++a)
; #pragma unroll
;             for (int b = 0; b < 2; ++b)
; #pragma unroll
;                 for (int m = 0; m < 4; ++m)
; #pragma unroll
;                     for (int n = 0; n < 2; ++n) acc[a][b][m][n] = (f32x4){0.f, 0.f, 0.f, 0.f};
;         cur = nxt; cA = nA; cB = nB; ++ui;
;     }
;     PG8_WAIT_V(0);
;     if (wr == 0) PG8_BAR;
;     DI void operator()(const f32x4 (&acc)[2][2][4][2], const Unit& u, int wr, int wc, int fr, int fq) const {
;         const int row0 = u.pm * BM + wr * 64 + fr, col0 = u.pn * BM + wc * 32 + 8 * fq;
; #pragma unroll
;         for (int ai = 0; ai < 2; ++ai)
; #pragma unroll
;             for (int m = 0; m < 4; ++m) { u16* rowp = O + (size_t)(row0 + ai * HALF + m * 16) * ldc + col0;
; #pragma unroll
;                 for (int bj = 0; bj < 2; ++bj) { const f32x4 v0 = acc[ai][bj][m][0], v1 = acc[ai][bj][m][1];
;                     *(u32x4*)(rowp + bj * HALF) = (u32x4){pk(v0[0], v0[1]), pk(v0[2], v0[3]), pk(v1[0], v1[1]), pk(v1[2], v1[3])}; } }
;     }
	v_lshl_add_u32 v144, s33, 8, v134
	v_lshl_or_b32 v138, s31, 8, v136
	v_ashrrev_i32_e32 v139, 31, v138
	v_mov_b64_e32 v[140:141], s[50:51]
	s_movk_i32 s9, 0x3000
	v_cvt_pk_bf16_f32 v68, v68, v69
	v_cvt_pk_bf16_f32 v69, v70, v71
	v_cvt_pk_bf16_f32 v70, v64, v65
	v_add_u32_e32 v64, 0x80, v144
	v_mad_i64_i32 v[142:143], s[4:5], v144, s9, v[140:141]
	v_lshlrev_b64 v[138:139], 1, v[138:139]
	v_cvt_pk_bf16_f32 v108, v108, v109
	v_cvt_pk_bf16_f32 v109, v110, v111
	v_cvt_pk_bf16_f32 v110, v104, v105
	v_or_b32_e32 v104, 16, v144
	v_mad_i64_i32 v[64:65], s[4:5], v64, s9, v[140:141]
	v_cvt_pk_bf16_f32 v44, v44, v45
	v_cvt_pk_bf16_f32 v45, v46, v47
	v_cvt_pk_bf16_f32 v46, v40, v41
	v_add_u32_e32 v40, 0x90, v144
	v_lshl_add_u64 v[142:143], v[142:143], 0, v[138:139]
	v_cvt_pk_bf16_f32 v111, v106, v107
	v_mad_i64_i32 v[104:105], s[4:5], v104, s9, v[140:141]
	v_cvt_pk_bf16_f32 v92, v92, v93
	v_cvt_pk_bf16_f32 v93, v94, v95
	v_cvt_pk_bf16_f32 v94, v88, v89
	v_or_b32_e32 v88, 32, v144
	v_lshl_add_u64 v[64:65], v[64:65], 0, v[138:139]
	v_cvt_pk_bf16_f32 v47, v42, v43
	v_mad_i64_i32 v[40:41], s[4:5], v40, s9, v[140:141]
	v_cvt_pk_bf16_f32 v28, v28, v29
	v_cvt_pk_bf16_f32 v29, v30, v31
	v_cvt_pk_bf16_f32 v30, v24, v25
	v_add_u32_e32 v24, 0xa0, v144
	global_store_dwordx4 v[142:143], v[108:111], off offset:256
	v_cvt_pk_bf16_f32 v95, v90, v91
	v_mad_i64_i32 v[88:89], s[4:5], v88, s9, v[140:141]
	v_lshl_add_u64 v[108:109], v[104:105], 0, v[138:139]
	v_cvt_pk_bf16_f32 v76, v76, v77
	v_cvt_pk_bf16_f32 v77, v78, v79
	v_cvt_pk_bf16_f32 v78, v72, v73
	v_or_b32_e32 v72, 48, v144
	global_store_dwordx4 v[64:65], v[44:47], off offset:256
	v_cvt_pk_bf16_f32 v31, v26, v27
	v_mad_i64_i32 v[24:25], s[4:5], v24, s9, v[140:141]
	v_lshl_add_u64 v[44:45], v[40:41], 0, v[138:139]
	v_cvt_pk_bf16_f32 v12, v12, v13
	v_cvt_pk_bf16_f32 v13, v14, v15
	v_cvt_pk_bf16_f32 v14, v8, v9
	v_add_u32_e32 v8, 0xb0, v144
	global_store_dwordx4 v[108:109], v[92:95], off offset:256
	v_cvt_pk_bf16_f32 v79, v74, v75
	v_mad_i64_i32 v[72:73], s[4:5], v72, s9, v[140:141]
	v_lshl_add_u64 v[92:93], v[88:89], 0, v[138:139]
	global_store_dwordx4 v[44:45], v[28:31], off offset:256
	v_cvt_pk_bf16_f32 v15, v10, v11
	v_mad_i64_i32 v[8:9], s[4:5], v8, s9, v[140:141]
	v_lshl_add_u64 v[28:29], v[24:25], 0, v[138:139]
	v_cvt_pk_bf16_f32 v124, v124, v125
	v_cvt_pk_bf16_f32 v125, v126, v127
	v_cvt_pk_bf16_f32 v126, v120, v121
	v_cvt_pk_bf16_f32 v127, v122, v123
	v_cvt_pk_bf16_f32 v104, v116, v117
	v_cvt_pk_bf16_f32 v105, v118, v119
	v_cvt_pk_bf16_f32 v106, v112, v113
	v_cvt_pk_bf16_f32 v107, v114, v115
	v_cvt_pk_bf16_f32 v88, v100, v101
	v_cvt_pk_bf16_f32 v89, v102, v103
	v_cvt_pk_bf16_f32 v90, v96, v97
	v_cvt_pk_bf16_f32 v91, v98, v99
	global_store_dwordx4 v[92:93], v[76:79], off offset:256
	v_cvt_pk_bf16_f32 v74, v80, v81
	v_cvt_pk_bf16_f32 v75, v82, v83
	v_lshl_add_u64 v[76:77], v[72:73], 0, v[138:139]
	v_cvt_pk_bf16_f32 v72, v84, v85
	v_cvt_pk_bf16_f32 v73, v86, v87
	v_cvt_pk_bf16_f32 v71, v66, v67
	v_cvt_pk_bf16_f32 v60, v60, v61
	v_cvt_pk_bf16_f32 v61, v62, v63
	v_cvt_pk_bf16_f32 v62, v56, v57
	v_cvt_pk_bf16_f32 v63, v58, v59
	v_cvt_pk_bf16_f32 v40, v52, v53
	v_cvt_pk_bf16_f32 v41, v54, v55
	v_cvt_pk_bf16_f32 v42, v48, v49
	v_cvt_pk_bf16_f32 v43, v50, v51
	v_cvt_pk_bf16_f32 v24, v36, v37
	v_cvt_pk_bf16_f32 v25, v38, v39
	v_cvt_pk_bf16_f32 v26, v32, v33
	v_cvt_pk_bf16_f32 v27, v34, v35
	global_store_dwordx4 v[28:29], v[12:15], off offset:256
	v_cvt_pk_bf16_f32 v10, v16, v17
	v_cvt_pk_bf16_f32 v11, v18, v19
	v_lshl_add_u64 v[12:13], v[8:9], 0, v[138:139]
	v_cvt_pk_bf16_f32 v8, v20, v21
	v_cvt_pk_bf16_f32 v9, v22, v23
	v_cvt_pk_bf16_f32 v4, v4, v5
	v_cvt_pk_bf16_f32 v5, v6, v7
	v_cvt_pk_bf16_f32 v6, v0, v1
	v_cvt_pk_bf16_f32 v7, v2, v3
	s_and_b64 vcc, exec, s[6:7]
	s_mov_b32 s31, s8
	s_mov_b32 s33, s10
	s_mov_b64 s[18:19], s[14:15]
	s_mov_b64 s[16:17], s[12:13]
	global_store_dwordx4 v[142:143], v[124:127], off
	global_store_dwordx4 v[108:109], v[104:107], off
	global_store_dwordx4 v[92:93], v[88:91], off
	global_store_dwordx4 v[76:77], v[72:75], off
	global_store_dwordx4 v[76:77], v[68:71], off offset:256
	global_store_dwordx4 v[64:65], v[60:63], off
	global_store_dwordx4 v[44:45], v[40:43], off
	global_store_dwordx4 v[28:29], v[24:27], off
	global_store_dwordx4 v[12:13], v[8:11], off
	global_store_dwordx4 v[12:13], v[4:7], off offset:256
	s_cbranch_vccz .LBB0_228
	s_waitcnt vmcnt(0)
	s_cmpk_gt_u32 s2, 0xff
	s_cbranch_scc1 .LBB0_235
	s_barrier

; #define PG8_STAGE(bufoff, gbase) do { _Pragma("unroll") for (int _i = 0; _i < 2; ++_i) \
;         __builtin_amdgcn_global_load_lds((const unsigned*)((const char*)(gbase) + voff[_i]), (LAS unsigned*)(lds + (bufoff) + ldsw + _i * 8192), 16, 0, 0); } while (0)
; #define PG8_LDA(dst, b, h) do { _Pragma("unroll") for (int m = 0; m < 4; ++m) _Pragma("unroll") for (int k = 0; k < 2; ++k) dst[m][k] = *(const LAS bf16x8*)(lds + PG8_SA(b, h) + aoff + m * 2048 + k * 1024); } while (0)
; #define PG8_LDB(dst, b, h) do { _Pragma("unroll") for (int n = 0; n < 2; ++n) _Pragma("unroll") for (int k = 0; k < 2; ++k) dst[n][k] = *(const LAS bf16x8*)(lds + PG8_SB(b, h) + boff + n * 2048 + k * 1024); } while (0)
; #define PG8_MMA(ai, bj, At, Bt) do { __builtin_amdgcn_s_setprio(1); _Pragma("unroll") for (int m = 0; m < 4; ++m) _Pragma("unroll") for (int n = 0; n < 2; ++n) _Pragma("unroll") for (int k = 0; k < 2; ++k) \
;         acc[ai][bj][m][n] = __builtin_amdgcn_mfma_f32_16x16x32_bf16(Bt[n][k], At[m][k], acc[ai][bj][m][n], 0, 0, 0); __builtin_amdgcn_s_setprio(0); } while (0)
; #define PG8_WAIT_V(n) asm volatile("s_waitcnt vmcnt(" #n ")" ::: "memory")
; #define PG8_WAIT_L(n) asm volatile("s_waitcnt lgkmcnt(" #n ")" ::: "memory")
; #define PG8_BAR __builtin_amdgcn_s_barrier()
; #define PG8_SCHED __builtin_amdgcn_sched_barrier(0)
; template <class Epi>
; DI void gemm_phase(LAS unsigned char* lds, const Gemm g, const StaticOrder& S, const Epi& E) {
;     ...
;         for (int t = 0; t < nt; t += 2) {
;             const bool last = (t == nt - 2);
;             const char* a1 = cA + (size_t)(t + 1) * kstep;
;             const char* a2 = last ? nA : cA + (size_t)(t + 2) * kstep; const char* b2 = last ? nB : cB + (size_t)(t + 2) * kstep;
;             const char* a3 = a2 + kstep; const char* b3 = b2 + kstep;
;             PG8_LDB(B0, 0, 0); PG8_SCHED; PG8_LDA(At, 0, 0); PG8_STAGE(PG8_SA(1, 1), a1 + hstep);
;             PG8_WAIT_L(8); PG8_BAR; PG8_WAIT_L(0); PG8_MMA(0, 0, At, B0); PG8_BAR; PG8_SCHED;
;             PG8_LDB(B1, 0, 1); PG8_STAGE(PG8_SB(0, 0), b2);
;             PG8_BAR; PG8_WAIT_L(0); PG8_MMA(0, 1, At, B1); PG8_BAR;
;             PG8_LDA(At, 0, 1); PG8_STAGE(PG8_SA(0, 0), a2);
;             PG8_BAR; PG8_WAIT_L(0); PG8_MMA(1, 0, At, B0); PG8_BAR; PG8_SCHED;
;             PG8_STAGE(PG8_SB(0, 1), b2 + hstep);
;             PG8_WAIT_V(6); PG8_BAR; PG8_MMA(1, 1, At, B1); PG8_BAR;
.LBB0_320:
	s_add_u32 s26, s24, 0x100
	s_addc_u32 s27, s25, 0
	s_add_i32 s47, 0, 0x10000
	ds_read_b128 v[128:131], v226
	ds_read_b128 v[132:135], v226 offset:1024
	ds_read_b128 v[136:139], v226 offset:2048
	ds_read_b128 v[140:143], v226 offset:3072
	s_cmp_eq_u32 s46, 28
	s_cselect_b32 s31, s4, s27
	s_cselect_b32 s30, s5, s26
	s_cselect_b32 s29, s9, s45
	s_cselect_b32 s28, s11, s33
	v_lshl_add_u64 v[214:215], s[24:25], 0, v[190:191]
	s_add_i32 m0, s38, 0xc000
	ds_read_b128 v[144:147], v228
	ds_read_b128 v[148:151], v228 offset:1024
	ds_read_b128 v[152:155], v228 offset:2048
	ds_read_b128 v[194:197], v228 offset:3072
	ds_read_b128 v[198:201], v228 offset:4096
	ds_read_b128 v[202:205], v228 offset:5120
	ds_read_b128 v[206:209], v228 offset:6144
	ds_read_b128 v[210:213], v228 offset:7168
	global_load_lds_dwordx4 v[214:215], off
	v_lshl_add_u64 v[214:215], s[24:25], 0, v[192:193]
	s_add_i32 m0, s38, 0xe000
	s_nop 0
	global_load_lds_dwordx4 v[214:215], off
	s_waitcnt lgkmcnt(0)
	s_setprio 1
	s_barrier
	v_mfma_f32_16x16x32_bf16 v[124:127], v[128:131], v[144:147], v[124:127]
	v_mfma_f32_16x16x32_bf16 v[120:123], v[136:139], v[144:147], v[120:123]
	v_mfma_f32_16x16x32_bf16 v[116:119], v[128:131], v[152:155], v[116:119]
	v_mfma_f32_16x16x32_bf16 v[112:115], v[136:139], v[152:155], v[112:115]
	v_mfma_f32_16x16x32_bf16 v[108:111], v[128:131], v[198:201], v[108:111]
	v_mfma_f32_16x16x32_bf16 v[104:107], v[136:139], v[198:201], v[104:107]
	v_mfma_f32_16x16x32_bf16 v[100:103], v[128:131], v[206:209], v[100:103]
	v_mfma_f32_16x16x32_bf16 v[96:99], v[136:139], v[206:209], v[96:99]
	v_mfma_f32_16x16x32_bf16 v[124:127], v[132:135], v[148:151], v[124:127]
	v_mfma_f32_16x16x32_bf16 v[120:123], v[140:143], v[148:151], v[120:123]
	v_mfma_f32_16x16x32_bf16 v[116:119], v[132:135], v[194:197], v[116:119]
	v_mfma_f32_16x16x32_bf16 v[112:115], v[140:143], v[194:197], v[112:115]
	v_mfma_f32_16x16x32_bf16 v[108:111], v[132:135], v[202:205], v[108:111]
	v_mfma_f32_16x16x32_bf16 v[104:107], v[140:143], v[202:205], v[104:107]
	v_mfma_f32_16x16x32_bf16 v[100:103], v[132:135], v[210:213], v[100:103]
	s_setprio 0
	v_mfma_f32_16x16x32_bf16 v[96:99], v[140:143], v[210:213], v[96:99]
	s_barrier
	ds_read_b128 v[214:217], v226 offset:16384
	ds_read_b128 v[230:233], v226 offset:17408
	ds_read_b128 v[234:237], v226 offset:18432
	ds_read_b128 v[238:241], v226 offset:19456
	s_add_i32 s48, 0, 0x14000
	s_add_i32 s24, s47, s37
	s_mov_b32 m0, s24
	s_nop 0
	global_load_lds_dwordx4 v188, s[28:29]
	s_add_i32 m0, s24, 0x2000
	s_nop 0
	global_load_lds_dwordx4 v186, s[28:29]
	s_waitcnt lgkmcnt(0)
	s_setprio 1
	s_barrier
	v_mfma_f32_16x16x32_bf16 v[60:63], v[214:217], v[144:147], v[60:63]
	v_mfma_f32_16x16x32_bf16 v[56:59], v[234:237], v[144:147], v[56:59]
	v_mfma_f32_16x16x32_bf16 v[52:55], v[214:217], v[152:155], v[52:55]
	v_mfma_f32_16x16x32_bf16 v[48:51], v[234:237], v[152:155], v[48:51]
	v_mfma_f32_16x16x32_bf16 v[44:47], v[214:217], v[198:201], v[44:47]
	v_mfma_f32_16x16x32_bf16 v[40:43], v[234:237], v[198:201], v[40:43]
	v_mfma_f32_16x16x32_bf16 v[36:39], v[214:217], v[206:209], v[36:39]
	v_mfma_f32_16x16x32_bf16 v[32:35], v[234:237], v[206:209], v[32:35]
	v_mfma_f32_16x16x32_bf16 v[60:63], v[230:233], v[148:151], v[60:63]
	s_mov_b32 m0, s38
	v_mfma_f32_16x16x32_bf16 v[56:59], v[238:241], v[148:151], v[56:59]
	v_mfma_f32_16x16x32_bf16 v[52:55], v[230:233], v[194:197], v[52:55]
	v_mfma_f32_16x16x32_bf16 v[48:51], v[238:241], v[194:197], v[48:51]
	v_mfma_f32_16x16x32_bf16 v[44:47], v[230:233], v[202:205], v[44:47]
	v_mfma_f32_16x16x32_bf16 v[40:43], v[238:241], v[202:205], v[40:43]
	v_mfma_f32_16x16x32_bf16 v[36:39], v[230:233], v[210:213], v[36:39]
	s_setprio 0
	v_mfma_f32_16x16x32_bf16 v[32:35], v[238:241], v[210:213], v[32:35]
	s_barrier
	ds_read_b128 v[144:147], v228 offset:16384
	ds_read_b128 v[148:151], v228 offset:17408
	ds_read_b128 v[152:155], v228 offset:18432
	ds_read_b128 v[194:197], v228 offset:19456
	ds_read_b128 v[198:201], v228 offset:20480
	ds_read_b128 v[202:205], v228 offset:21504
	ds_read_b128 v[206:209], v228 offset:22528
	ds_read_b128 v[210:213], v228 offset:23552
	global_load_lds_dwordx4 v188, s[30:31]
	s_mov_b64 s[100:101], s[30:31]
	s_mov_b32 m0, s39
	s_nop 0
	global_load_lds_dwordx4 v186, s[30:31]
	s_waitcnt lgkmcnt(0)
	s_setprio 1
	s_barrier
	v_mfma_f32_16x16x32_bf16 v[92:95], v[128:131], v[144:147], v[92:95]
	v_mfma_f32_16x16x32_bf16 v[88:91], v[136:139], v[144:147], v[88:91]
	v_mfma_f32_16x16x32_bf16 v[84:87], v[128:131], v[152:155], v[84:87]
	v_mfma_f32_16x16x32_bf16 v[80:83], v[136:139], v[152:155], v[80:83]
	v_mfma_f32_16x16x32_bf16 v[76:79], v[128:131], v[198:201], v[76:79]
	v_mfma_f32_16x16x32_bf16 v[72:75], v[136:139], v[198:201], v[72:75]
	v_mfma_f32_16x16x32_bf16 v[68:71], v[128:131], v[206:209], v[68:71]
	v_mfma_f32_16x16x32_bf16 v[64:67], v[136:139], v[206:209], v[64:67]
	v_mfma_f32_16x16x32_bf16 v[92:95], v[132:135], v[148:151], v[92:95]
	v_mfma_f32_16x16x32_bf16 v[88:91], v[140:143], v[148:151], v[88:91]
	v_mfma_f32_16x16x32_bf16 v[84:87], v[132:135], v[194:197], v[84:87]
	v_mfma_f32_16x16x32_bf16 v[80:83], v[140:143], v[194:197], v[80:83]
	v_mfma_f32_16x16x32_bf16 v[76:79], v[132:135], v[202:205], v[76:79]
	v_mfma_f32_16x16x32_bf16 v[72:75], v[140:143], v[202:205], v[72:75]
	v_mfma_f32_16x16x32_bf16 v[68:71], v[132:135], v[210:213], v[68:71]
	s_setprio 0
	v_mfma_f32_16x16x32_bf16 v[64:67], v[140:143], v[210:213], v[64:67]
	s_barrier
	s_add_u32 s24, s28, 0x80000
	s_addc_u32 s25, s29, 0
	s_add_i32 s47, s48, s37
	s_mov_b32 m0, s47
	s_nop 0
	global_load_lds_dwordx4 v188, s[24:25]
	s_add_i32 m0, s47, 0x2000
	s_nop 0
	global_load_lds_dwordx4 v186, s[24:25]
	s_waitcnt vmcnt(6)
	s_setprio 1
	s_barrier
; #define PG8_STAGE(bufoff, gbase) do { _Pragma("unroll") for (int _i = 0; _i < 2; ++_i) \
;         __builtin_amdgcn_global_load_lds((const unsigned*)((const char*)(gbase) + voff[_i]), (LAS unsigned*)(lds + (bufoff) + ldsw + _i * 8192), 16, 0, 0); } while (0)
; #define PG8_LDA(dst, b, h) do { _Pragma("unroll") for (int m = 0; m < 4; ++m) _Pragma("unroll") for (int k = 0; k < 2; ++k) dst[m][k] = *(const LAS bf16x8*)(lds + PG8_SA(b, h) + aoff + m * 2048 + k * 1024); } while (0)
; #define PG8_LDB(dst, b, h) do { _Pragma("unroll") for (int n = 0; n < 2; ++n) _Pragma("unroll") for (int k = 0; k < 2; ++k) dst[n][k] = *(const LAS bf16x8*)(lds + PG8_SB(b, h) + boff + n * 2048 + k * 1024); } while (0)
; #define PG8_MMA(ai, bj, At, Bt) do { __builtin_amdgcn_s_setprio(1); _Pragma("unroll") for (int m = 0; m < 4; ++m) _Pragma("unroll") for (int n = 0; n < 2; ++n) _Pragma("unroll") for (int k = 0; k < 2; ++k) \
;         acc[ai][bj][m][n] = __builtin_amdgcn_mfma_f32_16x16x32_bf16(Bt[n][k], At[m][k], acc[ai][bj][m][n], 0, 0, 0); __builtin_amdgcn_s_setprio(0); } while (0)
; #define PG8_WAIT_V(n) asm volatile("s_waitcnt vmcnt(" #n ")" ::: "memory")
; #define PG8_WAIT_L(n) asm volatile("s_waitcnt lgkmcnt(" #n ")" ::: "memory")
; #define PG8_BAR __builtin_amdgcn_s_barrier()
; #define PG8_SCHED __builtin_amdgcn_sched_barrier(0)
; template <class Epi>
; DI void gemm_phase(LAS unsigned char* lds, const Gemm g, const StaticOrder& S, const Epi& E) {
;     ...
;             PG8_WAIT_V(6); PG8_BAR; PG8_MMA(1, 1, At, B1); PG8_BAR;
;             PG8_LDB(B0, 1, 0); PG8_SCHED; PG8_LDA(At, 1, 0); PG8_STAGE(PG8_SA(0, 1), a2 + hstep);
;             PG8_WAIT_L(8); PG8_BAR; PG8_WAIT_L(0); PG8_MMA(0, 0, At, B0); PG8_BAR; PG8_SCHED;
;             PG8_LDB(B1, 1, 1); PG8_STAGE(PG8_SB(1, 0), b3);
;             PG8_BAR; PG8_WAIT_L(0); PG8_MMA(0, 1, At, B1); PG8_BAR;
;             PG8_LDA(At, 1, 1); PG8_STAGE(PG8_SA(1, 0), a3);
	v_mfma_f32_16x16x32_bf16 v[28:31], v[214:217], v[144:147], v[28:31]
	v_mfma_f32_16x16x32_bf16 v[24:27], v[234:237], v[144:147], v[24:27]
	v_mfma_f32_16x16x32_bf16 v[20:23], v[214:217], v[152:155], v[20:23]
	v_mfma_f32_16x16x32_bf16 v[16:19], v[234:237], v[152:155], v[16:19]
	v_mfma_f32_16x16x32_bf16 v[12:15], v[214:217], v[198:201], v[12:15]
	v_mfma_f32_16x16x32_bf16 v[8:11], v[234:237], v[198:201], v[8:11]
	v_mfma_f32_16x16x32_bf16 v[4:7], v[214:217], v[206:209], v[4:7]
	v_mfma_f32_16x16x32_bf16 v[0:3], v[234:237], v[206:209], v[0:3]
	v_mfma_f32_16x16x32_bf16 v[28:31], v[230:233], v[148:151], v[28:31]
	s_add_i32 s47, 0, 0x18000
	v_mfma_f32_16x16x32_bf16 v[24:27], v[238:241], v[148:151], v[24:27]
	v_mfma_f32_16x16x32_bf16 v[20:23], v[230:233], v[194:197], v[20:23]
	v_mfma_f32_16x16x32_bf16 v[16:19], v[238:241], v[194:197], v[16:19]
	v_mfma_f32_16x16x32_bf16 v[12:15], v[230:233], v[202:205], v[12:15]
	v_mfma_f32_16x16x32_bf16 v[8:11], v[238:241], v[202:205], v[8:11]
	v_mfma_f32_16x16x32_bf16 v[4:7], v[230:233], v[210:213], v[4:7]
	s_setprio 0
	v_mfma_f32_16x16x32_bf16 v[0:3], v[238:241], v[210:213], v[0:3]
	s_barrier
	ds_read_b128 v[128:131], v226 offset:32768
	ds_read_b128 v[132:135], v226 offset:33792
	ds_read_b128 v[136:139], v226 offset:34816
	ds_read_b128 v[140:143], v226 offset:35840
	ds_read_b128 v[144:147], v228 offset:32768
	ds_read_b128 v[148:151], v228 offset:33792
	ds_read_b128 v[152:155], v228 offset:34816
	ds_read_b128 v[194:197], v228 offset:35840
	ds_read_b128 v[198:201], v228 offset:36864
	ds_read_b128 v[202:205], v228 offset:37888
	ds_read_b128 v[206:209], v228 offset:38912
	ds_read_b128 v[210:213], v228 offset:39936
	s_add_u32 s24, s30, 0x80000
	s_addc_u32 s25, s31, 0
	s_mov_b32 m0, s40
	s_nop 0
	global_load_lds_dwordx4 v188, s[24:25]
	s_mov_b32 m0, s41
	s_nop 0
	global_load_lds_dwordx4 v186, s[24:25]
	s_waitcnt lgkmcnt(0)
	s_setprio 1
	s_barrier
	v_mfma_f32_16x16x32_bf16 v[124:127], v[128:131], v[144:147], v[124:127]
	v_mfma_f32_16x16x32_bf16 v[120:123], v[136:139], v[144:147], v[120:123]
	v_mfma_f32_16x16x32_bf16 v[116:119], v[128:131], v[152:155], v[116:119]
	v_mfma_f32_16x16x32_bf16 v[112:115], v[136:139], v[152:155], v[112:115]
	v_mfma_f32_16x16x32_bf16 v[108:111], v[128:131], v[198:201], v[108:111]
	v_mfma_f32_16x16x32_bf16 v[104:107], v[136:139], v[198:201], v[104:107]
	v_mfma_f32_16x16x32_bf16 v[100:103], v[128:131], v[206:209], v[100:103]
	v_mfma_f32_16x16x32_bf16 v[96:99], v[136:139], v[206:209], v[96:99]
	v_mfma_f32_16x16x32_bf16 v[124:127], v[132:135], v[148:151], v[124:127]
	v_mfma_f32_16x16x32_bf16 v[120:123], v[140:143], v[148:151], v[120:123]
	v_mfma_f32_16x16x32_bf16 v[116:119], v[132:135], v[194:197], v[116:119]
	v_mfma_f32_16x16x32_bf16 v[112:115], v[140:143], v[194:197], v[112:115]
	v_mfma_f32_16x16x32_bf16 v[108:111], v[132:135], v[202:205], v[108:111]
	v_mfma_f32_16x16x32_bf16 v[104:107], v[140:143], v[202:205], v[104:107]
	v_mfma_f32_16x16x32_bf16 v[100:103], v[132:135], v[210:213], v[100:103]
	s_setprio 0
	v_mfma_f32_16x16x32_bf16 v[96:99], v[140:143], v[210:213], v[96:99]
	s_barrier
	ds_read_b128 v[214:217], v226 offset:49152
	ds_read_b128 v[230:233], v226 offset:50176
	ds_read_b128 v[234:237], v226 offset:51200
	ds_read_b128 v[238:241], v226 offset:52224
	s_add_i32 s30, 0, 0x1c000
	s_add_i32 s24, s47, s37
	s_add_i32 m0, s24, 0xffffff80
	s_nop 0
	global_load_lds_dwordx4 v188, s[28:29] offset:128
	s_add_i32 m0, s24, 0x1f80
	s_nop 0
	global_load_lds_dwordx4 v186, s[28:29] offset:128
	s_waitcnt lgkmcnt(0)
	s_setprio 1
	s_barrier
	v_mfma_f32_16x16x32_bf16 v[60:63], v[214:217], v[144:147], v[60:63]
	v_mfma_f32_16x16x32_bf16 v[56:59], v[234:237], v[144:147], v[56:59]
	v_mfma_f32_16x16x32_bf16 v[52:55], v[214:217], v[152:155], v[52:55]
	v_mfma_f32_16x16x32_bf16 v[48:51], v[234:237], v[152:155], v[48:51]
	v_mfma_f32_16x16x32_bf16 v[44:47], v[214:217], v[198:201], v[44:47]
	v_mfma_f32_16x16x32_bf16 v[40:43], v[234:237], v[198:201], v[40:43]
	v_mfma_f32_16x16x32_bf16 v[36:39], v[214:217], v[206:209], v[36:39]
	v_mfma_f32_16x16x32_bf16 v[32:35], v[234:237], v[206:209], v[32:35]
	v_mfma_f32_16x16x32_bf16 v[60:63], v[230:233], v[148:151], v[60:63]
	s_add_i32 m0, s42, 0xffffff80
	v_mfma_f32_16x16x32_bf16 v[56:59], v[238:241], v[148:151], v[56:59]
	v_mfma_f32_16x16x32_bf16 v[52:55], v[230:233], v[194:197], v[52:55]
	v_mfma_f32_16x16x32_bf16 v[48:51], v[238:241], v[194:197], v[48:51]
	v_mfma_f32_16x16x32_bf16 v[44:47], v[230:233], v[202:205], v[44:47]
	v_mfma_f32_16x16x32_bf16 v[40:43], v[238:241], v[202:205], v[40:43]
	v_mfma_f32_16x16x32_bf16 v[36:39], v[230:233], v[210:213], v[36:39]
	s_setprio 0
	v_mfma_f32_16x16x32_bf16 v[32:35], v[238:241], v[210:213], v[32:35]
	s_barrier
	ds_read_b128 v[144:147], v228 offset:49152
	ds_read_b128 v[148:151], v228 offset:50176
	ds_read_b128 v[152:155], v228 offset:51200
	ds_read_b128 v[194:197], v228 offset:52224
	ds_read_b128 v[198:201], v228 offset:53248
	ds_read_b128 v[202:205], v228 offset:54272
	ds_read_b128 v[206:209], v228 offset:55296
	ds_read_b128 v[210:213], v228 offset:56320
	global_load_lds_dwordx4 v188, s[100:101] offset:128
	s_add_i32 m0, s43, 0xffffff80
	s_nop 0
	global_load_lds_dwordx4 v186, s[100:101] offset:128
	s_waitcnt lgkmcnt(0)
	s_setprio 1
	s_barrier
; #define PG8_WAIT_V(n) asm volatile("s_waitcnt vmcnt(" #n ")" ::: "memory")
; #define PG8_BAR __builtin_amdgcn_s_barrier()
; template <class Epi>
; DI void gemm_phase(LAS unsigned char* lds, const Gemm g, const StaticOrder& S, const Epi& E) {
;     ...
;             PG8_BAR; PG8_WAIT_L(0); PG8_MMA(1, 0, At, B0); PG8_BAR; PG8_SCHED;
;             PG8_STAGE(PG8_SB(1, 1), b3 + hstep);
;             PG8_WAIT_V(6); PG8_BAR; PG8_MMA(1, 1, At, B1); PG8_BAR;
;         }
;     template <bool LN, int BJ, int LO, int HI> DI void batch(const f32x4 (&acc)[2][2][4][2], unsigned row0, unsigned col0, const f32x4 (&gv)[2], const f32x4 (&bv)[2]) const {
;         f32x4 r[HI - LO]; float mean[(HI - LO) / 2], rstd[(HI - LO) / 2];
; #pragma unroll
;         for (int i = LO; i < HI; ++i) { const int ai = i >> 3, m = (i >> 1) & 3, n = i & 1; const unsigned row = row0 + ai * HALF + m * 16;
;             if (n == 0) { mean[(i - LO) >> 1] = 0.f; rstd[(i - LO) >> 1] = 1.f;
;                 if (LN) { const float2 st = *(const float2*)(stats + row * 2u); mean[(i - LO) >> 1] = st.x; rstd[(i - LO) >> 1] = st.y; } }
;             r[i - LO] = *(const f32x4*)(src + (row * (unsigned)DM + col0 + BJ * HALF + n * 16)); }
; #pragma unroll
;         for (int i = LO; i < HI; ++i) { const int ai = i >> 3, m = (i >> 1) & 3, n = i & 1; const unsigned row = row0 + ai * HALF + m * 16;
;             *(f32x4*)(Y + (row * (unsigned)DM + col0 + BJ * HALF + n * 16)) = acc[ai][BJ][m][n] + ((r[i - LO] - mean[(i - LO) >> 1]) * rstd[(i - LO) >> 1]) * gv[n] + bv[n]; }
;         __builtin_amdgcn_sched_barrier(0);
;     }
;     template <bool LN, int BJ> DI void load_gb(unsigned col0, f32x4 (&gv)[2], f32x4 (&bv)[2]) const {
; #pragma unroll
;         for (int n = 0; n < 2; ++n) {
;             if (LN) { gv[n] = *(const f32x4*)(gam + col0 + BJ * HALF + n * 16) * ALPHA; bv[n] = *(const f32x4*)(bet + col0 + BJ * HALF + n * 16) * ALPHA; }
;             else { gv[n] = (f32x4){ALPHA, ALPHA, ALPHA, ALPHA}; bv[n] = (f32x4){0.f, 0.f, 0.f, 0.f}; }
;         }
;     }
;     template <bool LN> DI void run(const f32x4 (&acc)[2][2][4][2], const Unit& u, int wr, int wc, int fr, int fq) const {
;         const unsigned row0 = u.pm * BM + wr * 64 + fr, col0 = u.pn * BM + wc * 32 + 4 * fq;
;         f32x4 gv[2], bv[2];
;         load_gb<LN, 0>(col0, gv, bv);
;         batch<LN, 0, 0, 4>(acc, row0, col0, gv, bv);
	v_mfma_f32_16x16x32_bf16 v[92:95], v[128:131], v[144:147], v[92:95]
	v_mfma_f32_16x16x32_bf16 v[88:91], v[136:139], v[144:147], v[88:91]
	v_mfma_f32_16x16x32_bf16 v[84:87], v[128:131], v[152:155], v[84:87]
	v_mfma_f32_16x16x32_bf16 v[80:83], v[136:139], v[152:155], v[80:83]
	v_mfma_f32_16x16x32_bf16 v[76:79], v[128:131], v[198:201], v[76:79]
	v_mfma_f32_16x16x32_bf16 v[72:75], v[136:139], v[198:201], v[72:75]
	v_mfma_f32_16x16x32_bf16 v[68:71], v[128:131], v[206:209], v[68:71]
	v_mfma_f32_16x16x32_bf16 v[64:67], v[136:139], v[206:209], v[64:67]
	v_mfma_f32_16x16x32_bf16 v[92:95], v[132:135], v[148:151], v[92:95]
	v_mfma_f32_16x16x32_bf16 v[88:91], v[140:143], v[148:151], v[88:91]
	v_mfma_f32_16x16x32_bf16 v[84:87], v[132:135], v[194:197], v[84:87]
	v_mfma_f32_16x16x32_bf16 v[80:83], v[140:143], v[194:197], v[80:83]
	v_mfma_f32_16x16x32_bf16 v[76:79], v[132:135], v[202:205], v[76:79]
	v_mfma_f32_16x16x32_bf16 v[72:75], v[140:143], v[202:205], v[72:75]
	v_mfma_f32_16x16x32_bf16 v[68:71], v[132:135], v[210:213], v[68:71]
	s_setprio 0
	v_mfma_f32_16x16x32_bf16 v[64:67], v[140:143], v[210:213], v[64:67]
	s_barrier
	s_add_u32 s24, s28, 0x80080
	s_addc_u32 s25, s29, 0
	s_add_i32 s28, s30, s37
	s_mov_b32 m0, s28
	s_nop 0
	global_load_lds_dwordx4 v188, s[24:25]
	s_add_i32 m0, s28, 0x2000
	s_nop 0
	global_load_lds_dwordx4 v186, s[24:25]
	s_waitcnt vmcnt(6)
	s_setprio 1
	s_barrier
	v_mfma_f32_16x16x32_bf16 v[28:31], v[214:217], v[144:147], v[28:31]
	v_mfma_f32_16x16x32_bf16 v[24:27], v[234:237], v[144:147], v[24:27]
	v_mfma_f32_16x16x32_bf16 v[20:23], v[214:217], v[152:155], v[20:23]
	v_mfma_f32_16x16x32_bf16 v[16:19], v[234:237], v[152:155], v[16:19]
	v_mfma_f32_16x16x32_bf16 v[12:15], v[214:217], v[198:201], v[12:15]
	v_mfma_f32_16x16x32_bf16 v[8:11], v[234:237], v[198:201], v[8:11]
	v_mfma_f32_16x16x32_bf16 v[4:7], v[214:217], v[206:209], v[4:7]
	v_mfma_f32_16x16x32_bf16 v[0:3], v[234:237], v[206:209], v[0:3]
	v_mfma_f32_16x16x32_bf16 v[28:31], v[230:233], v[148:151], v[28:31]
	s_add_i32 s46, s46, 2
	v_mfma_f32_16x16x32_bf16 v[24:27], v[238:241], v[148:151], v[24:27]
	s_add_u32 s33, s33, 0x100
	v_mfma_f32_16x16x32_bf16 v[20:23], v[230:233], v[194:197], v[20:23]
	s_addc_u32 s45, s45, 0
	v_mfma_f32_16x16x32_bf16 v[16:19], v[238:241], v[194:197], v[16:19]
	s_cmp_gt_u32 s46, 29
	v_mfma_f32_16x16x32_bf16 v[12:15], v[230:233], v[202:205], v[12:15]
	s_mov_b64 s[24:25], s[26:27]
	v_mfma_f32_16x16x32_bf16 v[8:11], v[238:241], v[202:205], v[8:11]
	v_mfma_f32_16x16x32_bf16 v[4:7], v[230:233], v[210:213], v[4:7]
	s_setprio 0
	v_mfma_f32_16x16x32_bf16 v[0:3], v[238:241], v[210:213], v[0:3]
	s_barrier
	s_cbranch_scc0 .LBB0_320
	v_lshl_add_u32 v206, s3, 8, v225
	v_lshl_or_b32 v158, s2, 8, v227
	v_lshlrev_b32_e32 v232, 11, v206
	s_andn2_b64 vcc, exec, s[14:15]
	v_or_b32_e32 v231, 16, v158
	v_add_u32_e32 v194, v232, v158
	v_or_b32_e32 v230, 0x80, v158
	v_or_b32_e32 v229, 0x90, v158
	s_cbranch_vccnz .LBB0_323
	v_lshlrev_b64 v[132:133], 2, v[158:159]
	v_lshl_add_u64 v[140:141], s[16:17], 0, v[132:133]
	global_load_dwordx4 v[128:131], v[140:141], off
	v_lshl_add_u64 v[142:143], s[18:19], 0, v[132:133]
	v_readlane_b32 s2, v253, 8
	v_mov_b32_e32 v195, v159
	v_lshlrev_b32_e32 v136, 1, v206
	v_mov_b32_e32 v137, v159
	v_readlane_b32 s3, v253, 9
	v_lshlrev_b64 v[212:213], 2, v[194:195]
	v_add_u32_e32 v146, v232, v231
	v_lshl_add_u64 v[144:145], v[136:137], 2, s[2:3]
	v_lshl_add_u64 v[136:137], s[88:89], 0, v[212:213]
	v_mov_b32_e32 v147, v159
	v_lshl_add_u64 v[146:147], v[146:147], 2, s[88:89]
	v_or_b32_e32 v195, 16, v206
	v_mov_b32_e32 v201, v159
	v_mov_b32_e32 v209, v159
	v_lshl_add_u64 v[212:213], s[90:91], 0, v[212:213]
	s_waitcnt vmcnt(0)
	v_pk_mul_f32 v[152:153], v[130:131], s[78:79] op_sel_hi:[1,0]
	v_pk_mul_f32 v[154:155], v[128:129], s[78:79] op_sel_hi:[1,0]
	global_load_dwordx4 v[132:135], v[142:143], off
	global_load_dwordx4 v[128:131], v[140:141], off offset:64
	global_load_dwordx2 v[204:205], v[144:145], off
	global_load_dwordx4 v[196:199], v[146:147], off
	v_lshlrev_b32_e32 v146, 1, v195
	global_load_dwordx4 v[136:139], v[136:137], off
	v_lshlrev_b32_e32 v195, 11, v195
	v_mov_b32_e32 v147, v159
	v_add_u32_e32 v200, v195, v158
	v_lshl_add_u64 v[146:147], v[146:147], 2, s[2:3]
	v_lshl_add_u64 v[200:201], v[200:201], 2, s[88:89]
	global_load_dwordx2 v[214:215], v[146:147], off
	v_add_u32_e32 v208, v195, v231
	global_load_dwordx4 v[200:203], v[200:201], off
	v_lshl_add_u64 v[208:209], v[208:209], 2, s[88:89]
	global_load_dwordx4 v[208:211], v[208:209], off
	s_waitcnt vmcnt(0)
	v_pk_mul_f32 v[148:149], v[130:131], s[78:79] op_sel_hi:[1,0]
	v_pk_mul_f32 v[150:151], v[128:129], s[78:79] op_sel_hi:[1,0]
	global_load_dwordx4 v[128:131], v[142:143], off offset:64
	v_sub_f32_e32 v137, v137, v204
	v_sub_f32_e32 v136, v136, v204
	v_sub_f32_e32 v139, v139, v204
	v_sub_f32_e32 v138, v138, v204
	v_pk_mul_f32 v[138:139], v[204:205], v[138:139] op_sel:[1,0]
	v_pk_mul_f32 v[136:137], v[204:205], v[136:137] op_sel:[1,0]
	v_pk_fma_f32 v[138:139], v[152:153], v[138:139], v[126:127]
	v_pk_fma_f32 v[136:137], v[154:155], v[136:137], v[124:125]
	v_pk_fma_f32 v[138:139], v[134:135], s[78:79], v[138:139] op_sel_hi:[1,0,1]
	v_pk_fma_f32 v[136:137], v[132:133], s[78:79], v[136:137] op_sel_hi:[1,0,1]
	global_store_dwordx4 v[212:213], v[136:139], off
	s_nop 1
	v_sub_f32_e32 v137, v197, v204
	v_sub_f32_e32 v136, v196, v204
	v_sub_f32_e32 v139, v199, v204
	v_sub_f32_e32 v138, v198, v204
	v_pk_mul_f32 v[138:139], v[204:205], v[138:139] op_sel:[1,0]
	v_pk_mul_f32 v[136:137], v[204:205], v[136:137] op_sel:[1,0]
	v_pk_fma_f32 v[138:139], v[148:149], v[138:139], v[122:123]
	v_pk_fma_f32 v[136:137], v[150:151], v[136:137], v[120:121]
	v_or_b32_e32 v196, 16, v194
	v_mov_b32_e32 v197, v159
	v_lshl_add_u64 v[196:197], v[196:197], 2, s[90:91]
	s_waitcnt vmcnt(0)
;     template <bool LN, int BJ, int LO, int HI> DI void batch(const f32x4 (&acc)[2][2][4][2], unsigned row0, unsigned col0, const f32x4 (&gv)[2], const f32x4 (&bv)[2]) const {
;         f32x4 r[HI - LO]; float mean[(HI - LO) / 2], rstd[(HI - LO) / 2];
; #pragma unroll
;         for (int i = LO; i < HI; ++i) { const int ai = i >> 3, m = (i >> 1) & 3, n = i & 1; const unsigned row = row0 + ai * HALF + m * 16;
;             if (n == 0) { mean[(i - LO) >> 1] = 0.f; rstd[(i - LO) >> 1] = 1.f;
;                 if (LN) { const float2 st = *(const float2*)(stats + row * 2u); mean[(i - LO) >> 1] = st.x; rstd[(i - LO) >> 1] = st.y; } }
;             r[i - LO] = *(const f32x4*)(src + (row * (unsigned)DM + col0 + BJ * HALF + n * 16)); }
; #pragma unroll
;         for (int i = LO; i < HI; ++i) { const int ai = i >> 3, m = (i >> 1) & 3, n = i & 1; const unsigned row = row0 + ai * HALF + m * 16;
;             *(f32x4*)(Y + (row * (unsigned)DM + col0 + BJ * HALF + n * 16)) = acc[ai][BJ][m][n] + ((r[i - LO] - mean[(i - LO) >> 1]) * rstd[(i - LO) >> 1]) * gv[n] + bv[n]; }
;         __builtin_amdgcn_sched_barrier(0);
;     }
;     template <bool LN, int BJ> DI void load_gb(unsigned col0, f32x4 (&gv)[2], f32x4 (&bv)[2]) const {
; #pragma unroll
;         for (int n = 0; n < 2; ++n) {
;             if (LN) { gv[n] = *(const f32x4*)(gam + col0 + BJ * HALF + n * 16) * ALPHA; bv[n] = *(const f32x4*)(bet + col0 + BJ * HALF + n * 16) * ALPHA; }
;             else { gv[n] = (f32x4){ALPHA, ALPHA, ALPHA, ALPHA}; bv[n] = (f32x4){0.f, 0.f, 0.f, 0.f}; }
;         }
;     }
;     template <bool LN> DI void run(const f32x4 (&acc)[2][2][4][2], const Unit& u, int wr, int wc, int fr, int fq) const {
;         const unsigned row0 = u.pm * BM + wr * 64 + fr, col0 = u.pn * BM + wc * 32 + 4 * fq;
;         f32x4 gv[2], bv[2];
;         load_gb<LN, 0>(col0, gv, bv);
;         batch<LN, 0, 0, 4>(acc, row0, col0, gv, bv);
;         batch<LN, 0, 4, 8>(acc, row0, col0, gv, bv);
;         batch<LN, 0, 8, 12>(acc, row0, col0, gv, bv);
;         batch<LN, 0, 12, 16>(acc, row0, col0, gv, bv);
	v_pk_fma_f32 v[138:139], v[130:131], s[78:79], v[138:139] op_sel_hi:[1,0,1]
	v_pk_fma_f32 v[136:137], v[128:129], s[78:79], v[136:137] op_sel_hi:[1,0,1]
	global_store_dwordx4 v[196:197], v[136:139], off
	v_add_u32_e32 v196, 0x8000, v194
	v_mov_b32_e32 v197, v159
	v_sub_f32_e32 v137, v201, v214
	v_sub_f32_e32 v136, v200, v214
	v_sub_f32_e32 v139, v203, v214
	v_sub_f32_e32 v138, v202, v214
	v_pk_mul_f32 v[138:139], v[214:215], v[138:139] op_sel:[1,0]
	v_pk_mul_f32 v[136:137], v[214:215], v[136:137] op_sel:[1,0]
	v_pk_fma_f32 v[138:139], v[152:153], v[138:139], v[118:119]
	v_pk_fma_f32 v[136:137], v[154:155], v[136:137], v[116:117]
	v_pk_fma_f32 v[138:139], v[134:135], s[78:79], v[138:139] op_sel_hi:[1,0,1]
	v_pk_fma_f32 v[136:137], v[132:133], s[78:79], v[136:137] op_sel_hi:[1,0,1]
	v_lshl_add_u64 v[196:197], v[196:197], 2, s[90:91]
	global_store_dwordx4 v[196:197], v[136:139], off
	v_add_u32_e32 v196, 0x8010, v194
	v_mov_b32_e32 v197, v159
	v_sub_f32_e32 v137, v209, v214
	v_sub_f32_e32 v136, v208, v214
	v_sub_f32_e32 v139, v211, v214
	v_sub_f32_e32 v138, v210, v214
	v_pk_mul_f32 v[138:139], v[214:215], v[138:139] op_sel:[1,0]
	v_pk_mul_f32 v[136:137], v[214:215], v[136:137] op_sel:[1,0]
	v_pk_fma_f32 v[138:139], v[148:149], v[138:139], v[114:115]
	v_pk_fma_f32 v[136:137], v[150:151], v[136:137], v[112:113]
	v_pk_fma_f32 v[138:139], v[130:131], s[78:79], v[138:139] op_sel_hi:[1,0,1]
	v_pk_fma_f32 v[136:137], v[128:129], s[78:79], v[136:137] op_sel_hi:[1,0,1]
	v_lshl_add_u64 v[196:197], v[196:197], 2, s[90:91]
	global_store_dwordx4 v[196:197], v[136:139], off
	s_nop 1
	v_or_b32_e32 v138, 32, v206
	v_lshlrev_b32_e32 v136, 1, v138
	v_mov_b32_e32 v137, v159
	v_lshlrev_b32_e32 v236, 11, v138
	v_lshl_add_u64 v[200:201], v[136:137], 2, s[2:3]
	v_add_u32_e32 v136, v236, v158
	v_lshl_add_u64 v[136:137], v[136:137], 2, s[88:89]
	global_load_dwordx2 v[204:205], v[200:201], off
	v_add_u32_e32 v196, v236, v231
	global_load_dwordx4 v[136:139], v[136:137], off
	v_mov_b32_e32 v197, v159
	v_lshl_add_u64 v[196:197], v[196:197], 2, s[88:89]
	global_load_dwordx4 v[196:199], v[196:197], off
	v_or_b32_e32 v207, 48, v206
	v_lshlrev_b32_e32 v235, 11, v207
	v_lshlrev_b32_e32 v202, 1, v207
	v_mov_b32_e32 v203, v159
	v_add_u32_e32 v208, v235, v158
	v_mov_b32_e32 v209, v159
	v_lshl_add_u64 v[202:203], v[202:203], 2, s[2:3]
	v_lshl_add_u64 v[208:209], v[208:209], 2, s[88:89]
	global_load_dwordx2 v[216:217], v[202:203], off
	v_add_u32_e32 v212, v235, v231
	global_load_dwordx4 v[208:211], v[208:209], off
	v_mov_b32_e32 v213, v159
	v_lshl_add_u64 v[212:213], v[212:213], 2, s[88:89]
	global_load_dwordx4 v[212:215], v[212:213], off
	v_add_u32_e32 v218, 0x10000, v194
	v_mov_b32_e32 v219, v159
	v_lshl_add_u64 v[218:219], v[218:219], 2, s[90:91]
	s_waitcnt vmcnt(0)
	v_sub_f32_e32 v137, v137, v204
	v_sub_f32_e32 v136, v136, v204
	v_sub_f32_e32 v139, v139, v204
	v_sub_f32_e32 v138, v138, v204
	v_pk_mul_f32 v[138:139], v[204:205], v[138:139] op_sel:[1,0]
	v_pk_mul_f32 v[136:137], v[204:205], v[136:137] op_sel:[1,0]
	v_pk_fma_f32 v[138:139], v[152:153], v[138:139], v[110:111]
	v_pk_fma_f32 v[136:137], v[154:155], v[136:137], v[108:109]
	v_pk_fma_f32 v[138:139], v[134:135], s[78:79], v[138:139] op_sel_hi:[1,0,1]
	v_pk_fma_f32 v[136:137], v[132:133], s[78:79], v[136:137] op_sel_hi:[1,0,1]
	global_store_dwordx4 v[218:219], v[136:139], off
	s_nop 1
	v_sub_f32_e32 v137, v197, v204
	v_sub_f32_e32 v136, v196, v204
	v_sub_f32_e32 v139, v199, v204
	v_sub_f32_e32 v138, v198, v204
	v_pk_mul_f32 v[138:139], v[204:205], v[138:139] op_sel:[1,0]
	v_pk_mul_f32 v[136:137], v[204:205], v[136:137] op_sel:[1,0]
	v_pk_fma_f32 v[138:139], v[148:149], v[138:139], v[106:107]
	v_pk_fma_f32 v[136:137], v[150:151], v[136:137], v[104:105]
	v_add_u32_e32 v196, 0x10010, v194
	v_mov_b32_e32 v197, v159
	v_pk_fma_f32 v[138:139], v[130:131], s[78:79], v[138:139] op_sel_hi:[1,0,1]
	v_pk_fma_f32 v[136:137], v[128:129], s[78:79], v[136:137] op_sel_hi:[1,0,1]
	v_lshl_add_u64 v[196:197], v[196:197], 2, s[90:91]
	global_store_dwordx4 v[196:197], v[136:139], off
	v_add_u32_e32 v196, 0x18000, v194
	v_mov_b32_e32 v197, v159
	v_sub_f32_e32 v137, v209, v216
	v_sub_f32_e32 v136, v208, v216
	v_sub_f32_e32 v139, v211, v216
	v_sub_f32_e32 v138, v210, v216
	v_pk_mul_f32 v[138:139], v[216:217], v[138:139] op_sel:[1,0]
	v_pk_mul_f32 v[136:137], v[216:217], v[136:137] op_sel:[1,0]
	v_pk_fma_f32 v[138:139], v[152:153], v[138:139], v[102:103]
	v_pk_fma_f32 v[136:137], v[154:155], v[136:137], v[100:101]
	v_pk_fma_f32 v[138:139], v[134:135], s[78:79], v[138:139] op_sel_hi:[1,0,1]
	v_pk_fma_f32 v[136:137], v[132:133], s[78:79], v[136:137] op_sel_hi:[1,0,1]
	v_lshl_add_u64 v[196:197], v[196:197], 2, s[90:91]
	global_store_dwordx4 v[196:197], v[136:139], off
	v_add_u32_e32 v196, 0x18010, v194
	v_mov_b32_e32 v197, v159
	v_sub_f32_e32 v137, v213, v216
	v_sub_f32_e32 v136, v212, v216
	v_sub_f32_e32 v139, v215, v216
	v_sub_f32_e32 v138, v214, v216
	v_pk_mul_f32 v[138:139], v[216:217], v[138:139] op_sel:[1,0]
	v_pk_mul_f32 v[136:137], v[216:217], v[136:137] op_sel:[1,0]
	v_pk_fma_f32 v[138:139], v[148:149], v[138:139], v[98:99]
	v_pk_fma_f32 v[136:137], v[150:151], v[136:137], v[96:97]
	v_pk_fma_f32 v[138:139], v[130:131], s[78:79], v[138:139] op_sel_hi:[1,0,1]
	v_pk_fma_f32 v[136:137], v[128:129], s[78:79], v[136:137] op_sel_hi:[1,0,1]
	v_lshl_add_u64 v[196:197], v[196:197], 2, s[90:91]
	global_store_dwordx4 v[196:197], v[136:139], off
	s_nop 1
	v_add_u32_e32 v138, 0x80, v206
	v_lshlrev_b32_e32 v136, 1, v138
	v_mov_b32_e32 v137, v159
	v_lshlrev_b32_e32 v233, 11, v138
	v_lshl_add_u64 v[196:197], v[136:137], 2, s[2:3]
	v_add_u32_e32 v136, v233, v158
	v_lshl_add_u64 v[136:137], v[136:137], 2, s[88:89]
	global_load_dwordx2 v[204:205], v[196:197], off
	v_add_u32_e32 v198, v233, v231
	global_load_dwordx4 v[136:139], v[136:137], off
	v_mov_b32_e32 v199, v159
	v_add_u32_e32 v207, 0x90, v206
	v_lshl_add_u64 v[198:199], v[198:199], 2, s[88:89]
	v_lshlrev_b32_e32 v234, 11, v207
	global_load_dwordx4 v[208:211], v[198:199], off
	v_add_u32_e32 v212, v234, v158
	v_mov_b32_e32 v213, v159
	v_lshl_add_u64 v[212:213], v[212:213], 2, s[88:89]
	global_load_dwordx4 v[212:215], v[212:213], off
	v_lshlrev_b32_e32 v198, 1, v207
	v_mov_b32_e32 v199, v159
	v_lshl_add_u64 v[198:199], v[198:199], 2, s[2:3]
	global_load_dwordx2 v[238:239], v[198:199], off
	v_add_u32_e32 v216, v234, v231
	v_mov_b32_e32 v217, v159
	v_lshl_add_u64 v[216:217], v[216:217], 2, s[88:89]
	global_load_dwordx4 v[216:219], v[216:217], off
	v_add_u32_e32 v240, 0x40000, v194
	v_mov_b32_e32 v241, v159
	v_lshl_add_u64 v[240:241], v[240:241], 2, s[90:91]
	s_waitcnt vmcnt(0)
;     template <bool LN, int BJ, int LO, int HI> DI void batch(const f32x4 (&acc)[2][2][4][2], unsigned row0, unsigned col0, const f32x4 (&gv)[2], const f32x4 (&bv)[2]) const {
;         f32x4 r[HI - LO]; float mean[(HI - LO) / 2], rstd[(HI - LO) / 2];
; #pragma unroll
;         for (int i = LO; i < HI; ++i) { const int ai = i >> 3, m = (i >> 1) & 3, n = i & 1; const unsigned row = row0 + ai * HALF + m * 16;
;             if (n == 0) { mean[(i - LO) >> 1] = 0.f; rstd[(i - LO) >> 1] = 1.f;
;                 if (LN) { const float2 st = *(const float2*)(stats + row * 2u); mean[(i - LO) >> 1] = st.x; rstd[(i - LO) >> 1] = st.y; } }
;             r[i - LO] = *(const f32x4*)(src + (row * (unsigned)DM + col0 + BJ * HALF + n * 16)); }
; #pragma unroll
;         for (int i = LO; i < HI; ++i) { const int ai = i >> 3, m = (i >> 1) & 3, n = i & 1; const unsigned row = row0 + ai * HALF + m * 16;
;             *(f32x4*)(Y + (row * (unsigned)DM + col0 + BJ * HALF + n * 16)) = acc[ai][BJ][m][n] + ((r[i - LO] - mean[(i - LO) >> 1]) * rstd[(i - LO) >> 1]) * gv[n] + bv[n]; }
;         __builtin_amdgcn_sched_barrier(0);
;     }
;     template <bool LN, int BJ> DI void load_gb(unsigned col0, f32x4 (&gv)[2], f32x4 (&bv)[2]) const {
; #pragma unroll
;         for (int n = 0; n < 2; ++n) {
;             if (LN) { gv[n] = *(const f32x4*)(gam + col0 + BJ * HALF + n * 16) * ALPHA; bv[n] = *(const f32x4*)(bet + col0 + BJ * HALF + n * 16) * ALPHA; }
;             else { gv[n] = (f32x4){ALPHA, ALPHA, ALPHA, ALPHA}; bv[n] = (f32x4){0.f, 0.f, 0.f, 0.f}; }
;         }
;     }
;     template <bool LN> DI void run(const f32x4 (&acc)[2][2][4][2], const Unit& u, int wr, int wc, int fr, int fq) const {
;         const unsigned row0 = u.pm * BM + wr * 64 + fr, col0 = u.pn * BM + wc * 32 + 4 * fq;
;         f32x4 gv[2], bv[2];
;         load_gb<LN, 0>(col0, gv, bv);
;         batch<LN, 0, 0, 4>(acc, row0, col0, gv, bv);
;         batch<LN, 0, 4, 8>(acc, row0, col0, gv, bv);
;         batch<LN, 0, 8, 12>(acc, row0, col0, gv, bv);
;         batch<LN, 0, 12, 16>(acc, row0, col0, gv, bv);
	v_sub_f32_e32 v137, v137, v204
	v_sub_f32_e32 v136, v136, v204
	v_sub_f32_e32 v139, v139, v204
	v_sub_f32_e32 v138, v138, v204
	v_pk_mul_f32 v[138:139], v[204:205], v[138:139] op_sel:[1,0]
	v_pk_mul_f32 v[136:137], v[204:205], v[136:137] op_sel:[1,0]
	v_pk_fma_f32 v[138:139], v[152:153], v[138:139], v[94:95]
	v_pk_fma_f32 v[136:137], v[154:155], v[136:137], v[92:93]
	v_pk_fma_f32 v[138:139], v[134:135], s[78:79], v[138:139] op_sel_hi:[1,0,1]
	v_pk_fma_f32 v[136:137], v[132:133], s[78:79], v[136:137] op_sel_hi:[1,0,1]
	global_store_dwordx4 v[240:241], v[136:139], off
	s_nop 1
	v_sub_f32_e32 v137, v209, v204
	v_sub_f32_e32 v136, v208, v204
	v_sub_f32_e32 v139, v211, v204
	v_sub_f32_e32 v138, v210, v204
	v_pk_mul_f32 v[138:139], v[204:205], v[138:139] op_sel:[1,0]
	v_pk_mul_f32 v[136:137], v[204:205], v[136:137] op_sel:[1,0]
	v_pk_fma_f32 v[138:139], v[148:149], v[138:139], v[90:91]
	v_pk_fma_f32 v[136:137], v[150:151], v[136:137], v[88:89]
	v_add_u32_e32 v204, 0x40010, v194
	v_mov_b32_e32 v205, v159
	v_pk_fma_f32 v[138:139], v[130:131], s[78:79], v[138:139] op_sel_hi:[1,0,1]
	v_pk_fma_f32 v[136:137], v[128:129], s[78:79], v[136:137] op_sel_hi:[1,0,1]
	v_lshl_add_u64 v[204:205], v[204:205], 2, s[90:91]
	global_store_dwordx4 v[204:205], v[136:139], off
	v_add_u32_e32 v204, 0x48000, v194
	v_mov_b32_e32 v205, v159
	v_sub_f32_e32 v137, v213, v238
	v_sub_f32_e32 v136, v212, v238
	v_sub_f32_e32 v139, v215, v238
	v_sub_f32_e32 v138, v214, v238
	v_pk_mul_f32 v[138:139], v[238:239], v[138:139] op_sel:[1,0]
	v_pk_mul_f32 v[136:137], v[238:239], v[136:137] op_sel:[1,0]
	v_pk_fma_f32 v[138:139], v[152:153], v[138:139], v[86:87]
	v_pk_fma_f32 v[136:137], v[154:155], v[136:137], v[84:85]
	v_pk_fma_f32 v[138:139], v[134:135], s[78:79], v[138:139] op_sel_hi:[1,0,1]
	v_pk_fma_f32 v[136:137], v[132:133], s[78:79], v[136:137] op_sel_hi:[1,0,1]
	v_lshl_add_u64 v[204:205], v[204:205], 2, s[90:91]
	global_store_dwordx4 v[204:205], v[136:139], off
	v_add_u32_e32 v204, 0x48010, v194
	v_mov_b32_e32 v205, v159
	v_sub_f32_e32 v137, v217, v238
	v_sub_f32_e32 v136, v216, v238
	v_sub_f32_e32 v139, v219, v238
	v_sub_f32_e32 v138, v218, v238
	v_pk_mul_f32 v[138:139], v[238:239], v[138:139] op_sel:[1,0]
	v_pk_mul_f32 v[136:137], v[238:239], v[136:137] op_sel:[1,0]
	v_pk_fma_f32 v[138:139], v[148:149], v[138:139], v[82:83]
	v_pk_fma_f32 v[136:137], v[150:151], v[136:137], v[80:81]
	v_pk_fma_f32 v[138:139], v[130:131], s[78:79], v[138:139] op_sel_hi:[1,0,1]
	v_pk_fma_f32 v[136:137], v[128:129], s[78:79], v[136:137] op_sel_hi:[1,0,1]
	v_lshl_add_u64 v[204:205], v[204:205], 2, s[90:91]
	global_store_dwordx4 v[204:205], v[136:139], off
	s_nop 1
	v_add_u32_e32 v138, 0xa0, v206
	v_lshlrev_b32_e32 v136, 1, v138
	v_mov_b32_e32 v137, v159
	v_lshlrev_b32_e32 v237, 11, v138
	v_lshl_add_u64 v[204:205], v[136:137], 2, s[2:3]
	v_add_u32_e32 v136, v237, v158
	v_lshl_add_u64 v[136:137], v[136:137], 2, s[88:89]
	global_load_dwordx2 v[240:241], v[204:205], off
	v_add_u32_e32 v208, v237, v231
	global_load_dwordx4 v[136:139], v[136:137], off
	v_mov_b32_e32 v209, v159
	v_lshl_add_u64 v[208:209], v[208:209], 2, s[88:89]
	global_load_dwordx4 v[212:215], v[208:209], off
	v_add_u32_e32 v208, 0xb0, v206
	v_lshlrev_b32_e32 v206, 1, v208
	v_mov_b32_e32 v207, v159
	v_lshlrev_b32_e32 v238, 11, v208
	v_lshl_add_u64 v[210:211], v[206:207], 2, s[2:3]
	v_add_u32_e32 v206, v238, v158
	v_lshl_add_u64 v[206:207], v[206:207], 2, s[88:89]
	global_load_dwordx2 v[242:243], v[210:211], off
	v_add_u32_e32 v216, v238, v231
	global_load_dwordx4 v[206:209], v[206:207], off
	v_mov_b32_e32 v217, v159
	v_lshl_add_u64 v[216:217], v[216:217], 2, s[88:89]
	global_load_dwordx4 v[216:219], v[216:217], off
	v_add_u32_e32 v244, 0x50000, v194
	v_mov_b32_e32 v245, v159
	v_lshl_add_u64 v[244:245], v[244:245], 2, s[90:91]
	s_waitcnt vmcnt(0)
	v_sub_f32_e32 v137, v137, v240
	v_sub_f32_e32 v136, v136, v240
	v_sub_f32_e32 v139, v139, v240
	v_sub_f32_e32 v138, v138, v240
	v_pk_mul_f32 v[138:139], v[240:241], v[138:139] op_sel:[1,0]
	v_pk_mul_f32 v[136:137], v[240:241], v[136:137] op_sel:[1,0]
	v_pk_fma_f32 v[138:139], v[152:153], v[138:139], v[78:79]
	v_pk_fma_f32 v[136:137], v[154:155], v[136:137], v[76:77]
	v_pk_fma_f32 v[138:139], v[134:135], s[78:79], v[138:139] op_sel_hi:[1,0,1]
	v_pk_fma_f32 v[136:137], v[132:133], s[78:79], v[136:137] op_sel_hi:[1,0,1]
	global_store_dwordx4 v[244:245], v[136:139], off
	s_nop 1
	v_sub_f32_e32 v137, v213, v240
	v_sub_f32_e32 v136, v212, v240
	v_sub_f32_e32 v139, v215, v240
	v_sub_f32_e32 v138, v214, v240
	v_pk_mul_f32 v[138:139], v[240:241], v[138:139] op_sel:[1,0]
	v_pk_mul_f32 v[136:137], v[240:241], v[136:137] op_sel:[1,0]
	v_pk_fma_f32 v[138:139], v[148:149], v[138:139], v[74:75]
	v_pk_fma_f32 v[136:137], v[150:151], v[136:137], v[72:73]
	v_add_u32_e32 v212, 0x50010, v194
	v_mov_b32_e32 v213, v159
	v_pk_fma_f32 v[138:139], v[130:131], s[78:79], v[138:139] op_sel_hi:[1,0,1]
	v_pk_fma_f32 v[136:137], v[128:129], s[78:79], v[136:137] op_sel_hi:[1,0,1]
	v_lshl_add_u64 v[212:213], v[212:213], 2, s[90:91]
	global_store_dwordx4 v[212:213], v[136:139], off
	s_nop 1
	v_sub_f32_e32 v137, v207, v242
	v_sub_f32_e32 v136, v206, v242
	v_sub_f32_e32 v139, v209, v242
	v_sub_f32_e32 v138, v208, v242
	v_pk_mul_f32 v[136:137], v[242:243], v[136:137] op_sel:[1,0]
	v_pk_mul_f32 v[138:139], v[242:243], v[138:139] op_sel:[1,0]
	v_pk_fma_f32 v[136:137], v[154:155], v[136:137], v[68:69]
	v_pk_fma_f32 v[138:139], v[152:153], v[138:139], v[70:71]
	v_pk_fma_f32 v[132:133], v[132:133], s[78:79], v[136:137] op_sel_hi:[1,0,1]
	v_add_u32_e32 v136, 0x58000, v194
	v_mov_b32_e32 v137, v159
	v_pk_fma_f32 v[134:135], v[134:135], s[78:79], v[138:139] op_sel_hi:[1,0,1]
	v_lshl_add_u64 v[136:137], v[136:137], 2, s[90:91]
	global_store_dwordx4 v[136:137], v[132:135], off
	s_nop 1
	v_sub_f32_e32 v133, v217, v242
	v_sub_f32_e32 v132, v216, v242
	v_sub_f32_e32 v135, v219, v242
	v_sub_f32_e32 v134, v218, v242
	v_pk_mul_f32 v[132:133], v[242:243], v[132:133] op_sel:[1,0]
	v_pk_mul_f32 v[134:135], v[242:243], v[134:135] op_sel:[1,0]
	v_pk_fma_f32 v[132:133], v[150:151], v[132:133], v[64:65]
	v_pk_fma_f32 v[134:135], v[148:149], v[134:135], v[66:67]
	v_pk_fma_f32 v[128:129], v[128:129], s[78:79], v[132:133] op_sel_hi:[1,0,1]
	v_add_u32_e32 v132, 0x58010, v194
	v_mov_b32_e32 v133, v159
	v_pk_fma_f32 v[130:131], v[130:131], s[78:79], v[134:135] op_sel_hi:[1,0,1]
	v_lshl_add_u64 v[132:133], v[132:133], 2, s[90:91]
	global_store_dwordx4 v[132:133], v[128:131], off
	global_load_dwordx4 v[128:131], v[140:141], off offset:512
	v_add_u32_e32 v136, v232, v230
	v_mov_b32_e32 v137, v159
	v_lshl_add_u64 v[136:137], v[136:137], 2, s[88:89]
	s_waitcnt vmcnt(0)
;     template <bool LN, int BJ, int LO, int HI> DI void batch(const f32x4 (&acc)[2][2][4][2], unsigned row0, unsigned col0, const f32x4 (&gv)[2], const f32x4 (&bv)[2]) const {
;         f32x4 r[HI - LO]; float mean[(HI - LO) / 2], rstd[(HI - LO) / 2];
; #pragma unroll
;         for (int i = LO; i < HI; ++i) { const int ai = i >> 3, m = (i >> 1) & 3, n = i & 1; const unsigned row = row0 + ai * HALF + m * 16;
;             if (n == 0) { mean[(i - LO) >> 1] = 0.f; rstd[(i - LO) >> 1] = 1.f;
;                 if (LN) { const float2 st = *(const float2*)(stats + row * 2u); mean[(i - LO) >> 1] = st.x; rstd[(i - LO) >> 1] = st.y; } }
;             r[i - LO] = *(const f32x4*)(src + (row * (unsigned)DM + col0 + BJ * HALF + n * 16)); }
; #pragma unroll
;         for (int i = LO; i < HI; ++i) { const int ai = i >> 3, m = (i >> 1) & 3, n = i & 1; const unsigned row = row0 + ai * HALF + m * 16;
;             *(f32x4*)(Y + (row * (unsigned)DM + col0 + BJ * HALF + n * 16)) = acc[ai][BJ][m][n] + ((r[i - LO] - mean[(i - LO) >> 1]) * rstd[(i - LO) >> 1]) * gv[n] + bv[n]; }
;         __builtin_amdgcn_sched_barrier(0);
;     }
;     template <bool LN, int BJ> DI void load_gb(unsigned col0, f32x4 (&gv)[2], f32x4 (&bv)[2]) const {
; #pragma unroll
;         for (int n = 0; n < 2; ++n) {
;             if (LN) { gv[n] = *(const f32x4*)(gam + col0 + BJ * HALF + n * 16) * ALPHA; bv[n] = *(const f32x4*)(bet + col0 + BJ * HALF + n * 16) * ALPHA; }
;             else { gv[n] = (f32x4){ALPHA, ALPHA, ALPHA, ALPHA}; bv[n] = (f32x4){0.f, 0.f, 0.f, 0.f}; }
;         }
;     }
;     template <bool LN> DI void run(const f32x4 (&acc)[2][2][4][2], const Unit& u, int wr, int wc, int fr, int fq) const {
;         const unsigned row0 = u.pm * BM + wr * 64 + fr, col0 = u.pn * BM + wc * 32 + 4 * fq;
;         f32x4 gv[2], bv[2];
;         load_gb<LN, 0>(col0, gv, bv);
;         batch<LN, 0, 0, 4>(acc, row0, col0, gv, bv);
;         batch<LN, 0, 4, 8>(acc, row0, col0, gv, bv);
;         batch<LN, 0, 8, 12>(acc, row0, col0, gv, bv);
;         batch<LN, 0, 12, 16>(acc, row0, col0, gv, bv);
;         load_gb<LN, 1>(col0, gv, bv);
;         batch<LN, 1, 0, 8>(acc, row0, col0, gv, bv);
;         batch<LN, 1, 8, 16>(acc, row0, col0, gv, bv);
	v_pk_mul_f32 v[212:213], v[130:131], s[78:79] op_sel_hi:[1,0]
	v_pk_mul_f32 v[214:215], v[128:129], s[78:79] op_sel_hi:[1,0]
	global_load_dwordx4 v[132:135], v[142:143], off offset:512
	global_load_dwordx4 v[128:131], v[140:141], off offset:576
	s_waitcnt vmcnt(0)
	v_pk_mul_f32 v[206:207], v[130:131], s[78:79] op_sel_hi:[1,0]
	v_pk_mul_f32 v[208:209], v[128:129], s[78:79] op_sel_hi:[1,0]
	global_load_dwordx4 v[128:131], v[142:143], off offset:576
	global_load_dwordx2 v[220:221], v[144:145], off
	global_load_dwordx4 v[240:243], v[136:137], off
	v_add_u32_e32 v136, v232, v229
	v_mov_b32_e32 v137, v159
	v_lshl_add_u64 v[136:137], v[136:137], 2, s[88:89]
	global_load_dwordx4 v[244:247], v[136:137], off
	global_load_dwordx2 v[218:219], v[146:147], off
	v_add_u32_e32 v136, v195, v230
	v_mov_b32_e32 v137, v159
	v_lshl_add_u64 v[136:137], v[136:137], 2, s[88:89]
	global_load_dwordx4 v[248:251], v[136:137], off
	v_add_u32_e32 v136, v195, v229
	v_mov_b32_e32 v137, v159
	v_lshl_add_u64 v[136:137], v[136:137], 2, s[88:89]
	global_load_dwordx4 v[152:155], v[136:137], off
	global_load_dwordx2 v[216:217], v[200:201], off
	v_add_u32_e32 v136, v236, v230
	v_mov_b32_e32 v137, v159
	v_lshl_add_u64 v[136:137], v[136:137], 2, s[88:89]
	global_load_dwordx4 v[148:151], v[136:137], off
	v_add_u32_e32 v136, v236, v229
	v_mov_b32_e32 v137, v159
	v_lshl_add_u64 v[136:137], v[136:137], 2, s[88:89]
	global_load_dwordx4 v[144:147], v[136:137], off
	global_load_dwordx2 v[200:201], v[202:203], off
	v_add_u32_e32 v136, v235, v230
	v_mov_b32_e32 v137, v159
	v_lshl_add_u64 v[136:137], v[136:137], 2, s[88:89]
	global_load_dwordx4 v[140:143], v[136:137], off
	v_add_u32_e32 v136, v235, v229
	v_mov_b32_e32 v137, v159
	v_lshl_add_u64 v[136:137], v[136:137], 2, s[88:89]
	global_load_dwordx4 v[136:139], v[136:137], off
	v_add_u32_e32 v202, 0x80, v194
	v_mov_b32_e32 v203, v159
	v_lshl_add_u64 v[202:203], v[202:203], 2, s[90:91]
	s_waitcnt vmcnt(0)
	v_sub_f32_e32 v241, v241, v220
	v_sub_f32_e32 v240, v240, v220
	v_sub_f32_e32 v243, v243, v220
	v_sub_f32_e32 v242, v242, v220
	v_pk_mul_f32 v[242:243], v[220:221], v[242:243] op_sel:[1,0]
	v_pk_mul_f32 v[240:241], v[220:221], v[240:241] op_sel:[1,0]
	v_pk_fma_f32 v[242:243], v[212:213], v[242:243], v[62:63]
	v_pk_fma_f32 v[240:241], v[214:215], v[240:241], v[60:61]
	v_pk_fma_f32 v[242:243], v[134:135], s[78:79], v[242:243] op_sel_hi:[1,0,1]
	v_pk_fma_f32 v[240:241], v[132:133], s[78:79], v[240:241] op_sel_hi:[1,0,1]
	global_store_dwordx4 v[202:203], v[240:243], off
	v_sub_f32_e32 v203, v245, v220
	v_sub_f32_e32 v202, v244, v220
	v_sub_f32_e32 v241, v247, v220
	v_sub_f32_e32 v240, v246, v220
	v_pk_mul_f32 v[202:203], v[220:221], v[202:203] op_sel:[1,0]
	v_pk_mul_f32 v[240:241], v[220:221], v[240:241] op_sel:[1,0]
	v_pk_fma_f32 v[202:203], v[208:209], v[202:203], v[56:57]
	v_pk_fma_f32 v[220:221], v[206:207], v[240:241], v[58:59]
	v_pk_fma_f32 v[240:241], v[128:129], s[78:79], v[202:203] op_sel_hi:[1,0,1]
	v_add_u32_e32 v202, 0x90, v194
	v_mov_b32_e32 v203, v159
	v_pk_fma_f32 v[242:243], v[130:131], s[78:79], v[220:221] op_sel_hi:[1,0,1]
	v_lshl_add_u64 v[202:203], v[202:203], 2, s[90:91]
	global_store_dwordx4 v[202:203], v[240:243], off
	v_sub_f32_e32 v203, v249, v218
	v_sub_f32_e32 v202, v248, v218
	v_sub_f32_e32 v221, v251, v218
	v_sub_f32_e32 v220, v250, v218
	v_pk_mul_f32 v[202:203], v[218:219], v[202:203] op_sel:[1,0]
	v_pk_mul_f32 v[220:221], v[218:219], v[220:221] op_sel:[1,0]
	v_pk_fma_f32 v[202:203], v[214:215], v[202:203], v[52:53]
	v_pk_fma_f32 v[220:221], v[212:213], v[220:221], v[54:55]
	v_pk_fma_f32 v[240:241], v[132:133], s[78:79], v[202:203] op_sel_hi:[1,0,1]
	v_add_u32_e32 v202, 0x8080, v194
	v_mov_b32_e32 v203, v159
	v_sub_f32_e32 v153, v153, v218
	v_sub_f32_e32 v152, v152, v218
	v_sub_f32_e32 v155, v155, v218
	v_sub_f32_e32 v154, v154, v218
	v_pk_fma_f32 v[242:243], v[134:135], s[78:79], v[220:221] op_sel_hi:[1,0,1]
	v_lshl_add_u64 v[202:203], v[202:203], 2, s[90:91]
	v_pk_mul_f32 v[154:155], v[218:219], v[154:155] op_sel:[1,0]
	v_pk_mul_f32 v[152:153], v[218:219], v[152:153] op_sel:[1,0]
	global_store_dwordx4 v[202:203], v[240:243], off
	v_pk_fma_f32 v[152:153], v[208:209], v[152:153], v[48:49]
	v_pk_fma_f32 v[154:155], v[206:207], v[154:155], v[50:51]
	v_add_u32_e32 v202, 0x8090, v194
	v_mov_b32_e32 v203, v159
	v_sub_f32_e32 v149, v149, v216
	v_sub_f32_e32 v148, v148, v216
	v_sub_f32_e32 v151, v151, v216
	v_sub_f32_e32 v150, v150, v216
	v_pk_fma_f32 v[154:155], v[130:131], s[78:79], v[154:155] op_sel_hi:[1,0,1]
	v_pk_fma_f32 v[152:153], v[128:129], s[78:79], v[152:153] op_sel_hi:[1,0,1]
	v_lshl_add_u64 v[202:203], v[202:203], 2, s[90:91]
	v_pk_mul_f32 v[150:151], v[216:217], v[150:151] op_sel:[1,0]
	v_pk_mul_f32 v[148:149], v[216:217], v[148:149] op_sel:[1,0]
	global_store_dwordx4 v[202:203], v[152:155], off
	v_pk_fma_f32 v[148:149], v[214:215], v[148:149], v[44:45]
	v_pk_fma_f32 v[150:151], v[212:213], v[150:151], v[46:47]
	v_add_u32_e32 v152, 0x10080, v194
	v_mov_b32_e32 v153, v159
	v_sub_f32_e32 v145, v145, v216
	v_sub_f32_e32 v144, v144, v216
	v_sub_f32_e32 v147, v147, v216
	v_sub_f32_e32 v146, v146, v216
	v_pk_fma_f32 v[150:151], v[134:135], s[78:79], v[150:151] op_sel_hi:[1,0,1]
	v_pk_fma_f32 v[148:149], v[132:133], s[78:79], v[148:149] op_sel_hi:[1,0,1]
	v_lshl_add_u64 v[152:153], v[152:153], 2, s[90:91]
	v_pk_mul_f32 v[146:147], v[216:217], v[146:147] op_sel:[1,0]
	v_pk_mul_f32 v[144:145], v[216:217], v[144:145] op_sel:[1,0]
	global_store_dwordx4 v[152:153], v[148:151], off
	v_pk_fma_f32 v[144:145], v[208:209], v[144:145], v[40:41]
	v_pk_fma_f32 v[146:147], v[206:207], v[146:147], v[42:43]
;     template <bool LN, int BJ, int LO, int HI> DI void batch(const f32x4 (&acc)[2][2][4][2], unsigned row0, unsigned col0, const f32x4 (&gv)[2], const f32x4 (&bv)[2]) const {
;         f32x4 r[HI - LO]; float mean[(HI - LO) / 2], rstd[(HI - LO) / 2];
; #pragma unroll
;         for (int i = LO; i < HI; ++i) { const int ai = i >> 3, m = (i >> 1) & 3, n = i & 1; const unsigned row = row0 + ai * HALF + m * 16;
;             if (n == 0) { mean[(i - LO) >> 1] = 0.f; rstd[(i - LO) >> 1] = 1.f;
;                 if (LN) { const float2 st = *(const float2*)(stats + row * 2u); mean[(i - LO) >> 1] = st.x; rstd[(i - LO) >> 1] = st.y; } }
;             r[i - LO] = *(const f32x4*)(src + (row * (unsigned)DM + col0 + BJ * HALF + n * 16)); }
; #pragma unroll
;         for (int i = LO; i < HI; ++i) { const int ai = i >> 3, m = (i >> 1) & 3, n = i & 1; const unsigned row = row0 + ai * HALF + m * 16;
;             *(f32x4*)(Y + (row * (unsigned)DM + col0 + BJ * HALF + n * 16)) = acc[ai][BJ][m][n] + ((r[i - LO] - mean[(i - LO) >> 1]) * rstd[(i - LO) >> 1]) * gv[n] + bv[n]; }
;         __builtin_amdgcn_sched_barrier(0);
;     }
;     template <bool LN, int BJ> DI void load_gb(unsigned col0, f32x4 (&gv)[2], f32x4 (&bv)[2]) const {
; #pragma unroll
;         for (int n = 0; n < 2; ++n) {
;             if (LN) { gv[n] = *(const f32x4*)(gam + col0 + BJ * HALF + n * 16) * ALPHA; bv[n] = *(const f32x4*)(bet + col0 + BJ * HALF + n * 16) * ALPHA; }
;             else { gv[n] = (f32x4){ALPHA, ALPHA, ALPHA, ALPHA}; bv[n] = (f32x4){0.f, 0.f, 0.f, 0.f}; }
;         }
;     }
;     template <bool LN> DI void run(const f32x4 (&acc)[2][2][4][2], const Unit& u, int wr, int wc, int fr, int fq) const {
;         const unsigned row0 = u.pm * BM + wr * 64 + fr, col0 = u.pn * BM + wc * 32 + 4 * fq;
;         f32x4 gv[2], bv[2];
;         load_gb<LN, 0>(col0, gv, bv);
;         batch<LN, 0, 0, 4>(acc, row0, col0, gv, bv);
;         batch<LN, 0, 4, 8>(acc, row0, col0, gv, bv);
;         batch<LN, 0, 8, 12>(acc, row0, col0, gv, bv);
;         batch<LN, 0, 12, 16>(acc, row0, col0, gv, bv);
;         load_gb<LN, 1>(col0, gv, bv);
;         batch<LN, 1, 0, 8>(acc, row0, col0, gv, bv);
;         batch<LN, 1, 8, 16>(acc, row0, col0, gv, bv);
	v_add_u32_e32 v148, 0x10090, v194
	v_mov_b32_e32 v149, v159
	v_sub_f32_e32 v141, v141, v200
	v_sub_f32_e32 v140, v140, v200
	v_sub_f32_e32 v143, v143, v200
	v_sub_f32_e32 v142, v142, v200
	v_pk_fma_f32 v[146:147], v[130:131], s[78:79], v[146:147] op_sel_hi:[1,0,1]
	v_pk_fma_f32 v[144:145], v[128:129], s[78:79], v[144:145] op_sel_hi:[1,0,1]
	v_lshl_add_u64 v[148:149], v[148:149], 2, s[90:91]
	v_pk_mul_f32 v[142:143], v[200:201], v[142:143] op_sel:[1,0]
	v_pk_mul_f32 v[140:141], v[200:201], v[140:141] op_sel:[1,0]
	global_store_dwordx4 v[148:149], v[144:147], off
	v_pk_fma_f32 v[140:141], v[214:215], v[140:141], v[36:37]
	v_pk_fma_f32 v[142:143], v[212:213], v[142:143], v[38:39]
	v_add_u32_e32 v144, 0x18080, v194
	v_mov_b32_e32 v145, v159
	v_sub_f32_e32 v137, v137, v200
	v_sub_f32_e32 v136, v136, v200
	v_sub_f32_e32 v139, v139, v200
	v_sub_f32_e32 v138, v138, v200
	v_pk_fma_f32 v[142:143], v[134:135], s[78:79], v[142:143] op_sel_hi:[1,0,1]
	v_pk_fma_f32 v[140:141], v[132:133], s[78:79], v[140:141] op_sel_hi:[1,0,1]
	v_lshl_add_u64 v[144:145], v[144:145], 2, s[90:91]
	v_pk_mul_f32 v[138:139], v[200:201], v[138:139] op_sel:[1,0]
	v_pk_mul_f32 v[136:137], v[200:201], v[136:137] op_sel:[1,0]
	global_store_dwordx4 v[144:145], v[140:143], off
	v_pk_fma_f32 v[136:137], v[208:209], v[136:137], v[32:33]
	v_pk_fma_f32 v[138:139], v[206:207], v[138:139], v[34:35]
	v_add_u32_e32 v140, 0x18090, v194
	v_mov_b32_e32 v141, v159
	v_pk_fma_f32 v[138:139], v[130:131], s[78:79], v[138:139] op_sel_hi:[1,0,1]
	v_pk_fma_f32 v[136:137], v[128:129], s[78:79], v[136:137] op_sel_hi:[1,0,1]
	v_lshl_add_u64 v[140:141], v[140:141], 2, s[90:91]
	global_store_dwordx4 v[140:141], v[136:139], off
	s_nop 1
	v_add_u32_e32 v136, v233, v230
	v_mov_b32_e32 v137, v159
	v_lshl_add_u64 v[136:137], v[136:137], 2, s[88:89]
	global_load_dwordx2 v[220:221], v[196:197], off
	global_load_dwordx4 v[216:219], v[136:137], off
	v_add_u32_e32 v136, v233, v229
	v_mov_b32_e32 v137, v159
	v_lshl_add_u64 v[136:137], v[136:137], 2, s[88:89]
	global_load_dwordx4 v[240:243], v[136:137], off
	global_load_dwordx2 v[200:201], v[198:199], off
	v_add_u32_e32 v136, v234, v230
	v_mov_b32_e32 v137, v159
	v_lshl_add_u64 v[136:137], v[136:137], 2, s[88:89]
	global_load_dwordx4 v[244:247], v[136:137], off
	v_add_u32_e32 v136, v234, v229
	v_mov_b32_e32 v137, v159
	v_lshl_add_u64 v[136:137], v[136:137], 2, s[88:89]
	global_load_dwordx4 v[152:155], v[136:137], off
	global_load_dwordx2 v[198:199], v[204:205], off
	v_add_u32_e32 v136, v237, v230
	v_mov_b32_e32 v137, v159
	v_lshl_add_u64 v[136:137], v[136:137], 2, s[88:89]
	global_load_dwordx4 v[148:151], v[136:137], off
	v_add_u32_e32 v136, v237, v229
	v_mov_b32_e32 v137, v159
	v_lshl_add_u64 v[136:137], v[136:137], 2, s[88:89]
	global_load_dwordx4 v[144:147], v[136:137], off
	global_load_dwordx2 v[196:197], v[210:211], off
	v_add_u32_e32 v136, v238, v230
	v_mov_b32_e32 v137, v159
	v_lshl_add_u64 v[136:137], v[136:137], 2, s[88:89]
	global_load_dwordx4 v[140:143], v[136:137], off
	v_add_u32_e32 v136, v238, v229
	v_mov_b32_e32 v137, v159
	v_lshl_add_u64 v[136:137], v[136:137], 2, s[88:89]
	global_load_dwordx4 v[136:139], v[136:137], off
	v_add_u32_e32 v210, 0x40080, v194
	v_mov_b32_e32 v211, v159
	v_lshl_add_u64 v[210:211], v[210:211], 2, s[90:91]
	s_waitcnt vmcnt(0)
;     template <bool LN, int BJ, int LO, int HI> DI void batch(const f32x4 (&acc)[2][2][4][2], unsigned row0, unsigned col0, const f32x4 (&gv)[2], const f32x4 (&bv)[2]) const {
;         f32x4 r[HI - LO]; float mean[(HI - LO) / 2], rstd[(HI - LO) / 2];
; #pragma unroll
;         for (int i = LO; i < HI; ++i) { const int ai = i >> 3, m = (i >> 1) & 3, n = i & 1; const unsigned row = row0 + ai * HALF + m * 16;
;             if (n == 0) { mean[(i - LO) >> 1] = 0.f; rstd[(i - LO) >> 1] = 1.f;
;                 if (LN) { const float2 st = *(const float2*)(stats + row * 2u); mean[(i - LO) >> 1] = st.x; rstd[(i - LO) >> 1] = st.y; } }
;             r[i - LO] = *(const f32x4*)(src + (row * (unsigned)DM + col0 + BJ * HALF + n * 16)); }
; #pragma unroll
;         for (int i = LO; i < HI; ++i) { const int ai = i >> 3, m = (i >> 1) & 3, n = i & 1; const unsigned row = row0 + ai * HALF + m * 16;
;             *(f32x4*)(Y + (row * (unsigned)DM + col0 + BJ * HALF + n * 16)) = acc[ai][BJ][m][n] + ((r[i - LO] - mean[(i - LO) >> 1]) * rstd[(i - LO) >> 1]) * gv[n] + bv[n]; }
;         __builtin_amdgcn_sched_barrier(0);
;     }
;     template <bool LN, int BJ> DI void load_gb(unsigned col0, f32x4 (&gv)[2], f32x4 (&bv)[2]) const {
; #pragma unroll
;         for (int n = 0; n < 2; ++n) {
;             if (LN) { gv[n] = *(const f32x4*)(gam + col0 + BJ * HALF + n * 16) * ALPHA; bv[n] = *(const f32x4*)(bet + col0 + BJ * HALF + n * 16) * ALPHA; }
;             else { gv[n] = (f32x4){ALPHA, ALPHA, ALPHA, ALPHA}; bv[n] = (f32x4){0.f, 0.f, 0.f, 0.f}; }
;         }
;     }
;     template <bool LN> DI void run(const f32x4 (&acc)[2][2][4][2], const Unit& u, int wr, int wc, int fr, int fq) const {
;         const unsigned row0 = u.pm * BM + wr * 64 + fr, col0 = u.pn * BM + wc * 32 + 4 * fq;
;         f32x4 gv[2], bv[2];
;         load_gb<LN, 0>(col0, gv, bv);
;         batch<LN, 0, 0, 4>(acc, row0, col0, gv, bv);
;         batch<LN, 0, 4, 8>(acc, row0, col0, gv, bv);
;         batch<LN, 0, 8, 12>(acc, row0, col0, gv, bv);
;         batch<LN, 0, 12, 16>(acc, row0, col0, gv, bv);
;         load_gb<LN, 1>(col0, gv, bv);
;         batch<LN, 1, 0, 8>(acc, row0, col0, gv, bv);
;         batch<LN, 1, 8, 16>(acc, row0, col0, gv, bv);
;     }
	v_sub_f32_e32 v203, v217, v220
	v_sub_f32_e32 v202, v216, v220
	v_sub_f32_e32 v205, v219, v220
	v_sub_f32_e32 v204, v218, v220
	v_pk_mul_f32 v[204:205], v[220:221], v[204:205] op_sel:[1,0]
	v_pk_mul_f32 v[202:203], v[220:221], v[202:203] op_sel:[1,0]
	v_pk_fma_f32 v[204:205], v[212:213], v[204:205], v[30:31]
	v_pk_fma_f32 v[202:203], v[214:215], v[202:203], v[28:29]
	v_pk_fma_f32 v[204:205], v[134:135], s[78:79], v[204:205] op_sel_hi:[1,0,1]
	v_pk_fma_f32 v[202:203], v[132:133], s[78:79], v[202:203] op_sel_hi:[1,0,1]
	global_store_dwordx4 v[210:211], v[202:205], off
	v_add_u32_e32 v210, 0x40090, v194
	v_mov_b32_e32 v211, v159
	v_sub_f32_e32 v203, v241, v220
	v_sub_f32_e32 v202, v240, v220
	v_sub_f32_e32 v205, v243, v220
	v_sub_f32_e32 v204, v242, v220
	v_pk_mul_f32 v[204:205], v[220:221], v[204:205] op_sel:[1,0]
	v_pk_mul_f32 v[202:203], v[220:221], v[202:203] op_sel:[1,0]
	v_pk_fma_f32 v[204:205], v[206:207], v[204:205], v[26:27]
	v_pk_fma_f32 v[202:203], v[208:209], v[202:203], v[24:25]
	v_pk_fma_f32 v[204:205], v[130:131], s[78:79], v[204:205] op_sel_hi:[1,0,1]
	v_pk_fma_f32 v[202:203], v[128:129], s[78:79], v[202:203] op_sel_hi:[1,0,1]
	v_lshl_add_u64 v[210:211], v[210:211], 2, s[90:91]
	global_store_dwordx4 v[210:211], v[202:205], off
	v_sub_f32_e32 v149, v149, v198
	v_sub_f32_e32 v148, v148, v198
	v_sub_f32_e32 v203, v245, v200
	v_sub_f32_e32 v202, v244, v200
	v_sub_f32_e32 v141, v141, v196
	v_sub_f32_e32 v140, v140, v196
	v_sub_f32_e32 v205, v247, v200
	v_sub_f32_e32 v204, v246, v200
	v_pk_mul_f32 v[202:203], v[200:201], v[202:203] op_sel:[1,0]
	v_sub_f32_e32 v151, v151, v198
	v_sub_f32_e32 v150, v150, v198
	v_pk_mul_f32 v[148:149], v[198:199], v[148:149] op_sel:[1,0]
	v_sub_f32_e32 v143, v143, v196
	v_sub_f32_e32 v142, v142, v196
	v_pk_mul_f32 v[140:141], v[196:197], v[140:141] op_sel:[1,0]
	v_pk_mul_f32 v[204:205], v[200:201], v[204:205] op_sel:[1,0]
	v_pk_fma_f32 v[202:203], v[214:215], v[202:203], v[20:21]
	v_sub_f32_e32 v153, v153, v200
	v_sub_f32_e32 v152, v152, v200
	v_sub_f32_e32 v155, v155, v200
	v_sub_f32_e32 v154, v154, v200
	v_pk_mul_f32 v[150:151], v[198:199], v[150:151] op_sel:[1,0]
	v_pk_fma_f32 v[148:149], v[214:215], v[148:149], v[12:13]
	v_pk_mul_f32 v[142:143], v[196:197], v[142:143] op_sel:[1,0]
	v_pk_fma_f32 v[140:141], v[214:215], v[140:141], v[4:5]
	v_pk_fma_f32 v[204:205], v[212:213], v[204:205], v[22:23]
	v_pk_fma_f32 v[202:203], v[132:133], s[78:79], v[202:203] op_sel_hi:[1,0,1]
	v_pk_mul_f32 v[154:155], v[200:201], v[154:155] op_sel:[1,0]
	v_pk_mul_f32 v[152:153], v[200:201], v[152:153] op_sel:[1,0]
	v_pk_fma_f32 v[150:151], v[212:213], v[150:151], v[14:15]
	v_pk_fma_f32 v[148:149], v[132:133], s[78:79], v[148:149] op_sel_hi:[1,0,1]
	v_pk_fma_f32 v[142:143], v[212:213], v[142:143], v[6:7]
	v_pk_fma_f32 v[132:133], v[132:133], s[78:79], v[140:141] op_sel_hi:[1,0,1]
	v_add_u32_e32 v140, 0x58080, v194
	v_mov_b32_e32 v141, v159
	v_pk_fma_f32 v[204:205], v[134:135], s[78:79], v[204:205] op_sel_hi:[1,0,1]
	v_pk_fma_f32 v[152:153], v[208:209], v[152:153], v[16:17]
	v_pk_fma_f32 v[154:155], v[206:207], v[154:155], v[18:19]
	v_add_u32_e32 v200, 0x48090, v194
	v_mov_b32_e32 v201, v159
	v_pk_fma_f32 v[150:151], v[134:135], s[78:79], v[150:151] op_sel_hi:[1,0,1]
	v_pk_fma_f32 v[134:135], v[134:135], s[78:79], v[142:143] op_sel_hi:[1,0,1]
	v_lshl_add_u64 v[140:141], v[140:141], 2, s[90:91]
	v_pk_fma_f32 v[154:155], v[130:131], s[78:79], v[154:155] op_sel_hi:[1,0,1]
	v_pk_fma_f32 v[152:153], v[128:129], s[78:79], v[152:153] op_sel_hi:[1,0,1]
	v_lshl_add_u64 v[200:201], v[200:201], 2, s[90:91]
	v_sub_f32_e32 v145, v145, v198
	v_sub_f32_e32 v144, v144, v198
	global_store_dwordx4 v[140:141], v[132:135], off
	global_store_dwordx4 v[200:201], v[152:155], off
	v_sub_f32_e32 v147, v147, v198
	v_sub_f32_e32 v133, v137, v196
	v_sub_f32_e32 v132, v136, v196
	v_add_u32_e32 v152, 0x50080, v194
	v_mov_b32_e32 v153, v159
	v_sub_f32_e32 v146, v146, v198
	v_pk_mul_f32 v[144:145], v[198:199], v[144:145] op_sel:[1,0]
	v_sub_f32_e32 v135, v139, v196
	v_sub_f32_e32 v134, v138, v196
	v_pk_mul_f32 v[132:133], v[196:197], v[132:133] op_sel:[1,0]
	v_lshl_add_u64 v[152:153], v[152:153], 2, s[90:91]
	v_pk_mul_f32 v[146:147], v[198:199], v[146:147] op_sel:[1,0]
	v_pk_fma_f32 v[144:145], v[208:209], v[144:145], v[8:9]
	v_pk_mul_f32 v[134:135], v[196:197], v[134:135] op_sel:[1,0]
	v_pk_fma_f32 v[132:133], v[208:209], v[132:133], v[0:1]
	v_add_u32_e32 v210, 0x48080, v194
	v_mov_b32_e32 v211, v159
	global_store_dwordx4 v[152:153], v[148:151], off
	v_pk_fma_f32 v[146:147], v[206:207], v[146:147], v[10:11]
	v_pk_fma_f32 v[144:145], v[128:129], s[78:79], v[144:145] op_sel_hi:[1,0,1]
	v_add_u32_e32 v148, 0x50090, v194
	v_mov_b32_e32 v149, v159
	v_pk_fma_f32 v[134:135], v[206:207], v[134:135], v[2:3]
	v_pk_fma_f32 v[128:129], v[128:129], s[78:79], v[132:133] op_sel_hi:[1,0,1]
	v_add_u32_e32 v132, 0x58090, v194
	v_mov_b32_e32 v133, v159
	v_lshl_add_u64 v[210:211], v[210:211], 2, s[90:91]
	v_pk_fma_f32 v[146:147], v[130:131], s[78:79], v[146:147] op_sel_hi:[1,0,1]
	v_lshl_add_u64 v[148:149], v[148:149], 2, s[90:91]
	v_pk_fma_f32 v[130:131], v[130:131], s[78:79], v[134:135] op_sel_hi:[1,0,1]
	v_lshl_add_u64 v[132:133], v[132:133], 2, s[90:91]
	global_store_dwordx4 v[210:211], v[202:205], off
	global_store_dwordx4 v[148:149], v[144:147], off
	global_store_dwordx4 v[132:133], v[128:131], off
	s_mov_b64 s[24:25], 0
	s_branch .LBB0_324
